# 8 GEMM K-loops: loop-carried SALU block (counter/pointer updates + compare) moved ahead of the iteration's final s_barrier (back-edge rotation); pure reorder
# baseline (speedup 1.0000x reference)
; #define PG8_STAGE(bufoff, gbase, voff) do { _Pragma("unroll") for (int _i = 0; _i < 2; ++_i) \
;         __builtin_amdgcn_global_load_lds((const unsigned*)((const char*)(gbase) + (voff)[_i]), (LAS unsigned*)(lds + (bufoff) + ldsw + _i * 8192), 16, 0, 0); } while (0)
; #define PG8_LDA(dst, b, h) do { _Pragma("unroll") for (int m = 0; m < 4; ++m) _Pragma("unroll") for (int k = 0; k < 2; ++k) dst[m][k] = *(const LAS bf16x8*)(lds + PG8_SA(b, h) + aoff + m * 2048 + k * 1024); } while (0)
; #define PG8_LDB(dst, b, h) do { _Pragma("unroll") for (int n = 0; n < 2; ++n) _Pragma("unroll") for (int k = 0; k < 2; ++k) dst[n][k] = *(const LAS bf16x8*)(lds + PG8_SB(b, h) + boff + n * 2048 + k * 1024); } while (0)
; #define PG8_MMA(ai, bj, At, Bt) do { __builtin_amdgcn_s_setprio(1); _Pragma("unroll") for (int m = 0; m < 4; ++m) _Pragma("unroll") for (int n = 0; n < 2; ++n) _Pragma("unroll") for (int k = 0; k < 2; ++k) \
;         acc[ai][bj][m][n] = __builtin_amdgcn_mfma_f32_16x16x32_bf16(Bt[n][k], At[m][k], acc[ai][bj][m][n], 0, 0, 0); __builtin_amdgcn_s_setprio(0); } while (0)
; #define PG8_WAIT_V(n) asm volatile("s_waitcnt vmcnt(" #n ")" ::: "memory")
; #define PG8_WAIT_L(n) asm volatile("s_waitcnt lgkmcnt(" #n ")" ::: "memory")
; #define PG8_BAR __builtin_amdgcn_s_barrier()
; #define PG8_SCHED __builtin_amdgcn_sched_barrier(0)
; template <class Epi>
; __device__ __forceinline__ void gemm_phase(LAS unsigned char* lds, const Gemm g, const StaticOrder& S, const Epi& E) {
;     ...
;         for (int t = 0; t < nt; t += 2) {
;             const bool last = (t == nt - 2);
;             const char* a1 = cA + (size_t)(t + 1) * kstepA;
;             const char* a2 = last ? nA : cA + (size_t)(t + 2) * kstepA; const char* b2 = last ? nB : cB + (size_t)(t + 2) * kstep;
;             const char* a3 = a2 + kstepA; const char* b3 = b2 + kstep;
;             PG8_LDB(B0, 0, 0); PG8_LDB(B1, 0, 1); PG8_SCHED; PG8_LDA(At, 0, 0); PG8_STAGE(PG8_SA(1, 1), a1 + hstepA, voffA);
;             PG8_WAIT_V(8); PG8_WAIT_L(0); PG8_BAR; PG8_MMA(0, 0, At, B0); PG8_MMA(0, 1, At, B1); PG8_BAR; PG8_SCHED;
;             PG8_LDA(At, 0, 1); PG8_STAGE(PG8_SB(0, 0), b2, voffB); PG8_STAGE(PG8_SB(0, 1), b2 + hstepB, voffB); PG8_STAGE(PG8_SA(0, 0), a2, voffA);
.LBB0_452:
	ds_read_b128 v[150:153], v146
	ds_read_b128 v[154:157], v146 offset:1024
	ds_read_b128 v[158:161], v146 offset:2048
	ds_read_b128 v[162:165], v146 offset:3072
	ds_read_b128 v[166:169], v147
	ds_read_b128 v[170:173], v147 offset:1024
	ds_read_b128 v[174:177], v147 offset:2048
	ds_read_b128 v[178:181], v147 offset:3072
	s_add_u32 s30, s28, 0xfffc0080
	s_addc_u32 s31, s29, -1
	s_cmp_eq_u32 s61, 12
	s_cselect_b32 s39, s15, s31
	s_cselect_b32 s38, s57, s30
	s_cselect_b32 s31, s13, s60
	s_cselect_b32 s30, s58, s59
	v_lshl_add_u64 v[206:207], s[28:29], 0, v[136:137]
	s_add_i32 m0, s42, 0xc000
	ds_read_b128 v[182:185], v148
	ds_read_b128 v[186:189], v148 offset:1024
	ds_read_b128 v[190:193], v148 offset:2048
	ds_read_b128 v[194:197], v148 offset:3072
	ds_read_b128 v[198:201], v148 offset:4096
	ds_read_b128 v[202:205], v148 offset:5120
	ds_read_b128 v[212:215], v148 offset:6144
	ds_read_b128 v[216:219], v148 offset:7168
	global_load_lds_dwordx4 v[206:207], off
	v_lshl_add_u64 v[206:207], s[28:29], 0, v[138:139]
	s_add_i32 m0, s42, 0xe000
	s_nop 0
	global_load_lds_dwordx4 v[206:207], off
	s_waitcnt vmcnt(8)
	s_waitcnt lgkmcnt(0)
	s_barrier
	s_setprio 1
	s_waitcnt lgkmcnt(0)
	v_mfma_f32_16x16x32_bf16 v[124:127], v[150:153], v[182:185], v[124:127]
	v_mfma_f32_16x16x32_bf16 v[116:119], v[158:161], v[182:185], v[116:119]
	v_mfma_f32_16x16x32_bf16 v[108:111], v[150:153], v[190:193], v[108:111]
	v_mfma_f32_16x16x32_bf16 v[100:103], v[158:161], v[190:193], v[100:103]
	v_mfma_f32_16x16x32_bf16 v[92:95], v[150:153], v[198:201], v[92:95]
	v_mfma_f32_16x16x32_bf16 v[84:87], v[158:161], v[198:201], v[84:87]
	v_mfma_f32_16x16x32_bf16 v[76:79], v[150:153], v[212:215], v[76:79]
	v_mfma_f32_16x16x32_bf16 v[68:71], v[158:161], v[212:215], v[68:71]
	v_mfma_f32_16x16x32_bf16 v[124:127], v[154:157], v[186:189], v[124:127]
	v_mfma_f32_16x16x32_bf16 v[116:119], v[162:165], v[186:189], v[116:119]
	v_mfma_f32_16x16x32_bf16 v[108:111], v[154:157], v[194:197], v[108:111]
	v_mfma_f32_16x16x32_bf16 v[100:103], v[162:165], v[194:197], v[100:103]
	v_mfma_f32_16x16x32_bf16 v[92:95], v[154:157], v[202:205], v[92:95]
	v_mfma_f32_16x16x32_bf16 v[84:87], v[162:165], v[202:205], v[84:87]
	v_mfma_f32_16x16x32_bf16 v[76:79], v[154:157], v[216:219], v[76:79]
	v_mfma_f32_16x16x32_bf16 v[68:71], v[162:165], v[216:219], v[68:71]
	s_setprio 0
	s_setprio 1
	v_mfma_f32_16x16x32_bf16 v[120:123], v[166:169], v[182:185], v[120:123]
	v_mfma_f32_16x16x32_bf16 v[112:115], v[174:177], v[182:185], v[112:115]
	v_mfma_f32_16x16x32_bf16 v[104:107], v[166:169], v[190:193], v[104:107]
	v_mfma_f32_16x16x32_bf16 v[96:99], v[174:177], v[190:193], v[96:99]
	v_mfma_f32_16x16x32_bf16 v[88:91], v[166:169], v[198:201], v[88:91]
	v_mfma_f32_16x16x32_bf16 v[80:83], v[174:177], v[198:201], v[80:83]
	v_mfma_f32_16x16x32_bf16 v[72:75], v[166:169], v[212:215], v[72:75]
	v_mfma_f32_16x16x32_bf16 v[64:67], v[174:177], v[212:215], v[64:67]
	v_mfma_f32_16x16x32_bf16 v[120:123], v[170:173], v[186:189], v[120:123]
	v_mfma_f32_16x16x32_bf16 v[112:115], v[178:181], v[186:189], v[112:115]
	v_mfma_f32_16x16x32_bf16 v[104:107], v[170:173], v[194:197], v[104:107]
	v_mfma_f32_16x16x32_bf16 v[96:99], v[178:181], v[194:197], v[96:99]
	v_mfma_f32_16x16x32_bf16 v[88:91], v[170:173], v[202:205], v[88:91]
	v_mfma_f32_16x16x32_bf16 v[80:83], v[178:181], v[202:205], v[80:83]
	v_mfma_f32_16x16x32_bf16 v[72:75], v[170:173], v[216:219], v[72:75]
	v_mfma_f32_16x16x32_bf16 v[64:67], v[178:181], v[216:219], v[64:67]
	s_setprio 0
	s_barrier
	s_add_i32 s62, s52, s33
	v_lshl_add_u64 v[206:207], s[30:31], 0, v[130:131]
	s_mov_b32 m0, s62
	ds_read_b128 v[182:185], v148 offset:16384
	ds_read_b128 v[186:189], v148 offset:17408
	ds_read_b128 v[190:193], v148 offset:18432
	ds_read_b128 v[194:197], v148 offset:19456
	ds_read_b128 v[198:201], v148 offset:20480
	ds_read_b128 v[202:205], v148 offset:21504
	ds_read_b128 v[212:215], v148 offset:22528
	ds_read_b128 v[216:219], v148 offset:23552
	global_load_lds_dwordx4 v[206:207], off
	s_add_i32 m0, s62, 0x2000
	s_add_u32 s62, s30, 0x40000
	v_lshl_add_u64 v[220:221], s[30:31], 0, v[128:129]
	s_addc_u32 s63, s31, 0
	s_add_i32 s64, s53, s33
	global_load_lds_dwordx4 v[220:221], off
	v_lshl_add_u64 v[222:223], s[62:63], 0, v[130:131]
	s_mov_b32 m0, s64
	v_lshl_add_u64 v[224:225], s[38:39], 0, v[128:129]
	global_load_lds_dwordx4 v[222:223], off
	v_lshl_add_u64 v[222:223], s[62:63], 0, v[128:129]
	s_add_i32 m0, s64, 0x2000
	s_nop 0
	global_load_lds_dwordx4 v[222:223], off
	v_lshl_add_u64 v[222:223], s[38:39], 0, v[130:131]
	s_mov_b32 m0, s42
	s_nop 0
	global_load_lds_dwordx4 v[222:223], off
	s_mov_b32 m0, s43
	s_nop 0
	global_load_lds_dwordx4 v[224:225], off
	s_waitcnt vmcnt(8)
	s_waitcnt lgkmcnt(0)
	s_barrier
; #define PG8_STAGE(bufoff, gbase, voff) do { _Pragma("unroll") for (int _i = 0; _i < 2; ++_i) \
;         __builtin_amdgcn_global_load_lds((const unsigned*)((const char*)(gbase) + (voff)[_i]), (LAS unsigned*)(lds + (bufoff) + ldsw + _i * 8192), 16, 0, 0); } while (0)
; #define PG8_LDA(dst, b, h) do { _Pragma("unroll") for (int m = 0; m < 4; ++m) _Pragma("unroll") for (int k = 0; k < 2; ++k) dst[m][k] = *(const LAS bf16x8*)(lds + PG8_SA(b, h) + aoff + m * 2048 + k * 1024); } while (0)
; #define PG8_LDB(dst, b, h) do { _Pragma("unroll") for (int n = 0; n < 2; ++n) _Pragma("unroll") for (int k = 0; k < 2; ++k) dst[n][k] = *(const LAS bf16x8*)(lds + PG8_SB(b, h) + boff + n * 2048 + k * 1024); } while (0)
; #define PG8_MMA(ai, bj, At, Bt) do { __builtin_amdgcn_s_setprio(1); _Pragma("unroll") for (int m = 0; m < 4; ++m) _Pragma("unroll") for (int n = 0; n < 2; ++n) _Pragma("unroll") for (int k = 0; k < 2; ++k) \
;         acc[ai][bj][m][n] = __builtin_amdgcn_mfma_f32_16x16x32_bf16(Bt[n][k], At[m][k], acc[ai][bj][m][n], 0, 0, 0); __builtin_amdgcn_s_setprio(0); } while (0)
; #define PG8_WAIT_V(n) asm volatile("s_waitcnt vmcnt(" #n ")" ::: "memory")
; #define PG8_WAIT_L(n) asm volatile("s_waitcnt lgkmcnt(" #n ")" ::: "memory")
; #define PG8_BAR __builtin_amdgcn_s_barrier()
; #define PG8_SCHED __builtin_amdgcn_sched_barrier(0)
; template <class Epi>
; __device__ __forceinline__ void gemm_phase(LAS unsigned char* lds, const Gemm g, const StaticOrder& S, const Epi& E) {
;     ...
;             PG8_WAIT_V(8); PG8_WAIT_L(0); PG8_BAR; PG8_MMA(1, 0, At, B0); PG8_MMA(1, 1, At, B1); PG8_BAR; PG8_SCHED;
;             PG8_LDB(B0, 1, 0); PG8_LDB(B1, 1, 1); PG8_SCHED; PG8_LDA(At, 1, 0); PG8_STAGE(PG8_SA(0, 1), a2 + hstepA, voffA);
;             PG8_WAIT_V(8); PG8_WAIT_L(0); PG8_BAR; PG8_MMA(0, 0, At, B0); PG8_MMA(0, 1, At, B1); PG8_BAR; PG8_SCHED;
;             PG8_LDA(At, 1, 1); PG8_STAGE(PG8_SB(1, 0), b3, voffB); PG8_STAGE(PG8_SB(1, 1), b3 + hstepB, voffB); PG8_STAGE(PG8_SA(1, 0), a3, voffA);
	s_setprio 1
	s_waitcnt lgkmcnt(0)
	v_mfma_f32_16x16x32_bf16 v[60:63], v[150:153], v[182:185], v[60:63]
	v_mfma_f32_16x16x32_bf16 v[52:55], v[158:161], v[182:185], v[52:55]
	v_mfma_f32_16x16x32_bf16 v[44:47], v[150:153], v[190:193], v[44:47]
	v_mfma_f32_16x16x32_bf16 v[36:39], v[158:161], v[190:193], v[36:39]
	v_mfma_f32_16x16x32_bf16 v[28:31], v[150:153], v[198:201], v[28:31]
	v_mfma_f32_16x16x32_bf16 v[20:23], v[158:161], v[198:201], v[20:23]
	v_mfma_f32_16x16x32_bf16 v[12:15], v[150:153], v[212:215], v[12:15]
	v_mfma_f32_16x16x32_bf16 v[4:7], v[158:161], v[212:215], v[4:7]
	v_mfma_f32_16x16x32_bf16 v[60:63], v[154:157], v[186:189], v[60:63]
	v_mfma_f32_16x16x32_bf16 v[52:55], v[162:165], v[186:189], v[52:55]
	v_mfma_f32_16x16x32_bf16 v[44:47], v[154:157], v[194:197], v[44:47]
	v_mfma_f32_16x16x32_bf16 v[36:39], v[162:165], v[194:197], v[36:39]
	v_mfma_f32_16x16x32_bf16 v[28:31], v[154:157], v[202:205], v[28:31]
	v_mfma_f32_16x16x32_bf16 v[20:23], v[162:165], v[202:205], v[20:23]
	v_mfma_f32_16x16x32_bf16 v[12:15], v[154:157], v[216:219], v[12:15]
	v_mfma_f32_16x16x32_bf16 v[4:7], v[162:165], v[216:219], v[4:7]
	s_setprio 0
	s_setprio 1
	v_mfma_f32_16x16x32_bf16 v[56:59], v[166:169], v[182:185], v[56:59]
	v_mfma_f32_16x16x32_bf16 v[48:51], v[174:177], v[182:185], v[48:51]
	v_mfma_f32_16x16x32_bf16 v[40:43], v[166:169], v[190:193], v[40:43]
	v_mfma_f32_16x16x32_bf16 v[32:35], v[174:177], v[190:193], v[32:35]
	v_mfma_f32_16x16x32_bf16 v[24:27], v[166:169], v[198:201], v[24:27]
	v_mfma_f32_16x16x32_bf16 v[16:19], v[174:177], v[198:201], v[16:19]
	v_mfma_f32_16x16x32_bf16 v[8:11], v[166:169], v[212:215], v[8:11]
	v_mfma_f32_16x16x32_bf16 v[0:3], v[174:177], v[212:215], v[0:3]
	v_mfma_f32_16x16x32_bf16 v[56:59], v[170:173], v[186:189], v[56:59]
	v_mfma_f32_16x16x32_bf16 v[48:51], v[178:181], v[186:189], v[48:51]
	v_mfma_f32_16x16x32_bf16 v[40:43], v[170:173], v[194:197], v[40:43]
	v_mfma_f32_16x16x32_bf16 v[32:35], v[178:181], v[194:197], v[32:35]
	v_mfma_f32_16x16x32_bf16 v[24:27], v[170:173], v[202:205], v[24:27]
	v_mfma_f32_16x16x32_bf16 v[16:19], v[178:181], v[202:205], v[16:19]
	v_mfma_f32_16x16x32_bf16 v[8:11], v[170:173], v[216:219], v[8:11]
	v_mfma_f32_16x16x32_bf16 v[0:3], v[178:181], v[216:219], v[0:3]
	s_setprio 0
	s_barrier
	s_add_i32 s62, 0, 0x18000
	s_add_i32 s63, 0, 0x1c000
	v_add_u32_e32 v162, s62, v145
	v_add_u32_e32 v178, s63, v145
	ds_read_b128 v[150:153], v162
	ds_read_b128 v[154:157], v162 offset:1024
	ds_read_b128 v[158:161], v162 offset:2048
	ds_read_b128 v[162:165], v162 offset:3072
	ds_read_b128 v[166:169], v178
	ds_read_b128 v[170:173], v178 offset:1024
	ds_read_b128 v[174:177], v178 offset:2048
	ds_read_b128 v[178:181], v178 offset:3072
	s_add_u32 s38, s38, 0x40000
	s_addc_u32 s39, s39, 0
	s_mov_b32 m0, s44
	v_lshl_add_u64 v[226:227], s[38:39], 0, v[130:131]
	ds_read_b128 v[182:185], v148 offset:32768
	ds_read_b128 v[186:189], v148 offset:33792
	ds_read_b128 v[190:193], v148 offset:34816
	ds_read_b128 v[194:197], v148 offset:35840
	ds_read_b128 v[198:201], v148 offset:36864
	ds_read_b128 v[202:205], v148 offset:37888
	ds_read_b128 v[212:215], v148 offset:38912
	ds_read_b128 v[216:219], v148 offset:39936
	global_load_lds_dwordx4 v[226:227], off
	v_lshl_add_u64 v[226:227], s[38:39], 0, v[128:129]
	s_mov_b32 m0, s45
	s_nop 0
	global_load_lds_dwordx4 v[226:227], off
	s_waitcnt vmcnt(8)
	s_waitcnt lgkmcnt(0)
	s_barrier
	s_setprio 1
	s_waitcnt lgkmcnt(0)
	v_mfma_f32_16x16x32_bf16 v[124:127], v[150:153], v[182:185], v[124:127]
	v_mfma_f32_16x16x32_bf16 v[116:119], v[158:161], v[182:185], v[116:119]
	v_mfma_f32_16x16x32_bf16 v[108:111], v[150:153], v[190:193], v[108:111]
	v_mfma_f32_16x16x32_bf16 v[100:103], v[158:161], v[190:193], v[100:103]
	v_mfma_f32_16x16x32_bf16 v[92:95], v[150:153], v[198:201], v[92:95]
	v_mfma_f32_16x16x32_bf16 v[84:87], v[158:161], v[198:201], v[84:87]
	v_mfma_f32_16x16x32_bf16 v[76:79], v[150:153], v[212:215], v[76:79]
	v_mfma_f32_16x16x32_bf16 v[68:71], v[158:161], v[212:215], v[68:71]
	v_mfma_f32_16x16x32_bf16 v[124:127], v[154:157], v[186:189], v[124:127]
	v_mfma_f32_16x16x32_bf16 v[116:119], v[162:165], v[186:189], v[116:119]
	v_mfma_f32_16x16x32_bf16 v[108:111], v[154:157], v[194:197], v[108:111]
	v_mfma_f32_16x16x32_bf16 v[100:103], v[162:165], v[194:197], v[100:103]
	v_mfma_f32_16x16x32_bf16 v[92:95], v[154:157], v[202:205], v[92:95]
	v_mfma_f32_16x16x32_bf16 v[84:87], v[162:165], v[202:205], v[84:87]
	v_mfma_f32_16x16x32_bf16 v[76:79], v[154:157], v[216:219], v[76:79]
	v_mfma_f32_16x16x32_bf16 v[68:71], v[162:165], v[216:219], v[68:71]
	s_setprio 0
	s_setprio 1
	v_mfma_f32_16x16x32_bf16 v[120:123], v[166:169], v[182:185], v[120:123]
	v_mfma_f32_16x16x32_bf16 v[112:115], v[174:177], v[182:185], v[112:115]
	v_mfma_f32_16x16x32_bf16 v[104:107], v[166:169], v[190:193], v[104:107]
	v_mfma_f32_16x16x32_bf16 v[96:99], v[174:177], v[190:193], v[96:99]
	v_mfma_f32_16x16x32_bf16 v[88:91], v[166:169], v[198:201], v[88:91]
	v_mfma_f32_16x16x32_bf16 v[80:83], v[174:177], v[198:201], v[80:83]
	v_mfma_f32_16x16x32_bf16 v[72:75], v[166:169], v[212:215], v[72:75]
	v_mfma_f32_16x16x32_bf16 v[64:67], v[174:177], v[212:215], v[64:67]
	v_mfma_f32_16x16x32_bf16 v[120:123], v[170:173], v[186:189], v[120:123]
	v_mfma_f32_16x16x32_bf16 v[112:115], v[178:181], v[186:189], v[112:115]
	v_mfma_f32_16x16x32_bf16 v[104:107], v[170:173], v[194:197], v[104:107]
	v_mfma_f32_16x16x32_bf16 v[96:99], v[178:181], v[194:197], v[96:99]
	v_mfma_f32_16x16x32_bf16 v[88:91], v[170:173], v[202:205], v[88:91]
	v_mfma_f32_16x16x32_bf16 v[80:83], v[178:181], v[202:205], v[80:83]
	v_mfma_f32_16x16x32_bf16 v[72:75], v[170:173], v[216:219], v[72:75]
	v_mfma_f32_16x16x32_bf16 v[64:67], v[178:181], v[216:219], v[64:67]
	s_setprio 0
	s_barrier
; #define PG8_STAGE(bufoff, gbase, voff) do { _Pragma("unroll") for (int _i = 0; _i < 2; ++_i) \
;         __builtin_amdgcn_global_load_lds((const unsigned*)((const char*)(gbase) + (voff)[_i]), (LAS unsigned*)(lds + (bufoff) + ldsw + _i * 8192), 16, 0, 0); } while (0)
; #define PG8_LDA(dst, b, h) do { _Pragma("unroll") for (int m = 0; m < 4; ++m) _Pragma("unroll") for (int k = 0; k < 2; ++k) dst[m][k] = *(const LAS bf16x8*)(lds + PG8_SA(b, h) + aoff + m * 2048 + k * 1024); } while (0)
; #define PG8_MMA(ai, bj, At, Bt) do { __builtin_amdgcn_s_setprio(1); _Pragma("unroll") for (int m = 0; m < 4; ++m) _Pragma("unroll") for (int n = 0; n < 2; ++n) _Pragma("unroll") for (int k = 0; k < 2; ++k) \
;         acc[ai][bj][m][n] = __builtin_amdgcn_mfma_f32_16x16x32_bf16(Bt[n][k], At[m][k], acc[ai][bj][m][n], 0, 0, 0); __builtin_amdgcn_s_setprio(0); } while (0)
; #define PG8_WAIT_V(n) asm volatile("s_waitcnt vmcnt(" #n ")" ::: "memory")
; #define PG8_WAIT_L(n) asm volatile("s_waitcnt lgkmcnt(" #n ")" ::: "memory")
; #define PG8_BAR __builtin_amdgcn_s_barrier()
; #define PG8_SCHED __builtin_amdgcn_sched_barrier(0)
; template <class Epi>
; __device__ __forceinline__ void gemm_phase(LAS unsigned char* lds, const Gemm g, const StaticOrder& S, const Epi& E) {
;     ...
;             PG8_LDA(At, 1, 1); PG8_STAGE(PG8_SB(1, 0), b3, voffB); PG8_STAGE(PG8_SB(1, 1), b3 + hstepB, voffB); PG8_STAGE(PG8_SA(1, 0), a3, voffA);
;             PG8_WAIT_V(8); PG8_WAIT_L(0); PG8_BAR; PG8_MMA(1, 0, At, B0); PG8_MMA(1, 1, At, B1); PG8_BAR; PG8_SCHED;
;         }
;         if (wr == 0) PG8_BAR;
	s_add_i32 s38, s62, s33
	v_lshl_add_u64 v[206:207], v[206:207], 0, s[8:9]
	s_mov_b32 m0, s38
	ds_read_b128 v[182:185], v148 offset:49152
	ds_read_b128 v[186:189], v148 offset:50176
	ds_read_b128 v[190:193], v148 offset:51200
	ds_read_b128 v[194:197], v148 offset:52224
	ds_read_b128 v[198:201], v148 offset:53248
	ds_read_b128 v[202:205], v148 offset:54272
	ds_read_b128 v[212:215], v148 offset:55296
	ds_read_b128 v[216:219], v148 offset:56320
	global_load_lds_dwordx4 v[206:207], off
	s_add_i32 m0, s38, 0x2000
	s_add_u32 s30, s30, 0x40080
	v_lshl_add_u64 v[206:207], v[220:221], 0, s[8:9]
	s_addc_u32 s31, s31, 0
	s_add_i32 s38, s63, s33
	global_load_lds_dwordx4 v[206:207], off
	v_lshl_add_u64 v[206:207], s[30:31], 0, v[130:131]
	s_mov_b32 m0, s38
	s_nop 0
	global_load_lds_dwordx4 v[206:207], off
	v_lshl_add_u64 v[206:207], s[30:31], 0, v[128:129]
	s_add_i32 m0, s38, 0x2000
	s_nop 0
	global_load_lds_dwordx4 v[206:207], off
	v_lshl_add_u64 v[206:207], v[222:223], 0, s[8:9]
	s_mov_b32 m0, s47
	s_nop 0
	global_load_lds_dwordx4 v[206:207], off
	v_lshl_add_u64 v[206:207], v[224:225], 0, s[8:9]
	s_mov_b32 m0, s48
	s_nop 0
	global_load_lds_dwordx4 v[206:207], off
	s_waitcnt vmcnt(8)
	s_waitcnt lgkmcnt(0)
	s_barrier
	s_setprio 1
	s_waitcnt lgkmcnt(0)
	v_mfma_f32_16x16x32_bf16 v[60:63], v[150:153], v[182:185], v[60:63]
	v_mfma_f32_16x16x32_bf16 v[52:55], v[158:161], v[182:185], v[52:55]
	v_mfma_f32_16x16x32_bf16 v[44:47], v[150:153], v[190:193], v[44:47]
	v_mfma_f32_16x16x32_bf16 v[36:39], v[158:161], v[190:193], v[36:39]
	v_mfma_f32_16x16x32_bf16 v[28:31], v[150:153], v[198:201], v[28:31]
	v_mfma_f32_16x16x32_bf16 v[20:23], v[158:161], v[198:201], v[20:23]
	v_mfma_f32_16x16x32_bf16 v[12:15], v[150:153], v[212:215], v[12:15]
	v_mfma_f32_16x16x32_bf16 v[4:7], v[158:161], v[212:215], v[4:7]
	v_mfma_f32_16x16x32_bf16 v[60:63], v[154:157], v[186:189], v[60:63]
	v_mfma_f32_16x16x32_bf16 v[52:55], v[162:165], v[186:189], v[52:55]
	v_mfma_f32_16x16x32_bf16 v[44:47], v[154:157], v[194:197], v[44:47]
	v_mfma_f32_16x16x32_bf16 v[36:39], v[162:165], v[194:197], v[36:39]
	v_mfma_f32_16x16x32_bf16 v[28:31], v[154:157], v[202:205], v[28:31]
	v_mfma_f32_16x16x32_bf16 v[20:23], v[162:165], v[202:205], v[20:23]
	v_mfma_f32_16x16x32_bf16 v[12:15], v[154:157], v[216:219], v[12:15]
	v_mfma_f32_16x16x32_bf16 v[4:7], v[162:165], v[216:219], v[4:7]
	s_setprio 0
	s_setprio 1
	v_mfma_f32_16x16x32_bf16 v[56:59], v[166:169], v[182:185], v[56:59]
	v_mfma_f32_16x16x32_bf16 v[48:51], v[174:177], v[182:185], v[48:51]
	v_mfma_f32_16x16x32_bf16 v[40:43], v[166:169], v[190:193], v[40:43]
	v_mfma_f32_16x16x32_bf16 v[32:35], v[174:177], v[190:193], v[32:35]
	v_mfma_f32_16x16x32_bf16 v[24:27], v[166:169], v[198:201], v[24:27]
	v_mfma_f32_16x16x32_bf16 v[16:19], v[174:177], v[198:201], v[16:19]
	v_mfma_f32_16x16x32_bf16 v[8:11], v[166:169], v[212:215], v[8:11]
	v_mfma_f32_16x16x32_bf16 v[0:3], v[174:177], v[212:215], v[0:3]
	v_mfma_f32_16x16x32_bf16 v[56:59], v[170:173], v[186:189], v[56:59]
	v_mfma_f32_16x16x32_bf16 v[48:51], v[178:181], v[186:189], v[48:51]
	v_mfma_f32_16x16x32_bf16 v[40:43], v[170:173], v[194:197], v[40:43]
	v_mfma_f32_16x16x32_bf16 v[32:35], v[178:181], v[194:197], v[32:35]
	v_mfma_f32_16x16x32_bf16 v[24:27], v[170:173], v[202:205], v[24:27]
	v_mfma_f32_16x16x32_bf16 v[16:19], v[178:181], v[202:205], v[16:19]
	v_mfma_f32_16x16x32_bf16 v[8:11], v[170:173], v[216:219], v[8:11]
	v_mfma_f32_16x16x32_bf16 v[0:3], v[178:181], v[216:219], v[0:3]
	s_setprio 0
	s_add_i32 s61, s61, 2
	s_add_u32 s28, s28, 0x100
	s_addc_u32 s29, s29, 0
	s_add_u32 s59, s59, 0x100
	s_addc_u32 s60, s60, 0
	s_cmp_gt_u32 s61, 13
	s_barrier
	s_cbranch_scc0 .LBB0_452
	s_and_b64 vcc, exec, s[10:11]
	s_cbranch_vccz .LBB0_455
	s_barrier

; #define PG8_STAGE(bufoff, gbase, voff) do { _Pragma("unroll") for (int _i = 0; _i < 2; ++_i) \
;         __builtin_amdgcn_global_load_lds((const unsigned*)((const char*)(gbase) + (voff)[_i]), (LAS unsigned*)(lds + (bufoff) + ldsw + _i * 8192), 16, 0, 0); } while (0)
; #define PG8_LDA(dst, b, h) do { _Pragma("unroll") for (int m = 0; m < 4; ++m) _Pragma("unroll") for (int k = 0; k < 2; ++k) dst[m][k] = *(const LAS bf16x8*)(lds + PG8_SA(b, h) + aoff + m * 2048 + k * 1024); } while (0)
; #define PG8_LDB(dst, b, h) do { _Pragma("unroll") for (int n = 0; n < 2; ++n) _Pragma("unroll") for (int k = 0; k < 2; ++k) dst[n][k] = *(const LAS bf16x8*)(lds + PG8_SB(b, h) + boff + n * 2048 + k * 1024); } while (0)
; #define PG8_MMA(ai, bj, At, Bt) do { __builtin_amdgcn_s_setprio(1); _Pragma("unroll") for (int m = 0; m < 4; ++m) _Pragma("unroll") for (int n = 0; n < 2; ++n) _Pragma("unroll") for (int k = 0; k < 2; ++k) \
;         acc[ai][bj][m][n] = __builtin_amdgcn_mfma_f32_16x16x32_bf16(Bt[n][k], At[m][k], acc[ai][bj][m][n], 0, 0, 0); __builtin_amdgcn_s_setprio(0); } while (0)
; #define PG8_WAIT_V(n) asm volatile("s_waitcnt vmcnt(" #n ")" ::: "memory")
; #define PG8_WAIT_L(n) asm volatile("s_waitcnt lgkmcnt(" #n ")" ::: "memory")
; #define PG8_BAR __builtin_amdgcn_s_barrier()
; #define PG8_SCHED __builtin_amdgcn_sched_barrier(0)
; template <class Epi>
; __device__ __forceinline__ void gemm_phase(LAS unsigned char* lds, const Gemm g, const StaticOrder& S, const Epi& E) {
;     ...
;         for (int t = 0; t < nt; t += 2) {
;             const bool last = (t == nt - 2);
;             const char* a1 = cA + (size_t)(t + 1) * kstepA;
;             const char* a2 = last ? nA : cA + (size_t)(t + 2) * kstepA; const char* b2 = last ? nB : cB + (size_t)(t + 2) * kstep;
;             const char* a3 = a2 + kstepA; const char* b3 = b2 + kstep;
;             PG8_LDB(B0, 0, 0); PG8_LDB(B1, 0, 1); PG8_SCHED; PG8_LDA(At, 0, 0); PG8_STAGE(PG8_SA(1, 1), a1 + hstepA, voffA);
;             PG8_WAIT_V(8); PG8_WAIT_L(0); PG8_BAR; PG8_MMA(0, 0, At, B0); PG8_MMA(0, 1, At, B1); PG8_BAR; PG8_SCHED;
;             PG8_LDA(At, 0, 1); PG8_STAGE(PG8_SB(0, 0), b2, voffB); PG8_STAGE(PG8_SB(0, 1), b2 + hstepB, voffB); PG8_STAGE(PG8_SA(0, 0), a2, voffA);
.LBB0_548:
	ds_read_b128 v[128:131], v238
	ds_read_b128 v[132:135], v238 offset:1024
	ds_read_b128 v[136:139], v238 offset:2048
	ds_read_b128 v[140:143], v238 offset:3072
	ds_read_b128 v[144:147], v239
	ds_read_b128 v[148:151], v239 offset:1024
	ds_read_b128 v[152:155], v239 offset:2048
	ds_read_b128 v[156:159], v239 offset:3072
	s_add_u32 s2, s0, 0x4000
	s_addc_u32 s3, s1, 0
	s_cmp_eq_u32 s16, 40
	s_cselect_b32 s10, s42, s2
	s_cselect_b32 s11, s43, s3
	s_cselect_b32 s8, s44, s14
	s_cselect_b32 s9, s45, s15
	s_add_u32 s2, s10, 0x8000
	s_addc_u32 s3, s11, 0
	v_lshl_add_u64 v[212:213], s[0:1], 0, v[200:201]
	s_add_i32 m0, s46, 0xc000
	ds_read_b128 v[160:163], v240
	ds_read_b128 v[164:167], v240 offset:1024
	ds_read_b128 v[168:171], v240 offset:2048
	ds_read_b128 v[172:175], v240 offset:3072
	ds_read_b128 v[176:179], v240 offset:4096
	ds_read_b128 v[180:183], v240 offset:5120
	ds_read_b128 v[184:187], v240 offset:6144
	ds_read_b128 v[188:191], v240 offset:7168
	global_load_lds_dwordx4 v[212:213], off
	v_lshl_add_u64 v[212:213], s[0:1], 0, v[202:203]
	s_add_i32 m0, s46, 0xe000
	s_nop 0
	global_load_lds_dwordx4 v[212:213], off
	s_waitcnt vmcnt(8)
	s_waitcnt lgkmcnt(0)
	s_barrier
	s_setprio 1
	s_waitcnt lgkmcnt(0)
	v_mfma_f32_16x16x32_bf16 v[120:123], v[128:131], v[160:163], v[120:123]
	v_mfma_f32_16x16x32_bf16 v[124:127], v[136:139], v[160:163], v[124:127]
	v_mfma_f32_16x16x32_bf16 v[104:107], v[128:131], v[168:171], v[104:107]
	v_mfma_f32_16x16x32_bf16 v[108:111], v[136:139], v[168:171], v[108:111]
	v_mfma_f32_16x16x32_bf16 v[88:91], v[128:131], v[176:179], v[88:91]
	v_mfma_f32_16x16x32_bf16 v[92:95], v[136:139], v[176:179], v[92:95]
	v_mfma_f32_16x16x32_bf16 v[72:75], v[128:131], v[184:187], v[72:75]
	v_mfma_f32_16x16x32_bf16 v[76:79], v[136:139], v[184:187], v[76:79]
	v_mfma_f32_16x16x32_bf16 v[120:123], v[132:135], v[164:167], v[120:123]
	v_mfma_f32_16x16x32_bf16 v[124:127], v[140:143], v[164:167], v[124:127]
	v_mfma_f32_16x16x32_bf16 v[104:107], v[132:135], v[172:175], v[104:107]
	v_mfma_f32_16x16x32_bf16 v[108:111], v[140:143], v[172:175], v[108:111]
	v_mfma_f32_16x16x32_bf16 v[88:91], v[132:135], v[180:183], v[88:91]
	v_mfma_f32_16x16x32_bf16 v[92:95], v[140:143], v[180:183], v[92:95]
	v_mfma_f32_16x16x32_bf16 v[72:75], v[132:135], v[188:191], v[72:75]
	v_mfma_f32_16x16x32_bf16 v[76:79], v[140:143], v[188:191], v[76:79]
	s_setprio 0
	s_setprio 1
	v_mfma_f32_16x16x32_bf16 v[112:115], v[144:147], v[160:163], v[112:115]
	v_mfma_f32_16x16x32_bf16 v[116:119], v[152:155], v[160:163], v[116:119]
	v_mfma_f32_16x16x32_bf16 v[96:99], v[144:147], v[168:171], v[96:99]
	v_mfma_f32_16x16x32_bf16 v[100:103], v[152:155], v[168:171], v[100:103]
	v_mfma_f32_16x16x32_bf16 v[80:83], v[144:147], v[176:179], v[80:83]
	v_mfma_f32_16x16x32_bf16 v[84:87], v[152:155], v[176:179], v[84:87]
	v_mfma_f32_16x16x32_bf16 v[64:67], v[144:147], v[184:187], v[64:67]
	v_mfma_f32_16x16x32_bf16 v[68:71], v[152:155], v[184:187], v[68:71]
	v_mfma_f32_16x16x32_bf16 v[112:115], v[148:151], v[164:167], v[112:115]
	v_mfma_f32_16x16x32_bf16 v[116:119], v[156:159], v[164:167], v[116:119]
	v_mfma_f32_16x16x32_bf16 v[96:99], v[148:151], v[172:175], v[96:99]
	v_mfma_f32_16x16x32_bf16 v[100:103], v[156:159], v[172:175], v[100:103]
	v_mfma_f32_16x16x32_bf16 v[80:83], v[148:151], v[180:183], v[80:83]
	v_mfma_f32_16x16x32_bf16 v[84:87], v[156:159], v[180:183], v[84:87]
	v_mfma_f32_16x16x32_bf16 v[64:67], v[148:151], v[188:191], v[64:67]
	v_mfma_f32_16x16x32_bf16 v[68:71], v[156:159], v[188:191], v[68:71]
	s_setprio 0
	s_barrier
	s_add_i32 s17, s59, s33
	v_lshl_add_u64 v[212:213], s[8:9], 0, v[194:195]
	s_mov_b32 m0, s17
	ds_read_b128 v[160:163], v240 offset:16384
	ds_read_b128 v[164:167], v240 offset:17408
	ds_read_b128 v[168:171], v240 offset:18432
	ds_read_b128 v[172:175], v240 offset:19456
	ds_read_b128 v[176:179], v240 offset:20480
	ds_read_b128 v[180:183], v240 offset:21504
	ds_read_b128 v[184:187], v240 offset:22528
	ds_read_b128 v[188:191], v240 offset:23552
	global_load_lds_dwordx4 v[212:213], off
	s_add_i32 m0, s17, 0x2000
	s_add_u32 s18, s8, 0xb0000
	v_lshl_add_u64 v[214:215], s[8:9], 0, v[198:199]
	s_addc_u32 s19, s9, 0
	s_add_i32 s17, s60, s33
	global_load_lds_dwordx4 v[214:215], off
	v_lshl_add_u64 v[216:217], s[18:19], 0, v[194:195]
	s_mov_b32 m0, s17
	s_nop 0
	global_load_lds_dwordx4 v[216:217], off
	v_lshl_add_u64 v[216:217], s[18:19], 0, v[198:199]
	s_add_i32 m0, s17, 0x2000
	s_nop 0
	global_load_lds_dwordx4 v[216:217], off
	v_lshl_add_u64 v[216:217], s[10:11], 0, v[192:193]
	s_mov_b32 m0, s46
	s_nop 0
	global_load_lds_dwordx4 v[216:217], off
	v_lshl_add_u64 v[216:217], s[10:11], 0, v[196:197]
	s_mov_b32 m0, s47
	s_nop 0
	global_load_lds_dwordx4 v[216:217], off
	s_waitcnt vmcnt(8)
	s_waitcnt lgkmcnt(0)
	s_barrier
; #define PG8_STAGE(bufoff, gbase, voff) do { _Pragma("unroll") for (int _i = 0; _i < 2; ++_i) \
;         __builtin_amdgcn_global_load_lds((const unsigned*)((const char*)(gbase) + (voff)[_i]), (LAS unsigned*)(lds + (bufoff) + ldsw + _i * 8192), 16, 0, 0); } while (0)
; #define PG8_LDA(dst, b, h) do { _Pragma("unroll") for (int m = 0; m < 4; ++m) _Pragma("unroll") for (int k = 0; k < 2; ++k) dst[m][k] = *(const LAS bf16x8*)(lds + PG8_SA(b, h) + aoff + m * 2048 + k * 1024); } while (0)
; #define PG8_LDB(dst, b, h) do { _Pragma("unroll") for (int n = 0; n < 2; ++n) _Pragma("unroll") for (int k = 0; k < 2; ++k) dst[n][k] = *(const LAS bf16x8*)(lds + PG8_SB(b, h) + boff + n * 2048 + k * 1024); } while (0)
; #define PG8_MMA(ai, bj, At, Bt) do { __builtin_amdgcn_s_setprio(1); _Pragma("unroll") for (int m = 0; m < 4; ++m) _Pragma("unroll") for (int n = 0; n < 2; ++n) _Pragma("unroll") for (int k = 0; k < 2; ++k) \
;         acc[ai][bj][m][n] = __builtin_amdgcn_mfma_f32_16x16x32_bf16(Bt[n][k], At[m][k], acc[ai][bj][m][n], 0, 0, 0); __builtin_amdgcn_s_setprio(0); } while (0)
; #define PG8_WAIT_V(n) asm volatile("s_waitcnt vmcnt(" #n ")" ::: "memory")
; #define PG8_WAIT_L(n) asm volatile("s_waitcnt lgkmcnt(" #n ")" ::: "memory")
; #define PG8_BAR __builtin_amdgcn_s_barrier()
; #define PG8_SCHED __builtin_amdgcn_sched_barrier(0)
; template <class Epi>
; __device__ __forceinline__ void gemm_phase(LAS unsigned char* lds, const Gemm g, const StaticOrder& S, const Epi& E) {
;     ...
;             PG8_WAIT_V(8); PG8_WAIT_L(0); PG8_BAR; PG8_MMA(1, 0, At, B0); PG8_MMA(1, 1, At, B1); PG8_BAR; PG8_SCHED;
;             PG8_LDB(B0, 1, 0); PG8_LDB(B1, 1, 1); PG8_SCHED; PG8_LDA(At, 1, 0); PG8_STAGE(PG8_SA(0, 1), a2 + hstepA, voffA);
;             PG8_WAIT_V(8); PG8_WAIT_L(0); PG8_BAR; PG8_MMA(0, 0, At, B0); PG8_MMA(0, 1, At, B1); PG8_BAR; PG8_SCHED;
;             PG8_LDA(At, 1, 1); PG8_STAGE(PG8_SB(1, 0), b3, voffB); PG8_STAGE(PG8_SB(1, 1), b3 + hstepB, voffB); PG8_STAGE(PG8_SA(1, 0), a3, voffA);
	s_setprio 1
	s_waitcnt lgkmcnt(0)
	v_mfma_f32_16x16x32_bf16 v[56:59], v[128:131], v[160:163], v[56:59]
	v_mfma_f32_16x16x32_bf16 v[60:63], v[136:139], v[160:163], v[60:63]
	v_mfma_f32_16x16x32_bf16 v[40:43], v[128:131], v[168:171], v[40:43]
	v_mfma_f32_16x16x32_bf16 v[44:47], v[136:139], v[168:171], v[44:47]
	v_mfma_f32_16x16x32_bf16 v[24:27], v[128:131], v[176:179], v[24:27]
	v_mfma_f32_16x16x32_bf16 v[28:31], v[136:139], v[176:179], v[28:31]
	v_mfma_f32_16x16x32_bf16 v[8:11], v[128:131], v[184:187], v[8:11]
	v_mfma_f32_16x16x32_bf16 v[12:15], v[136:139], v[184:187], v[12:15]
	v_mfma_f32_16x16x32_bf16 v[56:59], v[132:135], v[164:167], v[56:59]
	v_mfma_f32_16x16x32_bf16 v[60:63], v[140:143], v[164:167], v[60:63]
	v_mfma_f32_16x16x32_bf16 v[40:43], v[132:135], v[172:175], v[40:43]
	v_mfma_f32_16x16x32_bf16 v[44:47], v[140:143], v[172:175], v[44:47]
	v_mfma_f32_16x16x32_bf16 v[24:27], v[132:135], v[180:183], v[24:27]
	v_mfma_f32_16x16x32_bf16 v[28:31], v[140:143], v[180:183], v[28:31]
	v_mfma_f32_16x16x32_bf16 v[8:11], v[132:135], v[188:191], v[8:11]
	v_mfma_f32_16x16x32_bf16 v[12:15], v[140:143], v[188:191], v[12:15]
	s_setprio 0
	s_setprio 1
	v_mfma_f32_16x16x32_bf16 v[48:51], v[144:147], v[160:163], v[48:51]
	v_mfma_f32_16x16x32_bf16 v[52:55], v[152:155], v[160:163], v[52:55]
	v_mfma_f32_16x16x32_bf16 v[32:35], v[144:147], v[168:171], v[32:35]
	v_mfma_f32_16x16x32_bf16 v[36:39], v[152:155], v[168:171], v[36:39]
	v_mfma_f32_16x16x32_bf16 v[16:19], v[144:147], v[176:179], v[16:19]
	v_mfma_f32_16x16x32_bf16 v[20:23], v[152:155], v[176:179], v[20:23]
	v_mfma_f32_16x16x32_bf16 v[4:7], v[144:147], v[184:187], v[4:7]
	v_mfma_f32_16x16x32_bf16 v[0:3], v[152:155], v[184:187], v[0:3]
	v_mfma_f32_16x16x32_bf16 v[48:51], v[148:151], v[164:167], v[48:51]
	v_mfma_f32_16x16x32_bf16 v[52:55], v[156:159], v[164:167], v[52:55]
	v_mfma_f32_16x16x32_bf16 v[32:35], v[148:151], v[172:175], v[32:35]
	v_mfma_f32_16x16x32_bf16 v[36:39], v[156:159], v[172:175], v[36:39]
	v_mfma_f32_16x16x32_bf16 v[16:19], v[148:151], v[180:183], v[16:19]
	v_mfma_f32_16x16x32_bf16 v[20:23], v[156:159], v[180:183], v[20:23]
	v_mfma_f32_16x16x32_bf16 v[4:7], v[148:151], v[188:191], v[4:7]
	v_mfma_f32_16x16x32_bf16 v[0:3], v[156:159], v[188:191], v[0:3]
	s_setprio 0
	s_barrier
	s_add_i32 s17, 0, 0x18000
	s_add_i32 s18, 0, 0x1c000
	v_add_u32_e32 v140, s17, v236
	v_add_u32_e32 v156, s18, v236
	ds_read_b128 v[128:131], v140
	ds_read_b128 v[132:135], v140 offset:1024
	ds_read_b128 v[136:139], v140 offset:2048
	ds_read_b128 v[140:143], v140 offset:3072
	ds_read_b128 v[144:147], v156
	ds_read_b128 v[148:151], v156 offset:1024
	ds_read_b128 v[152:155], v156 offset:2048
	ds_read_b128 v[156:159], v156 offset:3072
	s_add_u32 s10, s10, 0x4000
	s_addc_u32 s11, s11, 0
	s_mov_b32 m0, s48
	v_lshl_add_u64 v[216:217], s[10:11], 0, v[192:193]
	ds_read_b128 v[160:163], v240 offset:32768
	ds_read_b128 v[164:167], v240 offset:33792
	ds_read_b128 v[168:171], v240 offset:34816
	ds_read_b128 v[172:175], v240 offset:35840
	ds_read_b128 v[176:179], v240 offset:36864
	ds_read_b128 v[180:183], v240 offset:37888
	ds_read_b128 v[184:187], v240 offset:38912
	ds_read_b128 v[188:191], v240 offset:39936
	global_load_lds_dwordx4 v[216:217], off
	v_lshl_add_u64 v[216:217], s[10:11], 0, v[196:197]
	s_mov_b32 m0, s49
	s_nop 0
	global_load_lds_dwordx4 v[216:217], off
	s_waitcnt vmcnt(8)
	s_waitcnt lgkmcnt(0)
	s_barrier
	s_setprio 1
	s_waitcnt lgkmcnt(0)
	v_mfma_f32_16x16x32_bf16 v[120:123], v[128:131], v[160:163], v[120:123]
	v_mfma_f32_16x16x32_bf16 v[124:127], v[136:139], v[160:163], v[124:127]
	v_mfma_f32_16x16x32_bf16 v[104:107], v[128:131], v[168:171], v[104:107]
	v_mfma_f32_16x16x32_bf16 v[108:111], v[136:139], v[168:171], v[108:111]
	v_mfma_f32_16x16x32_bf16 v[88:91], v[128:131], v[176:179], v[88:91]
	v_mfma_f32_16x16x32_bf16 v[92:95], v[136:139], v[176:179], v[92:95]
	v_mfma_f32_16x16x32_bf16 v[72:75], v[128:131], v[184:187], v[72:75]
	v_mfma_f32_16x16x32_bf16 v[76:79], v[136:139], v[184:187], v[76:79]
	v_mfma_f32_16x16x32_bf16 v[120:123], v[132:135], v[164:167], v[120:123]
	v_mfma_f32_16x16x32_bf16 v[124:127], v[140:143], v[164:167], v[124:127]
	v_mfma_f32_16x16x32_bf16 v[104:107], v[132:135], v[172:175], v[104:107]
	v_mfma_f32_16x16x32_bf16 v[108:111], v[140:143], v[172:175], v[108:111]
	v_mfma_f32_16x16x32_bf16 v[88:91], v[132:135], v[180:183], v[88:91]
	v_mfma_f32_16x16x32_bf16 v[92:95], v[140:143], v[180:183], v[92:95]
	v_mfma_f32_16x16x32_bf16 v[72:75], v[132:135], v[188:191], v[72:75]
	v_mfma_f32_16x16x32_bf16 v[76:79], v[140:143], v[188:191], v[76:79]
	s_setprio 0
	s_setprio 1
	v_mfma_f32_16x16x32_bf16 v[112:115], v[144:147], v[160:163], v[112:115]
	v_mfma_f32_16x16x32_bf16 v[116:119], v[152:155], v[160:163], v[116:119]
	v_mfma_f32_16x16x32_bf16 v[96:99], v[144:147], v[168:171], v[96:99]
	v_mfma_f32_16x16x32_bf16 v[100:103], v[152:155], v[168:171], v[100:103]
	v_mfma_f32_16x16x32_bf16 v[80:83], v[144:147], v[176:179], v[80:83]
	v_mfma_f32_16x16x32_bf16 v[84:87], v[152:155], v[176:179], v[84:87]
	v_mfma_f32_16x16x32_bf16 v[64:67], v[144:147], v[184:187], v[64:67]
	v_mfma_f32_16x16x32_bf16 v[68:71], v[152:155], v[184:187], v[68:71]
	v_mfma_f32_16x16x32_bf16 v[112:115], v[148:151], v[164:167], v[112:115]
	v_mfma_f32_16x16x32_bf16 v[116:119], v[156:159], v[164:167], v[116:119]
	v_mfma_f32_16x16x32_bf16 v[96:99], v[148:151], v[172:175], v[96:99]
	v_mfma_f32_16x16x32_bf16 v[100:103], v[156:159], v[172:175], v[100:103]
	v_mfma_f32_16x16x32_bf16 v[80:83], v[148:151], v[180:183], v[80:83]
	v_mfma_f32_16x16x32_bf16 v[84:87], v[156:159], v[180:183], v[84:87]
	v_mfma_f32_16x16x32_bf16 v[64:67], v[148:151], v[188:191], v[64:67]
	v_mfma_f32_16x16x32_bf16 v[68:71], v[156:159], v[188:191], v[68:71]
	s_setprio 0
	s_barrier
; #define PG8_STAGE(bufoff, gbase, voff) do { _Pragma("unroll") for (int _i = 0; _i < 2; ++_i) \
;         __builtin_amdgcn_global_load_lds((const unsigned*)((const char*)(gbase) + (voff)[_i]), (LAS unsigned*)(lds + (bufoff) + ldsw + _i * 8192), 16, 0, 0); } while (0)
; #define PG8_LDA(dst, b, h) do { _Pragma("unroll") for (int m = 0; m < 4; ++m) _Pragma("unroll") for (int k = 0; k < 2; ++k) dst[m][k] = *(const LAS bf16x8*)(lds + PG8_SA(b, h) + aoff + m * 2048 + k * 1024); } while (0)
; #define PG8_MMA(ai, bj, At, Bt) do { __builtin_amdgcn_s_setprio(1); _Pragma("unroll") for (int m = 0; m < 4; ++m) _Pragma("unroll") for (int n = 0; n < 2; ++n) _Pragma("unroll") for (int k = 0; k < 2; ++k) \
;         acc[ai][bj][m][n] = __builtin_amdgcn_mfma_f32_16x16x32_bf16(Bt[n][k], At[m][k], acc[ai][bj][m][n], 0, 0, 0); __builtin_amdgcn_s_setprio(0); } while (0)
; #define PG8_WAIT_V(n) asm volatile("s_waitcnt vmcnt(" #n ")" ::: "memory")
; #define PG8_WAIT_L(n) asm volatile("s_waitcnt lgkmcnt(" #n ")" ::: "memory")
; #define PG8_BAR __builtin_amdgcn_s_barrier()
; #define PG8_SCHED __builtin_amdgcn_sched_barrier(0)
; template <class Epi>
; __device__ __forceinline__ void gemm_phase(LAS unsigned char* lds, const Gemm g, const StaticOrder& S, const Epi& E) {
;     ...
;             PG8_LDA(At, 1, 1); PG8_STAGE(PG8_SB(1, 0), b3, voffB); PG8_STAGE(PG8_SB(1, 1), b3 + hstepB, voffB); PG8_STAGE(PG8_SA(1, 0), a3, voffA);
;             PG8_WAIT_V(8); PG8_WAIT_L(0); PG8_BAR; PG8_MMA(1, 0, At, B0); PG8_MMA(1, 1, At, B1); PG8_BAR; PG8_SCHED;
;         }
;         if (wr == 0) PG8_BAR;
	s_add_i32 s10, s17, s33
	v_lshl_add_u64 v[212:213], v[212:213], 0, s[38:39]
	s_mov_b32 m0, s10
	ds_read_b128 v[160:163], v240 offset:49152
	ds_read_b128 v[164:167], v240 offset:50176
	ds_read_b128 v[168:171], v240 offset:51200
	ds_read_b128 v[172:175], v240 offset:52224
	ds_read_b128 v[176:179], v240 offset:53248
	ds_read_b128 v[180:183], v240 offset:54272
	ds_read_b128 v[184:187], v240 offset:55296
	ds_read_b128 v[188:191], v240 offset:56320
	global_load_lds_dwordx4 v[212:213], off
	s_add_i32 m0, s10, 0x2000
	s_add_u32 s8, s8, 0xb0080
	v_lshl_add_u64 v[212:213], v[214:215], 0, s[38:39]
	s_addc_u32 s9, s9, 0
	s_add_i32 s10, s18, s33
	global_load_lds_dwordx4 v[212:213], off
	v_lshl_add_u64 v[212:213], s[8:9], 0, v[194:195]
	s_mov_b32 m0, s10
	s_nop 0
	global_load_lds_dwordx4 v[212:213], off
	v_lshl_add_u64 v[212:213], s[8:9], 0, v[198:199]
	s_add_i32 m0, s10, 0x2000
	s_nop 0
	global_load_lds_dwordx4 v[212:213], off
	v_lshl_add_u64 v[212:213], s[2:3], 0, v[192:193]
	s_mov_b32 m0, s51
	s_nop 0
	global_load_lds_dwordx4 v[212:213], off
	v_lshl_add_u64 v[212:213], s[2:3], 0, v[196:197]
	s_mov_b32 m0, s52
	s_nop 0
	global_load_lds_dwordx4 v[212:213], off
	s_waitcnt vmcnt(8)
	s_waitcnt lgkmcnt(0)
	s_barrier
	s_setprio 1
	s_waitcnt lgkmcnt(0)
	v_mfma_f32_16x16x32_bf16 v[56:59], v[128:131], v[160:163], v[56:59]
	v_mfma_f32_16x16x32_bf16 v[60:63], v[136:139], v[160:163], v[60:63]
	v_mfma_f32_16x16x32_bf16 v[40:43], v[128:131], v[168:171], v[40:43]
	v_mfma_f32_16x16x32_bf16 v[44:47], v[136:139], v[168:171], v[44:47]
	v_mfma_f32_16x16x32_bf16 v[24:27], v[128:131], v[176:179], v[24:27]
	v_mfma_f32_16x16x32_bf16 v[28:31], v[136:139], v[176:179], v[28:31]
	v_mfma_f32_16x16x32_bf16 v[8:11], v[128:131], v[184:187], v[8:11]
	v_mfma_f32_16x16x32_bf16 v[12:15], v[136:139], v[184:187], v[12:15]
	v_mfma_f32_16x16x32_bf16 v[56:59], v[132:135], v[164:167], v[56:59]
	v_mfma_f32_16x16x32_bf16 v[60:63], v[140:143], v[164:167], v[60:63]
	v_mfma_f32_16x16x32_bf16 v[40:43], v[132:135], v[172:175], v[40:43]
	v_mfma_f32_16x16x32_bf16 v[44:47], v[140:143], v[172:175], v[44:47]
	v_mfma_f32_16x16x32_bf16 v[24:27], v[132:135], v[180:183], v[24:27]
	v_mfma_f32_16x16x32_bf16 v[28:31], v[140:143], v[180:183], v[28:31]
	v_mfma_f32_16x16x32_bf16 v[8:11], v[132:135], v[188:191], v[8:11]
	v_mfma_f32_16x16x32_bf16 v[12:15], v[140:143], v[188:191], v[12:15]
	s_setprio 0
	s_setprio 1
	v_mfma_f32_16x16x32_bf16 v[48:51], v[144:147], v[160:163], v[48:51]
	v_mfma_f32_16x16x32_bf16 v[52:55], v[152:155], v[160:163], v[52:55]
	v_mfma_f32_16x16x32_bf16 v[32:35], v[144:147], v[168:171], v[32:35]
	v_mfma_f32_16x16x32_bf16 v[36:39], v[152:155], v[168:171], v[36:39]
	v_mfma_f32_16x16x32_bf16 v[16:19], v[144:147], v[176:179], v[16:19]
	v_mfma_f32_16x16x32_bf16 v[20:23], v[152:155], v[176:179], v[20:23]
	v_mfma_f32_16x16x32_bf16 v[4:7], v[144:147], v[184:187], v[4:7]
	v_mfma_f32_16x16x32_bf16 v[0:3], v[152:155], v[184:187], v[0:3]
	v_mfma_f32_16x16x32_bf16 v[48:51], v[148:151], v[164:167], v[48:51]
	v_mfma_f32_16x16x32_bf16 v[52:55], v[156:159], v[164:167], v[52:55]
	v_mfma_f32_16x16x32_bf16 v[32:35], v[148:151], v[172:175], v[32:35]
	v_mfma_f32_16x16x32_bf16 v[36:39], v[156:159], v[172:175], v[36:39]
	v_mfma_f32_16x16x32_bf16 v[16:19], v[148:151], v[180:183], v[16:19]
	v_mfma_f32_16x16x32_bf16 v[20:23], v[156:159], v[180:183], v[20:23]
	v_mfma_f32_16x16x32_bf16 v[4:7], v[148:151], v[188:191], v[4:7]
	v_mfma_f32_16x16x32_bf16 v[0:3], v[156:159], v[188:191], v[0:3]
	s_setprio 0
	s_add_i32 s16, s16, 2
	s_add_u32 s14, s14, 0x100
	s_addc_u32 s15, s15, 0
	s_add_u32 s0, s0, 0x10000
	s_addc_u32 s1, s1, 0
	s_cmp_gt_u32 s16, 41
	s_barrier
	s_cbranch_scc0 .LBB0_548
	s_and_b64 vcc, exec, s[40:41]
	s_cbranch_vccz .LBB0_551
	s_barrier

; #define PG8_STAGE(bufoff, gbase, voff) do { _Pragma("unroll") for (int _i = 0; _i < 2; ++_i) \
;         __builtin_amdgcn_global_load_lds((const unsigned*)((const char*)(gbase) + (voff)[_i]), (LAS unsigned*)(lds + (bufoff) + ldsw + _i * 8192), 16, 0, 0); } while (0)
; #define PG8_LDA(dst, b, h) do { _Pragma("unroll") for (int m = 0; m < 4; ++m) _Pragma("unroll") for (int k = 0; k < 2; ++k) dst[m][k] = *(const LAS bf16x8*)(lds + PG8_SA(b, h) + aoff + m * 2048 + k * 1024); } while (0)
; #define PG8_LDB(dst, b, h) do { _Pragma("unroll") for (int n = 0; n < 2; ++n) _Pragma("unroll") for (int k = 0; k < 2; ++k) dst[n][k] = *(const LAS bf16x8*)(lds + PG8_SB(b, h) + boff + n * 2048 + k * 1024); } while (0)
; #define PG8_MMA(ai, bj, At, Bt) do { __builtin_amdgcn_s_setprio(1); _Pragma("unroll") for (int m = 0; m < 4; ++m) _Pragma("unroll") for (int n = 0; n < 2; ++n) _Pragma("unroll") for (int k = 0; k < 2; ++k) \
;         acc[ai][bj][m][n] = __builtin_amdgcn_mfma_f32_16x16x32_bf16(Bt[n][k], At[m][k], acc[ai][bj][m][n], 0, 0, 0); __builtin_amdgcn_s_setprio(0); } while (0)
; #define PG8_WAIT_V(n) asm volatile("s_waitcnt vmcnt(" #n ")" ::: "memory")
; #define PG8_WAIT_L(n) asm volatile("s_waitcnt lgkmcnt(" #n ")" ::: "memory")
; #define PG8_BAR __builtin_amdgcn_s_barrier()
; #define PG8_SCHED __builtin_amdgcn_sched_barrier(0)
; template <class Epi>
; __device__ __forceinline__ void gemm_phase(LAS unsigned char* lds, const Gemm g, const StaticOrder& S, const Epi& E) {
;     ...
;         for (int t = 0; t < nt; t += 2) {
;             const bool last = (t == nt - 2);
;             const char* a1 = cA + (size_t)(t + 1) * kstepA;
;             const char* a2 = last ? nA : cA + (size_t)(t + 2) * kstepA; const char* b2 = last ? nB : cB + (size_t)(t + 2) * kstep;
;             const char* a3 = a2 + kstepA; const char* b3 = b2 + kstep;
;             PG8_LDB(B0, 0, 0); PG8_LDB(B1, 0, 1); PG8_SCHED; PG8_LDA(At, 0, 0); PG8_STAGE(PG8_SA(1, 1), a1 + hstepA, voffA);
;             PG8_WAIT_V(8); PG8_WAIT_L(0); PG8_BAR; PG8_MMA(0, 0, At, B0); PG8_MMA(0, 1, At, B1); PG8_BAR; PG8_SCHED;
;             PG8_LDA(At, 0, 1); PG8_STAGE(PG8_SB(0, 0), b2, voffB); PG8_STAGE(PG8_SB(0, 1), b2 + hstepB, voffB); PG8_STAGE(PG8_SA(0, 0), a2, voffA);
.LBB0_687:
	ds_read_b128 v[128:131], v171
	ds_read_b128 v[132:135], v171 offset:1024
	ds_read_b128 v[158:161], v171 offset:2048
	ds_read_b128 v[162:165], v171 offset:3072
	ds_read_b128 v[166:169], v172
	ds_read_b128 v[180:183], v172 offset:1024
	ds_read_b128 v[184:187], v172 offset:2048
	ds_read_b128 v[188:191], v172 offset:3072
	s_add_u32 s12, s10, 0xfffc0080
	s_addc_u32 s13, s11, -1
	s_cmp_eq_u32 s30, 12
	s_cselect_b32 s15, s1, s13
	s_cselect_b32 s14, s3, s12
	s_cselect_b32 s13, s16, s19
	s_cselect_b32 s12, s17, s18
	v_lshl_add_u64 v[136:137], s[10:11], 0, v[146:147]
	s_add_i32 m0, s56, 0xc000
	ds_read_b128 v[192:195], v173
	ds_read_b128 v[196:199], v173 offset:1024
	ds_read_b128 v[200:203], v173 offset:2048
	ds_read_b128 v[204:207], v173 offset:3072
	ds_read_b128 v[212:215], v173 offset:4096
	ds_read_b128 v[216:219], v173 offset:5120
	ds_read_b128 v[220:223], v173 offset:6144
	ds_read_b128 v[224:227], v173 offset:7168
	global_load_lds_dwordx4 v[136:137], off
	v_lshl_add_u64 v[136:137], s[10:11], 0, v[148:149]
	s_add_i32 m0, s56, 0xe000
	s_nop 0
	global_load_lds_dwordx4 v[136:137], off
	s_waitcnt vmcnt(8)
	s_waitcnt lgkmcnt(0)
	s_barrier
	s_setprio 1
	s_waitcnt lgkmcnt(0)
	v_mfma_f32_16x16x32_bf16 v[124:127], v[128:131], v[192:195], v[124:127]
	v_mfma_f32_16x16x32_bf16 v[120:123], v[158:161], v[192:195], v[120:123]
	v_mfma_f32_16x16x32_bf16 v[108:111], v[128:131], v[200:203], v[108:111]
	v_mfma_f32_16x16x32_bf16 v[104:107], v[158:161], v[200:203], v[104:107]
	v_mfma_f32_16x16x32_bf16 v[92:95], v[128:131], v[212:215], v[92:95]
	v_mfma_f32_16x16x32_bf16 v[88:91], v[158:161], v[212:215], v[88:91]
	v_mfma_f32_16x16x32_bf16 v[76:79], v[128:131], v[220:223], v[76:79]
	v_mfma_f32_16x16x32_bf16 v[72:75], v[158:161], v[220:223], v[72:75]
	v_mfma_f32_16x16x32_bf16 v[124:127], v[132:135], v[196:199], v[124:127]
	v_mfma_f32_16x16x32_bf16 v[120:123], v[162:165], v[196:199], v[120:123]
	v_mfma_f32_16x16x32_bf16 v[108:111], v[132:135], v[204:207], v[108:111]
	v_mfma_f32_16x16x32_bf16 v[104:107], v[162:165], v[204:207], v[104:107]
	v_mfma_f32_16x16x32_bf16 v[92:95], v[132:135], v[216:219], v[92:95]
	v_mfma_f32_16x16x32_bf16 v[88:91], v[162:165], v[216:219], v[88:91]
	v_mfma_f32_16x16x32_bf16 v[76:79], v[132:135], v[224:227], v[76:79]
	v_mfma_f32_16x16x32_bf16 v[72:75], v[162:165], v[224:227], v[72:75]
	s_setprio 0
	s_setprio 1
	v_mfma_f32_16x16x32_bf16 v[116:119], v[166:169], v[192:195], v[116:119]
	v_mfma_f32_16x16x32_bf16 v[112:115], v[184:187], v[192:195], v[112:115]
	v_mfma_f32_16x16x32_bf16 v[100:103], v[166:169], v[200:203], v[100:103]
	v_mfma_f32_16x16x32_bf16 v[96:99], v[184:187], v[200:203], v[96:99]
	v_mfma_f32_16x16x32_bf16 v[84:87], v[166:169], v[212:215], v[84:87]
	v_mfma_f32_16x16x32_bf16 v[80:83], v[184:187], v[212:215], v[80:83]
	v_mfma_f32_16x16x32_bf16 v[68:71], v[166:169], v[220:223], v[68:71]
	v_mfma_f32_16x16x32_bf16 v[64:67], v[184:187], v[220:223], v[64:67]
	v_mfma_f32_16x16x32_bf16 v[116:119], v[180:183], v[196:199], v[116:119]
	v_mfma_f32_16x16x32_bf16 v[112:115], v[188:191], v[196:199], v[112:115]
	v_mfma_f32_16x16x32_bf16 v[100:103], v[180:183], v[204:207], v[100:103]
	v_mfma_f32_16x16x32_bf16 v[96:99], v[188:191], v[204:207], v[96:99]
	v_mfma_f32_16x16x32_bf16 v[84:87], v[180:183], v[216:219], v[84:87]
	v_mfma_f32_16x16x32_bf16 v[80:83], v[188:191], v[216:219], v[80:83]
	v_mfma_f32_16x16x32_bf16 v[68:71], v[180:183], v[224:227], v[68:71]
	v_mfma_f32_16x16x32_bf16 v[64:67], v[188:191], v[224:227], v[64:67]
	s_setprio 0
	s_barrier
	s_add_i32 s33, s72, s43
	v_lshl_add_u64 v[136:137], s[12:13], 0, v[138:139]
	s_mov_b32 m0, s33
	ds_read_b128 v[192:195], v173 offset:16384
	ds_read_b128 v[196:199], v173 offset:17408
	ds_read_b128 v[200:203], v173 offset:18432
	ds_read_b128 v[204:207], v173 offset:19456
	ds_read_b128 v[212:215], v173 offset:20480
	ds_read_b128 v[216:219], v173 offset:21504
	ds_read_b128 v[220:223], v173 offset:22528
	ds_read_b128 v[224:227], v173 offset:23552
	global_load_lds_dwordx4 v[136:137], off
	s_add_i32 m0, s33, 0x2000
	s_add_u32 s50, s12, 0x40000
	v_lshl_add_u64 v[228:229], s[12:13], 0, v[140:141]
	s_addc_u32 s51, s13, 0
	s_add_i32 s33, s73, s43
	global_load_lds_dwordx4 v[228:229], off
	v_lshl_add_u64 v[230:231], s[50:51], 0, v[138:139]
	s_mov_b32 m0, s33
	v_lshl_add_u64 v[232:233], s[14:15], 0, v[140:141]
	global_load_lds_dwordx4 v[230:231], off
	v_lshl_add_u64 v[230:231], s[50:51], 0, v[140:141]
	s_add_i32 m0, s33, 0x2000
	s_nop 0
	global_load_lds_dwordx4 v[230:231], off
	v_lshl_add_u64 v[230:231], s[14:15], 0, v[138:139]
	s_mov_b32 m0, s56
	s_nop 0
	global_load_lds_dwordx4 v[230:231], off
	s_mov_b32 m0, s57
	s_nop 0
	global_load_lds_dwordx4 v[232:233], off
	s_waitcnt vmcnt(8)
	s_waitcnt lgkmcnt(0)
	s_barrier
; #define PG8_STAGE(bufoff, gbase, voff) do { _Pragma("unroll") for (int _i = 0; _i < 2; ++_i) \
;         __builtin_amdgcn_global_load_lds((const unsigned*)((const char*)(gbase) + (voff)[_i]), (LAS unsigned*)(lds + (bufoff) + ldsw + _i * 8192), 16, 0, 0); } while (0)
; #define PG8_LDA(dst, b, h) do { _Pragma("unroll") for (int m = 0; m < 4; ++m) _Pragma("unroll") for (int k = 0; k < 2; ++k) dst[m][k] = *(const LAS bf16x8*)(lds + PG8_SA(b, h) + aoff + m * 2048 + k * 1024); } while (0)
; #define PG8_LDB(dst, b, h) do { _Pragma("unroll") for (int n = 0; n < 2; ++n) _Pragma("unroll") for (int k = 0; k < 2; ++k) dst[n][k] = *(const LAS bf16x8*)(lds + PG8_SB(b, h) + boff + n * 2048 + k * 1024); } while (0)
; #define PG8_MMA(ai, bj, At, Bt) do { __builtin_amdgcn_s_setprio(1); _Pragma("unroll") for (int m = 0; m < 4; ++m) _Pragma("unroll") for (int n = 0; n < 2; ++n) _Pragma("unroll") for (int k = 0; k < 2; ++k) \
;         acc[ai][bj][m][n] = __builtin_amdgcn_mfma_f32_16x16x32_bf16(Bt[n][k], At[m][k], acc[ai][bj][m][n], 0, 0, 0); __builtin_amdgcn_s_setprio(0); } while (0)
; #define PG8_WAIT_V(n) asm volatile("s_waitcnt vmcnt(" #n ")" ::: "memory")
; #define PG8_WAIT_L(n) asm volatile("s_waitcnt lgkmcnt(" #n ")" ::: "memory")
; #define PG8_BAR __builtin_amdgcn_s_barrier()
; #define PG8_SCHED __builtin_amdgcn_sched_barrier(0)
; template <class Epi>
; __device__ __forceinline__ void gemm_phase(LAS unsigned char* lds, const Gemm g, const StaticOrder& S, const Epi& E) {
;     ...
;             PG8_WAIT_V(8); PG8_WAIT_L(0); PG8_BAR; PG8_MMA(1, 0, At, B0); PG8_MMA(1, 1, At, B1); PG8_BAR; PG8_SCHED;
;             PG8_LDB(B0, 1, 0); PG8_LDB(B1, 1, 1); PG8_SCHED; PG8_LDA(At, 1, 0); PG8_STAGE(PG8_SA(0, 1), a2 + hstepA, voffA);
;             PG8_WAIT_V(8); PG8_WAIT_L(0); PG8_BAR; PG8_MMA(0, 0, At, B0); PG8_MMA(0, 1, At, B1); PG8_BAR; PG8_SCHED;
;             PG8_LDA(At, 1, 1); PG8_STAGE(PG8_SB(1, 0), b3, voffB); PG8_STAGE(PG8_SB(1, 1), b3 + hstepB, voffB); PG8_STAGE(PG8_SA(1, 0), a3, voffA);
	s_setprio 1
	s_waitcnt lgkmcnt(0)
	v_mfma_f32_16x16x32_bf16 v[60:63], v[128:131], v[192:195], v[60:63]
	v_mfma_f32_16x16x32_bf16 v[56:59], v[158:161], v[192:195], v[56:59]
	v_mfma_f32_16x16x32_bf16 v[44:47], v[128:131], v[200:203], v[44:47]
	v_mfma_f32_16x16x32_bf16 v[40:43], v[158:161], v[200:203], v[40:43]
	v_mfma_f32_16x16x32_bf16 v[28:31], v[128:131], v[212:215], v[28:31]
	v_mfma_f32_16x16x32_bf16 v[24:27], v[158:161], v[212:215], v[24:27]
	v_mfma_f32_16x16x32_bf16 v[12:15], v[128:131], v[220:223], v[12:15]
	v_mfma_f32_16x16x32_bf16 v[8:11], v[158:161], v[220:223], v[8:11]
	v_mfma_f32_16x16x32_bf16 v[60:63], v[132:135], v[196:199], v[60:63]
	v_mfma_f32_16x16x32_bf16 v[56:59], v[162:165], v[196:199], v[56:59]
	v_mfma_f32_16x16x32_bf16 v[44:47], v[132:135], v[204:207], v[44:47]
	v_mfma_f32_16x16x32_bf16 v[40:43], v[162:165], v[204:207], v[40:43]
	v_mfma_f32_16x16x32_bf16 v[28:31], v[132:135], v[216:219], v[28:31]
	v_mfma_f32_16x16x32_bf16 v[24:27], v[162:165], v[216:219], v[24:27]
	v_mfma_f32_16x16x32_bf16 v[12:15], v[132:135], v[224:227], v[12:15]
	v_mfma_f32_16x16x32_bf16 v[8:11], v[162:165], v[224:227], v[8:11]
	s_setprio 0
	s_setprio 1
	v_mfma_f32_16x16x32_bf16 v[52:55], v[166:169], v[192:195], v[52:55]
	v_mfma_f32_16x16x32_bf16 v[48:51], v[184:187], v[192:195], v[48:51]
	v_mfma_f32_16x16x32_bf16 v[36:39], v[166:169], v[200:203], v[36:39]
	v_mfma_f32_16x16x32_bf16 v[32:35], v[184:187], v[200:203], v[32:35]
	v_mfma_f32_16x16x32_bf16 v[20:23], v[166:169], v[212:215], v[20:23]
	v_mfma_f32_16x16x32_bf16 v[16:19], v[184:187], v[212:215], v[16:19]
	v_mfma_f32_16x16x32_bf16 v[4:7], v[166:169], v[220:223], v[4:7]
	v_mfma_f32_16x16x32_bf16 v[0:3], v[184:187], v[220:223], v[0:3]
	v_mfma_f32_16x16x32_bf16 v[52:55], v[180:183], v[196:199], v[52:55]
	v_mfma_f32_16x16x32_bf16 v[48:51], v[188:191], v[196:199], v[48:51]
	v_mfma_f32_16x16x32_bf16 v[36:39], v[180:183], v[204:207], v[36:39]
	v_mfma_f32_16x16x32_bf16 v[32:35], v[188:191], v[204:207], v[32:35]
	v_mfma_f32_16x16x32_bf16 v[20:23], v[180:183], v[216:219], v[20:23]
	v_mfma_f32_16x16x32_bf16 v[16:19], v[188:191], v[216:219], v[16:19]
	v_mfma_f32_16x16x32_bf16 v[4:7], v[180:183], v[224:227], v[4:7]
	v_mfma_f32_16x16x32_bf16 v[0:3], v[188:191], v[224:227], v[0:3]
	s_setprio 0
	s_barrier
	s_add_i32 s33, 0, 0x18000
	v_add_u32_e32 v142, s33, v157
	s_add_i32 s45, 0, 0x1c000
	ds_read_b128 v[128:131], v142
	ds_read_b128 v[132:135], v142 offset:1024
	ds_read_b128 v[158:161], v142 offset:2048
	ds_read_b128 v[162:165], v142 offset:3072
	v_add_u32_e32 v142, s45, v157
	ds_read_b128 v[166:169], v142
	ds_read_b128 v[180:183], v142 offset:1024
	ds_read_b128 v[184:187], v142 offset:2048
	ds_read_b128 v[188:191], v142 offset:3072
	s_add_u32 s14, s14, 0x40000
	s_addc_u32 s15, s15, 0
	s_mov_b32 m0, s58
	v_lshl_add_u64 v[236:237], s[14:15], 0, v[138:139]
	ds_read_b128 v[192:195], v173 offset:32768
	ds_read_b128 v[196:199], v173 offset:33792
	ds_read_b128 v[200:203], v173 offset:34816
	ds_read_b128 v[204:207], v173 offset:35840
	ds_read_b128 v[212:215], v173 offset:36864
	ds_read_b128 v[216:219], v173 offset:37888
	ds_read_b128 v[220:223], v173 offset:38912
	ds_read_b128 v[224:227], v173 offset:39936
	global_load_lds_dwordx4 v[236:237], off
	v_lshl_add_u64 v[236:237], s[14:15], 0, v[140:141]
	s_mov_b32 m0, s59
	s_nop 0
	global_load_lds_dwordx4 v[236:237], off
	s_waitcnt vmcnt(8)
	s_waitcnt lgkmcnt(0)
	s_barrier
	s_setprio 1
	s_waitcnt lgkmcnt(0)
	v_mfma_f32_16x16x32_bf16 v[124:127], v[128:131], v[192:195], v[124:127]
	v_mfma_f32_16x16x32_bf16 v[120:123], v[158:161], v[192:195], v[120:123]
	v_mfma_f32_16x16x32_bf16 v[108:111], v[128:131], v[200:203], v[108:111]
	v_mfma_f32_16x16x32_bf16 v[104:107], v[158:161], v[200:203], v[104:107]
	v_mfma_f32_16x16x32_bf16 v[92:95], v[128:131], v[212:215], v[92:95]
	v_mfma_f32_16x16x32_bf16 v[88:91], v[158:161], v[212:215], v[88:91]
	v_mfma_f32_16x16x32_bf16 v[76:79], v[128:131], v[220:223], v[76:79]
	v_mfma_f32_16x16x32_bf16 v[72:75], v[158:161], v[220:223], v[72:75]
	v_mfma_f32_16x16x32_bf16 v[124:127], v[132:135], v[196:199], v[124:127]
	v_mfma_f32_16x16x32_bf16 v[120:123], v[162:165], v[196:199], v[120:123]
	v_mfma_f32_16x16x32_bf16 v[108:111], v[132:135], v[204:207], v[108:111]
	v_mfma_f32_16x16x32_bf16 v[104:107], v[162:165], v[204:207], v[104:107]
	v_mfma_f32_16x16x32_bf16 v[92:95], v[132:135], v[216:219], v[92:95]
	v_mfma_f32_16x16x32_bf16 v[88:91], v[162:165], v[216:219], v[88:91]
	v_mfma_f32_16x16x32_bf16 v[76:79], v[132:135], v[224:227], v[76:79]
	v_mfma_f32_16x16x32_bf16 v[72:75], v[162:165], v[224:227], v[72:75]
	s_setprio 0
	s_setprio 1
	v_mfma_f32_16x16x32_bf16 v[116:119], v[166:169], v[192:195], v[116:119]
	v_mfma_f32_16x16x32_bf16 v[112:115], v[184:187], v[192:195], v[112:115]
	v_mfma_f32_16x16x32_bf16 v[100:103], v[166:169], v[200:203], v[100:103]
	v_mfma_f32_16x16x32_bf16 v[96:99], v[184:187], v[200:203], v[96:99]
	v_mfma_f32_16x16x32_bf16 v[84:87], v[166:169], v[212:215], v[84:87]
	v_mfma_f32_16x16x32_bf16 v[80:83], v[184:187], v[212:215], v[80:83]
	v_mfma_f32_16x16x32_bf16 v[68:71], v[166:169], v[220:223], v[68:71]
	v_mfma_f32_16x16x32_bf16 v[64:67], v[184:187], v[220:223], v[64:67]
	v_mfma_f32_16x16x32_bf16 v[116:119], v[180:183], v[196:199], v[116:119]
	v_mfma_f32_16x16x32_bf16 v[112:115], v[188:191], v[196:199], v[112:115]
	v_mfma_f32_16x16x32_bf16 v[100:103], v[180:183], v[204:207], v[100:103]
	v_mfma_f32_16x16x32_bf16 v[96:99], v[188:191], v[204:207], v[96:99]
	v_mfma_f32_16x16x32_bf16 v[84:87], v[180:183], v[216:219], v[84:87]
	v_mfma_f32_16x16x32_bf16 v[80:83], v[188:191], v[216:219], v[80:83]
	v_mfma_f32_16x16x32_bf16 v[68:71], v[180:183], v[224:227], v[68:71]
	v_mfma_f32_16x16x32_bf16 v[64:67], v[188:191], v[224:227], v[64:67]
	s_setprio 0
	s_barrier
; #define PG8_STAGE(bufoff, gbase, voff) do { _Pragma("unroll") for (int _i = 0; _i < 2; ++_i) \
;         __builtin_amdgcn_global_load_lds((const unsigned*)((const char*)(gbase) + (voff)[_i]), (LAS unsigned*)(lds + (bufoff) + ldsw + _i * 8192), 16, 0, 0); } while (0)
; #define PG8_LDA(dst, b, h) do { _Pragma("unroll") for (int m = 0; m < 4; ++m) _Pragma("unroll") for (int k = 0; k < 2; ++k) dst[m][k] = *(const LAS bf16x8*)(lds + PG8_SA(b, h) + aoff + m * 2048 + k * 1024); } while (0)
; #define PG8_MMA(ai, bj, At, Bt) do { __builtin_amdgcn_s_setprio(1); _Pragma("unroll") for (int m = 0; m < 4; ++m) _Pragma("unroll") for (int n = 0; n < 2; ++n) _Pragma("unroll") for (int k = 0; k < 2; ++k) \
;         acc[ai][bj][m][n] = __builtin_amdgcn_mfma_f32_16x16x32_bf16(Bt[n][k], At[m][k], acc[ai][bj][m][n], 0, 0, 0); __builtin_amdgcn_s_setprio(0); } while (0)
; #define PG8_WAIT_V(n) asm volatile("s_waitcnt vmcnt(" #n ")" ::: "memory")
; #define PG8_WAIT_L(n) asm volatile("s_waitcnt lgkmcnt(" #n ")" ::: "memory")
; #define PG8_BAR __builtin_amdgcn_s_barrier()
; #define PG8_SCHED __builtin_amdgcn_sched_barrier(0)
; template <class Epi>
; __device__ __forceinline__ void gemm_phase(LAS unsigned char* lds, const Gemm g, const StaticOrder& S, const Epi& E) {
;     ...
;             PG8_LDA(At, 1, 1); PG8_STAGE(PG8_SB(1, 0), b3, voffB); PG8_STAGE(PG8_SB(1, 1), b3 + hstepB, voffB); PG8_STAGE(PG8_SA(1, 0), a3, voffA);
;             PG8_WAIT_V(8); PG8_WAIT_L(0); PG8_BAR; PG8_MMA(1, 0, At, B0); PG8_MMA(1, 1, At, B1); PG8_BAR; PG8_SCHED;
;         }
;         if (wr == 0) PG8_BAR;
	s_add_i32 s14, s33, s43
	v_lshl_add_u64 v[136:137], v[136:137], 0, s[38:39]
	s_mov_b32 m0, s14
	ds_read_b128 v[192:195], v173 offset:49152
	ds_read_b128 v[196:199], v173 offset:50176
	ds_read_b128 v[200:203], v173 offset:51200
	ds_read_b128 v[204:207], v173 offset:52224
	ds_read_b128 v[212:215], v173 offset:53248
	ds_read_b128 v[216:219], v173 offset:54272
	ds_read_b128 v[220:223], v173 offset:55296
	ds_read_b128 v[224:227], v173 offset:56320
	global_load_lds_dwordx4 v[136:137], off
	s_add_i32 m0, s14, 0x2000
	s_add_u32 s12, s12, 0x40080
	v_lshl_add_u64 v[136:137], v[228:229], 0, s[38:39]
	s_addc_u32 s13, s13, 0
	s_add_i32 s14, s45, s43
	global_load_lds_dwordx4 v[136:137], off
	v_lshl_add_u64 v[136:137], s[12:13], 0, v[138:139]
	s_mov_b32 m0, s14
	s_nop 0
	global_load_lds_dwordx4 v[136:137], off
	v_lshl_add_u64 v[136:137], s[12:13], 0, v[140:141]
	s_add_i32 m0, s14, 0x2000
	s_nop 0
	global_load_lds_dwordx4 v[136:137], off
	v_lshl_add_u64 v[136:137], v[230:231], 0, s[38:39]
	s_mov_b32 m0, s62
	s_nop 0
	global_load_lds_dwordx4 v[136:137], off
	v_lshl_add_u64 v[136:137], v[232:233], 0, s[38:39]
	s_mov_b32 m0, s63
	s_nop 0
	global_load_lds_dwordx4 v[136:137], off
	s_waitcnt vmcnt(8)
	s_waitcnt lgkmcnt(0)
	s_barrier
	s_setprio 1
	s_waitcnt lgkmcnt(0)
	v_mfma_f32_16x16x32_bf16 v[60:63], v[128:131], v[192:195], v[60:63]
	v_mfma_f32_16x16x32_bf16 v[56:59], v[158:161], v[192:195], v[56:59]
	v_mfma_f32_16x16x32_bf16 v[44:47], v[128:131], v[200:203], v[44:47]
	v_mfma_f32_16x16x32_bf16 v[40:43], v[158:161], v[200:203], v[40:43]
	v_mfma_f32_16x16x32_bf16 v[28:31], v[128:131], v[212:215], v[28:31]
	v_mfma_f32_16x16x32_bf16 v[24:27], v[158:161], v[212:215], v[24:27]
	v_mfma_f32_16x16x32_bf16 v[12:15], v[128:131], v[220:223], v[12:15]
	v_mfma_f32_16x16x32_bf16 v[8:11], v[158:161], v[220:223], v[8:11]
	v_mfma_f32_16x16x32_bf16 v[60:63], v[132:135], v[196:199], v[60:63]
	v_mfma_f32_16x16x32_bf16 v[56:59], v[162:165], v[196:199], v[56:59]
	v_mfma_f32_16x16x32_bf16 v[44:47], v[132:135], v[204:207], v[44:47]
	v_mfma_f32_16x16x32_bf16 v[40:43], v[162:165], v[204:207], v[40:43]
	v_mfma_f32_16x16x32_bf16 v[28:31], v[132:135], v[216:219], v[28:31]
	v_mfma_f32_16x16x32_bf16 v[24:27], v[162:165], v[216:219], v[24:27]
	v_mfma_f32_16x16x32_bf16 v[12:15], v[132:135], v[224:227], v[12:15]
	v_mfma_f32_16x16x32_bf16 v[8:11], v[162:165], v[224:227], v[8:11]
	s_setprio 0
	s_setprio 1
	v_mfma_f32_16x16x32_bf16 v[52:55], v[166:169], v[192:195], v[52:55]
	v_mfma_f32_16x16x32_bf16 v[48:51], v[184:187], v[192:195], v[48:51]
	v_mfma_f32_16x16x32_bf16 v[36:39], v[166:169], v[200:203], v[36:39]
	v_mfma_f32_16x16x32_bf16 v[32:35], v[184:187], v[200:203], v[32:35]
	v_mfma_f32_16x16x32_bf16 v[20:23], v[166:169], v[212:215], v[20:23]
	v_mfma_f32_16x16x32_bf16 v[16:19], v[184:187], v[212:215], v[16:19]
	v_mfma_f32_16x16x32_bf16 v[4:7], v[166:169], v[220:223], v[4:7]
	v_mfma_f32_16x16x32_bf16 v[0:3], v[184:187], v[220:223], v[0:3]
	v_mfma_f32_16x16x32_bf16 v[52:55], v[180:183], v[196:199], v[52:55]
	v_mfma_f32_16x16x32_bf16 v[48:51], v[188:191], v[196:199], v[48:51]
	v_mfma_f32_16x16x32_bf16 v[36:39], v[180:183], v[204:207], v[36:39]
	v_mfma_f32_16x16x32_bf16 v[32:35], v[188:191], v[204:207], v[32:35]
	v_mfma_f32_16x16x32_bf16 v[20:23], v[180:183], v[216:219], v[20:23]
	v_mfma_f32_16x16x32_bf16 v[16:19], v[188:191], v[216:219], v[16:19]
	v_mfma_f32_16x16x32_bf16 v[4:7], v[180:183], v[224:227], v[4:7]
	v_mfma_f32_16x16x32_bf16 v[0:3], v[188:191], v[224:227], v[0:3]
	s_setprio 0
	s_add_i32 s30, s30, 2
	s_add_u32 s10, s10, 0x100
	s_addc_u32 s11, s11, 0
	s_add_u32 s18, s18, 0x100
	s_addc_u32 s19, s19, 0
	s_cmp_gt_u32 s30, 13
	s_barrier
	s_cbranch_scc0 .LBB0_687
	s_and_b64 vcc, exec, s[40:41]
	s_cbranch_vccz .LBB0_690
	s_barrier

; #define PG8_STAGE(bufoff, gbase, voff) do { _Pragma("unroll") for (int _i = 0; _i < 2; ++_i) \
;         __builtin_amdgcn_global_load_lds((const unsigned*)((const char*)(gbase) + (voff)[_i]), (LAS unsigned*)(lds + (bufoff) + ldsw + _i * 8192), 16, 0, 0); } while (0)
; #define PG8_LDA(dst, b, h) do { _Pragma("unroll") for (int m = 0; m < 4; ++m) _Pragma("unroll") for (int k = 0; k < 2; ++k) dst[m][k] = *(const LAS bf16x8*)(lds + PG8_SA(b, h) + aoff + m * 2048 + k * 1024); } while (0)
; #define PG8_LDB(dst, b, h) do { _Pragma("unroll") for (int n = 0; n < 2; ++n) _Pragma("unroll") for (int k = 0; k < 2; ++k) dst[n][k] = *(const LAS bf16x8*)(lds + PG8_SB(b, h) + boff + n * 2048 + k * 1024); } while (0)
; #define PG8_MMA(ai, bj, At, Bt) do { __builtin_amdgcn_s_setprio(1); _Pragma("unroll") for (int m = 0; m < 4; ++m) _Pragma("unroll") for (int n = 0; n < 2; ++n) _Pragma("unroll") for (int k = 0; k < 2; ++k) \
;         acc[ai][bj][m][n] = __builtin_amdgcn_mfma_f32_16x16x32_bf16(Bt[n][k], At[m][k], acc[ai][bj][m][n], 0, 0, 0); __builtin_amdgcn_s_setprio(0); } while (0)
; #define PG8_WAIT_V(n) asm volatile("s_waitcnt vmcnt(" #n ")" ::: "memory")
; #define PG8_WAIT_L(n) asm volatile("s_waitcnt lgkmcnt(" #n ")" ::: "memory")
; #define PG8_BAR __builtin_amdgcn_s_barrier()
; #define PG8_SCHED __builtin_amdgcn_sched_barrier(0)
; template <class Epi>
; __device__ __forceinline__ void gemm_phase(LAS unsigned char* lds, const Gemm g, const StaticOrder& S, const Epi& E) {
;     ...
;         for (int t = 0; t < nt; t += 2) {
;             const bool last = (t == nt - 2);
;             const char* a1 = cA + (size_t)(t + 1) * kstepA;
;             const char* a2 = last ? nA : cA + (size_t)(t + 2) * kstepA; const char* b2 = last ? nB : cB + (size_t)(t + 2) * kstep;
;             const char* a3 = a2 + kstepA; const char* b3 = b2 + kstep;
;             PG8_LDB(B0, 0, 0); PG8_LDB(B1, 0, 1); PG8_SCHED; PG8_LDA(At, 0, 0); PG8_STAGE(PG8_SA(1, 1), a1 + hstepA, voffA);
;             PG8_WAIT_V(8); PG8_WAIT_L(0); PG8_BAR; PG8_MMA(0, 0, At, B0); PG8_MMA(0, 1, At, B1); PG8_BAR; PG8_SCHED;
;             PG8_LDA(At, 0, 1); PG8_STAGE(PG8_SB(0, 0), b2, voffB); PG8_STAGE(PG8_SB(0, 1), b2 + hstepB, voffB); PG8_STAGE(PG8_SA(0, 0), a2, voffA);
.LBB0_1460:
	ds_read_b128 v[128:131], v199
	ds_read_b128 v[132:135], v199 offset:1024
	ds_read_b128 v[136:139], v199 offset:2048
	ds_read_b128 v[140:143], v199 offset:3072
	ds_read_b128 v[144:147], v200
	ds_read_b128 v[148:151], v200 offset:1024
	ds_read_b128 v[152:155], v200 offset:2048
	ds_read_b128 v[156:159], v200 offset:3072
	s_add_u32 s6, s18, 0x100
	s_addc_u32 s7, s19, 0
	s_cmp_eq_u32 s45, 4
	s_cselect_b32 s23, s15, s7
	s_cselect_b32 s22, s14, s6
	s_cselect_b32 s21, s13, s44
	s_cselect_b32 s20, s42, s43
	v_lshl_add_u64 v[206:207], s[18:19], 0, v[176:177]
	s_add_i32 m0, s26, 0xc000
	ds_read_b128 v[160:163], v201
	ds_read_b128 v[164:167], v201 offset:1024
	ds_read_b128 v[184:187], v201 offset:2048
	ds_read_b128 v[188:191], v201 offset:3072
	ds_read_b128 v[192:195], v201 offset:4096
	ds_read_b128 v[202:205], v201 offset:5120
	ds_read_b128 v[210:213], v201 offset:6144
	ds_read_b128 v[214:217], v201 offset:7168
	global_load_lds_dwordx4 v[206:207], off
	v_lshl_add_u64 v[206:207], s[18:19], 0, v[178:179]
	s_add_i32 m0, s26, 0xe000
	s_nop 0
	global_load_lds_dwordx4 v[206:207], off
	s_waitcnt vmcnt(8)
	s_waitcnt lgkmcnt(0)
	s_barrier
	s_setprio 1
	s_waitcnt lgkmcnt(0)
	v_mfma_f32_16x16x32_bf16 v[124:127], v[128:131], v[160:163], v[124:127]
	v_mfma_f32_16x16x32_bf16 v[120:123], v[136:139], v[160:163], v[120:123]
	v_mfma_f32_16x16x32_bf16 v[112:115], v[128:131], v[184:187], v[112:115]
	v_mfma_f32_16x16x32_bf16 v[104:107], v[136:139], v[184:187], v[104:107]
	v_mfma_f32_16x16x32_bf16 v[96:99], v[128:131], v[192:195], v[96:99]
	v_mfma_f32_16x16x32_bf16 v[88:91], v[136:139], v[192:195], v[88:91]
	v_mfma_f32_16x16x32_bf16 v[80:83], v[128:131], v[210:213], v[80:83]
	v_mfma_f32_16x16x32_bf16 v[72:75], v[136:139], v[210:213], v[72:75]
	v_mfma_f32_16x16x32_bf16 v[124:127], v[132:135], v[164:167], v[124:127]
	v_mfma_f32_16x16x32_bf16 v[120:123], v[140:143], v[164:167], v[120:123]
	v_mfma_f32_16x16x32_bf16 v[112:115], v[132:135], v[188:191], v[112:115]
	v_mfma_f32_16x16x32_bf16 v[104:107], v[140:143], v[188:191], v[104:107]
	v_mfma_f32_16x16x32_bf16 v[96:99], v[132:135], v[202:205], v[96:99]
	v_mfma_f32_16x16x32_bf16 v[88:91], v[140:143], v[202:205], v[88:91]
	v_mfma_f32_16x16x32_bf16 v[80:83], v[132:135], v[214:217], v[80:83]
	v_mfma_f32_16x16x32_bf16 v[72:75], v[140:143], v[214:217], v[72:75]
	s_setprio 0
	s_setprio 1
	v_mfma_f32_16x16x32_bf16 v[116:119], v[144:147], v[160:163], v[116:119]
	v_mfma_f32_16x16x32_bf16 v[108:111], v[152:155], v[160:163], v[108:111]
	v_mfma_f32_16x16x32_bf16 v[100:103], v[144:147], v[184:187], v[100:103]
	v_mfma_f32_16x16x32_bf16 v[92:95], v[152:155], v[184:187], v[92:95]
	v_mfma_f32_16x16x32_bf16 v[84:87], v[144:147], v[192:195], v[84:87]
	v_mfma_f32_16x16x32_bf16 v[76:79], v[152:155], v[192:195], v[76:79]
	v_mfma_f32_16x16x32_bf16 v[68:71], v[144:147], v[210:213], v[68:71]
	v_mfma_f32_16x16x32_bf16 v[64:67], v[152:155], v[210:213], v[64:67]
	v_mfma_f32_16x16x32_bf16 v[116:119], v[148:151], v[164:167], v[116:119]
	v_mfma_f32_16x16x32_bf16 v[108:111], v[156:159], v[164:167], v[108:111]
	v_mfma_f32_16x16x32_bf16 v[100:103], v[148:151], v[188:191], v[100:103]
	v_mfma_f32_16x16x32_bf16 v[92:95], v[156:159], v[188:191], v[92:95]
	v_mfma_f32_16x16x32_bf16 v[84:87], v[148:151], v[202:205], v[84:87]
	v_mfma_f32_16x16x32_bf16 v[76:79], v[156:159], v[202:205], v[76:79]
	v_mfma_f32_16x16x32_bf16 v[68:71], v[148:151], v[214:217], v[68:71]
	v_mfma_f32_16x16x32_bf16 v[64:67], v[156:159], v[214:217], v[64:67]
	s_setprio 0
	s_barrier
	s_add_i32 s18, s36, s25
	v_lshl_add_u64 v[206:207], s[20:21], 0, v[170:171]
	s_mov_b32 m0, s18
	ds_read_b128 v[160:163], v201 offset:16384
	ds_read_b128 v[164:167], v201 offset:17408
	ds_read_b128 v[184:187], v201 offset:18432
	ds_read_b128 v[188:191], v201 offset:19456
	ds_read_b128 v[192:195], v201 offset:20480
	ds_read_b128 v[202:205], v201 offset:21504
	ds_read_b128 v[210:213], v201 offset:22528
	ds_read_b128 v[214:217], v201 offset:23552
	global_load_lds_dwordx4 v[206:207], off
	s_add_i32 m0, s18, 0x2000
	s_add_u32 s18, s20, 0x20000
	v_lshl_add_u64 v[218:219], s[20:21], 0, v[174:175]
	s_addc_u32 s19, s21, 0
	s_add_i32 s46, s37, s25
	global_load_lds_dwordx4 v[218:219], off
	v_lshl_add_u64 v[220:221], s[18:19], 0, v[170:171]
	s_mov_b32 m0, s46
	v_lshl_add_u64 v[222:223], s[22:23], 0, v[172:173]
	global_load_lds_dwordx4 v[220:221], off
	v_lshl_add_u64 v[220:221], s[18:19], 0, v[174:175]
	s_add_i32 m0, s46, 0x2000
	s_nop 0
	global_load_lds_dwordx4 v[220:221], off
	v_lshl_add_u64 v[220:221], s[22:23], 0, v[168:169]
	s_mov_b32 m0, s26
	s_nop 0
	global_load_lds_dwordx4 v[220:221], off
	s_mov_b32 m0, s27
	s_nop 0
	global_load_lds_dwordx4 v[222:223], off
	s_waitcnt vmcnt(8)
	s_waitcnt lgkmcnt(0)
	s_barrier
; #define PG8_STAGE(bufoff, gbase, voff) do { _Pragma("unroll") for (int _i = 0; _i < 2; ++_i) \
;         __builtin_amdgcn_global_load_lds((const unsigned*)((const char*)(gbase) + (voff)[_i]), (LAS unsigned*)(lds + (bufoff) + ldsw + _i * 8192), 16, 0, 0); } while (0)
; #define PG8_LDA(dst, b, h) do { _Pragma("unroll") for (int m = 0; m < 4; ++m) _Pragma("unroll") for (int k = 0; k < 2; ++k) dst[m][k] = *(const LAS bf16x8*)(lds + PG8_SA(b, h) + aoff + m * 2048 + k * 1024); } while (0)
; #define PG8_LDB(dst, b, h) do { _Pragma("unroll") for (int n = 0; n < 2; ++n) _Pragma("unroll") for (int k = 0; k < 2; ++k) dst[n][k] = *(const LAS bf16x8*)(lds + PG8_SB(b, h) + boff + n * 2048 + k * 1024); } while (0)
; #define PG8_MMA(ai, bj, At, Bt) do { __builtin_amdgcn_s_setprio(1); _Pragma("unroll") for (int m = 0; m < 4; ++m) _Pragma("unroll") for (int n = 0; n < 2; ++n) _Pragma("unroll") for (int k = 0; k < 2; ++k) \
;         acc[ai][bj][m][n] = __builtin_amdgcn_mfma_f32_16x16x32_bf16(Bt[n][k], At[m][k], acc[ai][bj][m][n], 0, 0, 0); __builtin_amdgcn_s_setprio(0); } while (0)
; #define PG8_WAIT_V(n) asm volatile("s_waitcnt vmcnt(" #n ")" ::: "memory")
; #define PG8_WAIT_L(n) asm volatile("s_waitcnt lgkmcnt(" #n ")" ::: "memory")
; #define PG8_BAR __builtin_amdgcn_s_barrier()
; #define PG8_SCHED __builtin_amdgcn_sched_barrier(0)
; template <class Epi>
; __device__ __forceinline__ void gemm_phase(LAS unsigned char* lds, const Gemm g, const StaticOrder& S, const Epi& E) {
;     ...
;             PG8_WAIT_V(8); PG8_WAIT_L(0); PG8_BAR; PG8_MMA(1, 0, At, B0); PG8_MMA(1, 1, At, B1); PG8_BAR; PG8_SCHED;
;             PG8_LDB(B0, 1, 0); PG8_LDB(B1, 1, 1); PG8_SCHED; PG8_LDA(At, 1, 0); PG8_STAGE(PG8_SA(0, 1), a2 + hstepA, voffA);
;             PG8_WAIT_V(8); PG8_WAIT_L(0); PG8_BAR; PG8_MMA(0, 0, At, B0); PG8_MMA(0, 1, At, B1); PG8_BAR; PG8_SCHED;
;             PG8_LDA(At, 1, 1); PG8_STAGE(PG8_SB(1, 0), b3, voffB); PG8_STAGE(PG8_SB(1, 1), b3 + hstepB, voffB); PG8_STAGE(PG8_SA(1, 0), a3, voffA);
	s_setprio 1
	s_waitcnt lgkmcnt(0)
	v_mfma_f32_16x16x32_bf16 v[60:63], v[128:131], v[160:163], v[60:63]
	v_mfma_f32_16x16x32_bf16 v[56:59], v[136:139], v[160:163], v[56:59]
	v_mfma_f32_16x16x32_bf16 v[48:51], v[128:131], v[184:187], v[48:51]
	v_mfma_f32_16x16x32_bf16 v[40:43], v[136:139], v[184:187], v[40:43]
	v_mfma_f32_16x16x32_bf16 v[32:35], v[128:131], v[192:195], v[32:35]
	v_mfma_f32_16x16x32_bf16 v[24:27], v[136:139], v[192:195], v[24:27]
	v_mfma_f32_16x16x32_bf16 v[16:19], v[128:131], v[210:213], v[16:19]
	v_mfma_f32_16x16x32_bf16 v[8:11], v[136:139], v[210:213], v[8:11]
	v_mfma_f32_16x16x32_bf16 v[60:63], v[132:135], v[164:167], v[60:63]
	v_mfma_f32_16x16x32_bf16 v[56:59], v[140:143], v[164:167], v[56:59]
	v_mfma_f32_16x16x32_bf16 v[48:51], v[132:135], v[188:191], v[48:51]
	v_mfma_f32_16x16x32_bf16 v[40:43], v[140:143], v[188:191], v[40:43]
	v_mfma_f32_16x16x32_bf16 v[32:35], v[132:135], v[202:205], v[32:35]
	v_mfma_f32_16x16x32_bf16 v[24:27], v[140:143], v[202:205], v[24:27]
	v_mfma_f32_16x16x32_bf16 v[16:19], v[132:135], v[214:217], v[16:19]
	v_mfma_f32_16x16x32_bf16 v[8:11], v[140:143], v[214:217], v[8:11]
	s_setprio 0
	s_setprio 1
	v_mfma_f32_16x16x32_bf16 v[52:55], v[144:147], v[160:163], v[52:55]
	v_mfma_f32_16x16x32_bf16 v[44:47], v[152:155], v[160:163], v[44:47]
	v_mfma_f32_16x16x32_bf16 v[36:39], v[144:147], v[184:187], v[36:39]
	v_mfma_f32_16x16x32_bf16 v[28:31], v[152:155], v[184:187], v[28:31]
	v_mfma_f32_16x16x32_bf16 v[20:23], v[144:147], v[192:195], v[20:23]
	v_mfma_f32_16x16x32_bf16 v[12:15], v[152:155], v[192:195], v[12:15]
	v_mfma_f32_16x16x32_bf16 v[4:7], v[144:147], v[210:213], v[4:7]
	v_mfma_f32_16x16x32_bf16 v[0:3], v[152:155], v[210:213], v[0:3]
	v_mfma_f32_16x16x32_bf16 v[52:55], v[148:151], v[164:167], v[52:55]
	v_mfma_f32_16x16x32_bf16 v[44:47], v[156:159], v[164:167], v[44:47]
	v_mfma_f32_16x16x32_bf16 v[36:39], v[148:151], v[188:191], v[36:39]
	v_mfma_f32_16x16x32_bf16 v[28:31], v[156:159], v[188:191], v[28:31]
	v_mfma_f32_16x16x32_bf16 v[20:23], v[148:151], v[202:205], v[20:23]
	v_mfma_f32_16x16x32_bf16 v[12:15], v[156:159], v[202:205], v[12:15]
	v_mfma_f32_16x16x32_bf16 v[4:7], v[148:151], v[214:217], v[4:7]
	v_mfma_f32_16x16x32_bf16 v[0:3], v[156:159], v[214:217], v[0:3]
	s_setprio 0
	s_barrier
	s_add_i32 s46, 0, 0x18000
	s_add_i32 s47, 0, 0x1c000
	v_add_u32_e32 v140, s46, v197
	v_add_u32_e32 v156, s47, v197
	ds_read_b128 v[128:131], v140
	ds_read_b128 v[132:135], v140 offset:1024
	ds_read_b128 v[136:139], v140 offset:2048
	ds_read_b128 v[140:143], v140 offset:3072
	ds_read_b128 v[144:147], v156
	ds_read_b128 v[148:151], v156 offset:1024
	ds_read_b128 v[152:155], v156 offset:2048
	ds_read_b128 v[156:159], v156 offset:3072
	s_add_u32 s18, s22, 0x320000
	s_addc_u32 s19, s23, 0
	s_mov_b32 m0, s28
	v_lshl_add_u64 v[224:225], s[18:19], 0, v[168:169]
	ds_read_b128 v[160:163], v201 offset:32768
	ds_read_b128 v[164:167], v201 offset:33792
	ds_read_b128 v[184:187], v201 offset:34816
	ds_read_b128 v[188:191], v201 offset:35840
	ds_read_b128 v[192:195], v201 offset:36864
	ds_read_b128 v[202:205], v201 offset:37888
	ds_read_b128 v[210:213], v201 offset:38912
	ds_read_b128 v[214:217], v201 offset:39936
	global_load_lds_dwordx4 v[224:225], off
	v_lshl_add_u64 v[224:225], s[18:19], 0, v[172:173]
	s_mov_b32 m0, s29
	s_nop 0
	global_load_lds_dwordx4 v[224:225], off
	s_waitcnt vmcnt(8)
	s_waitcnt lgkmcnt(0)
	s_barrier
	s_setprio 1
	s_waitcnt lgkmcnt(0)
	v_mfma_f32_16x16x32_bf16 v[124:127], v[128:131], v[160:163], v[124:127]
	v_mfma_f32_16x16x32_bf16 v[120:123], v[136:139], v[160:163], v[120:123]
	v_mfma_f32_16x16x32_bf16 v[112:115], v[128:131], v[184:187], v[112:115]
	v_mfma_f32_16x16x32_bf16 v[104:107], v[136:139], v[184:187], v[104:107]
	v_mfma_f32_16x16x32_bf16 v[96:99], v[128:131], v[192:195], v[96:99]
	v_mfma_f32_16x16x32_bf16 v[88:91], v[136:139], v[192:195], v[88:91]
	v_mfma_f32_16x16x32_bf16 v[80:83], v[128:131], v[210:213], v[80:83]
	v_mfma_f32_16x16x32_bf16 v[72:75], v[136:139], v[210:213], v[72:75]
	v_mfma_f32_16x16x32_bf16 v[124:127], v[132:135], v[164:167], v[124:127]
	v_mfma_f32_16x16x32_bf16 v[120:123], v[140:143], v[164:167], v[120:123]
	v_mfma_f32_16x16x32_bf16 v[112:115], v[132:135], v[188:191], v[112:115]
	v_mfma_f32_16x16x32_bf16 v[104:107], v[140:143], v[188:191], v[104:107]
	v_mfma_f32_16x16x32_bf16 v[96:99], v[132:135], v[202:205], v[96:99]
	v_mfma_f32_16x16x32_bf16 v[88:91], v[140:143], v[202:205], v[88:91]
	v_mfma_f32_16x16x32_bf16 v[80:83], v[132:135], v[214:217], v[80:83]
	v_mfma_f32_16x16x32_bf16 v[72:75], v[140:143], v[214:217], v[72:75]
	s_setprio 0
	s_setprio 1
	v_mfma_f32_16x16x32_bf16 v[116:119], v[144:147], v[160:163], v[116:119]
	v_mfma_f32_16x16x32_bf16 v[108:111], v[152:155], v[160:163], v[108:111]
	v_mfma_f32_16x16x32_bf16 v[100:103], v[144:147], v[184:187], v[100:103]
	v_mfma_f32_16x16x32_bf16 v[92:95], v[152:155], v[184:187], v[92:95]
	v_mfma_f32_16x16x32_bf16 v[84:87], v[144:147], v[192:195], v[84:87]
	v_mfma_f32_16x16x32_bf16 v[76:79], v[152:155], v[192:195], v[76:79]
	v_mfma_f32_16x16x32_bf16 v[68:71], v[144:147], v[210:213], v[68:71]
	v_mfma_f32_16x16x32_bf16 v[64:67], v[152:155], v[210:213], v[64:67]
	v_mfma_f32_16x16x32_bf16 v[116:119], v[148:151], v[164:167], v[116:119]
	v_mfma_f32_16x16x32_bf16 v[108:111], v[156:159], v[164:167], v[108:111]
	v_mfma_f32_16x16x32_bf16 v[100:103], v[148:151], v[188:191], v[100:103]
	v_mfma_f32_16x16x32_bf16 v[92:95], v[156:159], v[188:191], v[92:95]
	v_mfma_f32_16x16x32_bf16 v[84:87], v[148:151], v[202:205], v[84:87]
	v_mfma_f32_16x16x32_bf16 v[76:79], v[156:159], v[202:205], v[76:79]
	v_mfma_f32_16x16x32_bf16 v[68:71], v[148:151], v[214:217], v[68:71]
	v_mfma_f32_16x16x32_bf16 v[64:67], v[156:159], v[214:217], v[64:67]
	s_setprio 0
	s_barrier
; #define PG8_STAGE(bufoff, gbase, voff) do { _Pragma("unroll") for (int _i = 0; _i < 2; ++_i) \
;         __builtin_amdgcn_global_load_lds((const unsigned*)((const char*)(gbase) + (voff)[_i]), (LAS unsigned*)(lds + (bufoff) + ldsw + _i * 8192), 16, 0, 0); } while (0)
; #define PG8_LDA(dst, b, h) do { _Pragma("unroll") for (int m = 0; m < 4; ++m) _Pragma("unroll") for (int k = 0; k < 2; ++k) dst[m][k] = *(const LAS bf16x8*)(lds + PG8_SA(b, h) + aoff + m * 2048 + k * 1024); } while (0)
; #define PG8_MMA(ai, bj, At, Bt) do { __builtin_amdgcn_s_setprio(1); _Pragma("unroll") for (int m = 0; m < 4; ++m) _Pragma("unroll") for (int n = 0; n < 2; ++n) _Pragma("unroll") for (int k = 0; k < 2; ++k) \
;         acc[ai][bj][m][n] = __builtin_amdgcn_mfma_f32_16x16x32_bf16(Bt[n][k], At[m][k], acc[ai][bj][m][n], 0, 0, 0); __builtin_amdgcn_s_setprio(0); } while (0)
; #define PG8_WAIT_V(n) asm volatile("s_waitcnt vmcnt(" #n ")" ::: "memory")
; #define PG8_WAIT_L(n) asm volatile("s_waitcnt lgkmcnt(" #n ")" ::: "memory")
; #define PG8_BAR __builtin_amdgcn_s_barrier()
; #define PG8_SCHED __builtin_amdgcn_sched_barrier(0)
; template <class Epi>
; __device__ __forceinline__ void gemm_phase(LAS unsigned char* lds, const Gemm g, const StaticOrder& S, const Epi& E) {
;     ...
;             PG8_LDA(At, 1, 1); PG8_STAGE(PG8_SB(1, 0), b3, voffB); PG8_STAGE(PG8_SB(1, 1), b3 + hstepB, voffB); PG8_STAGE(PG8_SA(1, 0), a3, voffA);
;             PG8_WAIT_V(8); PG8_WAIT_L(0); PG8_BAR; PG8_MMA(1, 0, At, B0); PG8_MMA(1, 1, At, B1); PG8_BAR; PG8_SCHED;
;         }
;         if (wr == 0) PG8_BAR;
	s_add_i32 s18, s46, s25
	v_lshl_add_u64 v[206:207], v[206:207], 0, s[2:3]
	s_mov_b32 m0, s18
	ds_read_b128 v[160:163], v201 offset:49152
	ds_read_b128 v[164:167], v201 offset:50176
	ds_read_b128 v[184:187], v201 offset:51200
	ds_read_b128 v[188:191], v201 offset:52224
	ds_read_b128 v[192:195], v201 offset:53248
	ds_read_b128 v[202:205], v201 offset:54272
	ds_read_b128 v[210:213], v201 offset:55296
	ds_read_b128 v[214:217], v201 offset:56320
	global_load_lds_dwordx4 v[206:207], off
	s_add_i32 m0, s18, 0x2000
	s_add_u32 s18, s20, 0x20080
	v_lshl_add_u64 v[206:207], v[218:219], 0, s[2:3]
	s_addc_u32 s19, s21, 0
	s_add_i32 s20, s47, s25
	global_load_lds_dwordx4 v[206:207], off
	v_lshl_add_u64 v[206:207], s[18:19], 0, v[170:171]
	s_mov_b32 m0, s20
	s_nop 0
	global_load_lds_dwordx4 v[206:207], off
	v_lshl_add_u64 v[206:207], s[18:19], 0, v[174:175]
	s_add_i32 m0, s20, 0x2000
	s_nop 0
	global_load_lds_dwordx4 v[206:207], off
	v_lshl_add_u64 v[206:207], v[220:221], 0, s[2:3]
	s_mov_b32 m0, s31
	s_nop 0
	global_load_lds_dwordx4 v[206:207], off
	v_lshl_add_u64 v[206:207], v[222:223], 0, s[2:3]
	s_mov_b32 m0, s33
	s_nop 0
	global_load_lds_dwordx4 v[206:207], off
	s_waitcnt vmcnt(8)
	s_waitcnt lgkmcnt(0)
	s_barrier
	s_setprio 1
	s_waitcnt lgkmcnt(0)
	v_mfma_f32_16x16x32_bf16 v[60:63], v[128:131], v[160:163], v[60:63]
	v_mfma_f32_16x16x32_bf16 v[56:59], v[136:139], v[160:163], v[56:59]
	v_mfma_f32_16x16x32_bf16 v[48:51], v[128:131], v[184:187], v[48:51]
	v_mfma_f32_16x16x32_bf16 v[40:43], v[136:139], v[184:187], v[40:43]
	v_mfma_f32_16x16x32_bf16 v[32:35], v[128:131], v[192:195], v[32:35]
	v_mfma_f32_16x16x32_bf16 v[24:27], v[136:139], v[192:195], v[24:27]
	v_mfma_f32_16x16x32_bf16 v[16:19], v[128:131], v[210:213], v[16:19]
	v_mfma_f32_16x16x32_bf16 v[8:11], v[136:139], v[210:213], v[8:11]
	v_mfma_f32_16x16x32_bf16 v[60:63], v[132:135], v[164:167], v[60:63]
	v_mfma_f32_16x16x32_bf16 v[56:59], v[140:143], v[164:167], v[56:59]
	v_mfma_f32_16x16x32_bf16 v[48:51], v[132:135], v[188:191], v[48:51]
	v_mfma_f32_16x16x32_bf16 v[40:43], v[140:143], v[188:191], v[40:43]
	v_mfma_f32_16x16x32_bf16 v[32:35], v[132:135], v[202:205], v[32:35]
	v_mfma_f32_16x16x32_bf16 v[24:27], v[140:143], v[202:205], v[24:27]
	v_mfma_f32_16x16x32_bf16 v[16:19], v[132:135], v[214:217], v[16:19]
	v_mfma_f32_16x16x32_bf16 v[8:11], v[140:143], v[214:217], v[8:11]
	s_setprio 0
	s_setprio 1
	v_mfma_f32_16x16x32_bf16 v[52:55], v[144:147], v[160:163], v[52:55]
	v_mfma_f32_16x16x32_bf16 v[44:47], v[152:155], v[160:163], v[44:47]
	v_mfma_f32_16x16x32_bf16 v[36:39], v[144:147], v[184:187], v[36:39]
	v_mfma_f32_16x16x32_bf16 v[28:31], v[152:155], v[184:187], v[28:31]
	v_mfma_f32_16x16x32_bf16 v[20:23], v[144:147], v[192:195], v[20:23]
	v_mfma_f32_16x16x32_bf16 v[12:15], v[152:155], v[192:195], v[12:15]
	v_mfma_f32_16x16x32_bf16 v[4:7], v[144:147], v[210:213], v[4:7]
	v_mfma_f32_16x16x32_bf16 v[0:3], v[152:155], v[210:213], v[0:3]
	v_mfma_f32_16x16x32_bf16 v[52:55], v[148:151], v[164:167], v[52:55]
	v_mfma_f32_16x16x32_bf16 v[44:47], v[156:159], v[164:167], v[44:47]
	v_mfma_f32_16x16x32_bf16 v[36:39], v[148:151], v[188:191], v[36:39]
	v_mfma_f32_16x16x32_bf16 v[28:31], v[156:159], v[188:191], v[28:31]
	v_mfma_f32_16x16x32_bf16 v[20:23], v[148:151], v[202:205], v[20:23]
	v_mfma_f32_16x16x32_bf16 v[12:15], v[156:159], v[202:205], v[12:15]
	v_mfma_f32_16x16x32_bf16 v[4:7], v[148:151], v[214:217], v[4:7]
	v_mfma_f32_16x16x32_bf16 v[0:3], v[156:159], v[214:217], v[0:3]
	s_setprio 0
	s_add_i32 s45, s45, 2
	s_add_u32 s43, s43, 0x100
	s_addc_u32 s44, s44, 0
	s_cmp_gt_u32 s45, 5
	s_mov_b64 s[18:19], s[6:7]
	s_barrier
	s_cbranch_scc0 .LBB0_1460
	s_and_b64 vcc, exec, s[8:9]
	s_cbranch_vccz .LBB0_1463
	s_barrier

; #define PG8_STAGE(bufoff, gbase, voff) do { _Pragma("unroll") for (int _i = 0; _i < 2; ++_i) \
;         __builtin_amdgcn_global_load_lds((const unsigned*)((const char*)(gbase) + (voff)[_i]), (LAS unsigned*)(lds + (bufoff) + ldsw + _i * 8192), 16, 0, 0); } while (0)
; #define PG8_LDA(dst, b, h) do { _Pragma("unroll") for (int m = 0; m < 4; ++m) _Pragma("unroll") for (int k = 0; k < 2; ++k) dst[m][k] = *(const LAS bf16x8*)(lds + PG8_SA(b, h) + aoff + m * 2048 + k * 1024); } while (0)
; #define PG8_LDB(dst, b, h) do { _Pragma("unroll") for (int n = 0; n < 2; ++n) _Pragma("unroll") for (int k = 0; k < 2; ++k) dst[n][k] = *(const LAS bf16x8*)(lds + PG8_SB(b, h) + boff + n * 2048 + k * 1024); } while (0)
; #define PG8_MMA(ai, bj, At, Bt) do { __builtin_amdgcn_s_setprio(1); _Pragma("unroll") for (int m = 0; m < 4; ++m) _Pragma("unroll") for (int n = 0; n < 2; ++n) _Pragma("unroll") for (int k = 0; k < 2; ++k) \
;         acc[ai][bj][m][n] = __builtin_amdgcn_mfma_f32_16x16x32_bf16(Bt[n][k], At[m][k], acc[ai][bj][m][n], 0, 0, 0); __builtin_amdgcn_s_setprio(0); } while (0)
; #define PG8_WAIT_V(n) asm volatile("s_waitcnt vmcnt(" #n ")" ::: "memory")
; #define PG8_WAIT_L(n) asm volatile("s_waitcnt lgkmcnt(" #n ")" ::: "memory")
; #define PG8_BAR __builtin_amdgcn_s_barrier()
; #define PG8_SCHED __builtin_amdgcn_sched_barrier(0)
; template <class Epi>
; __device__ __forceinline__ void gemm_phase(LAS unsigned char* lds, const Gemm g, const StaticOrder& S, const Epi& E) {
;     ...
;         for (int t = 0; t < nt; t += 2) {
;             const bool last = (t == nt - 2);
;             const char* a1 = cA + (size_t)(t + 1) * kstepA;
;             const char* a2 = last ? nA : cA + (size_t)(t + 2) * kstepA; const char* b2 = last ? nB : cB + (size_t)(t + 2) * kstep;
;             const char* a3 = a2 + kstepA; const char* b3 = b2 + kstep;
;             PG8_LDB(B0, 0, 0); PG8_LDB(B1, 0, 1); PG8_SCHED; PG8_LDA(At, 0, 0); PG8_STAGE(PG8_SA(1, 1), a1 + hstepA, voffA);
;             PG8_WAIT_V(8); PG8_WAIT_L(0); PG8_BAR; PG8_MMA(0, 0, At, B0); PG8_MMA(0, 1, At, B1); PG8_BAR; PG8_SCHED;
;             PG8_LDA(At, 0, 1); PG8_STAGE(PG8_SB(0, 0), b2, voffB); PG8_STAGE(PG8_SB(0, 1), b2 + hstepB, voffB); PG8_STAGE(PG8_SA(0, 0), a2, voffA);
.LBB0_1503:
	ds_read_b128 v[144:147], v155
	ds_read_b128 v[148:151], v155 offset:1024
	ds_read_b128 v[158:161], v155 offset:2048
	ds_read_b128 v[162:165], v155 offset:3072
	ds_read_b128 v[166:169], v156
	ds_read_b128 v[170:173], v156 offset:1024
	ds_read_b128 v[174:177], v156 offset:2048
	ds_read_b128 v[178:181], v156 offset:3072
	s_add_u32 s8, s20, 0x100
	s_addc_u32 s9, s21, 0
	s_cmp_eq_u32 s50, 28
	s_cselect_b32 s25, s17, s9
	s_cselect_b32 s24, s16, s8
	s_cselect_b32 s23, s15, s49
	s_cselect_b32 s22, s47, s48
	v_lshl_add_u64 v[206:207], s[20:21], 0, v[136:137]
	s_add_i32 m0, s30, 0xc000
	ds_read_b128 v[182:185], v157
	ds_read_b128 v[186:189], v157 offset:1024
	ds_read_b128 v[190:193], v157 offset:2048
	ds_read_b128 v[194:197], v157 offset:3072
	ds_read_b128 v[198:201], v157 offset:4096
	ds_read_b128 v[202:205], v157 offset:5120
	ds_read_b128 v[210:213], v157 offset:6144
	ds_read_b128 v[214:217], v157 offset:7168
	global_load_lds_dwordx4 v[206:207], off
	v_lshl_add_u64 v[206:207], s[20:21], 0, v[138:139]
	s_add_i32 m0, s30, 0xe000
	s_nop 0
	global_load_lds_dwordx4 v[206:207], off
	s_waitcnt vmcnt(8)
	s_waitcnt lgkmcnt(0)
	s_barrier
	s_setprio 1
	s_waitcnt lgkmcnt(0)
	v_mfma_f32_16x16x32_bf16 v[124:127], v[144:147], v[182:185], v[124:127]
	v_mfma_f32_16x16x32_bf16 v[120:123], v[158:161], v[182:185], v[120:123]
	v_mfma_f32_16x16x32_bf16 v[108:111], v[144:147], v[190:193], v[108:111]
	v_mfma_f32_16x16x32_bf16 v[104:107], v[158:161], v[190:193], v[104:107]
	v_mfma_f32_16x16x32_bf16 v[92:95], v[144:147], v[198:201], v[92:95]
	v_mfma_f32_16x16x32_bf16 v[88:91], v[158:161], v[198:201], v[88:91]
	v_mfma_f32_16x16x32_bf16 v[76:79], v[144:147], v[210:213], v[76:79]
	v_mfma_f32_16x16x32_bf16 v[72:75], v[158:161], v[210:213], v[72:75]
	v_mfma_f32_16x16x32_bf16 v[124:127], v[148:151], v[186:189], v[124:127]
	v_mfma_f32_16x16x32_bf16 v[120:123], v[162:165], v[186:189], v[120:123]
	v_mfma_f32_16x16x32_bf16 v[108:111], v[148:151], v[194:197], v[108:111]
	v_mfma_f32_16x16x32_bf16 v[104:107], v[162:165], v[194:197], v[104:107]
	v_mfma_f32_16x16x32_bf16 v[92:95], v[148:151], v[202:205], v[92:95]
	v_mfma_f32_16x16x32_bf16 v[88:91], v[162:165], v[202:205], v[88:91]
	v_mfma_f32_16x16x32_bf16 v[76:79], v[148:151], v[214:217], v[76:79]
	v_mfma_f32_16x16x32_bf16 v[72:75], v[162:165], v[214:217], v[72:75]
	s_setprio 0
	s_setprio 1
	v_mfma_f32_16x16x32_bf16 v[116:119], v[166:169], v[182:185], v[116:119]
	v_mfma_f32_16x16x32_bf16 v[112:115], v[174:177], v[182:185], v[112:115]
	v_mfma_f32_16x16x32_bf16 v[100:103], v[166:169], v[190:193], v[100:103]
	v_mfma_f32_16x16x32_bf16 v[96:99], v[174:177], v[190:193], v[96:99]
	v_mfma_f32_16x16x32_bf16 v[84:87], v[166:169], v[198:201], v[84:87]
	v_mfma_f32_16x16x32_bf16 v[80:83], v[174:177], v[198:201], v[80:83]
	v_mfma_f32_16x16x32_bf16 v[68:71], v[166:169], v[210:213], v[68:71]
	v_mfma_f32_16x16x32_bf16 v[64:67], v[174:177], v[210:213], v[64:67]
	v_mfma_f32_16x16x32_bf16 v[116:119], v[170:173], v[186:189], v[116:119]
	v_mfma_f32_16x16x32_bf16 v[112:115], v[178:181], v[186:189], v[112:115]
	v_mfma_f32_16x16x32_bf16 v[100:103], v[170:173], v[194:197], v[100:103]
	v_mfma_f32_16x16x32_bf16 v[96:99], v[178:181], v[194:197], v[96:99]
	v_mfma_f32_16x16x32_bf16 v[84:87], v[170:173], v[202:205], v[84:87]
	v_mfma_f32_16x16x32_bf16 v[80:83], v[178:181], v[202:205], v[80:83]
	v_mfma_f32_16x16x32_bf16 v[68:71], v[170:173], v[214:217], v[68:71]
	v_mfma_f32_16x16x32_bf16 v[64:67], v[178:181], v[214:217], v[64:67]
	s_setprio 0
	s_barrier
	s_add_i32 s20, s40, s29
	v_lshl_add_u64 v[206:207], s[22:23], 0, v[130:131]
	s_mov_b32 m0, s20
	ds_read_b128 v[182:185], v157 offset:16384
	ds_read_b128 v[186:189], v157 offset:17408
	ds_read_b128 v[190:193], v157 offset:18432
	ds_read_b128 v[194:197], v157 offset:19456
	ds_read_b128 v[198:201], v157 offset:20480
	ds_read_b128 v[202:205], v157 offset:21504
	ds_read_b128 v[210:213], v157 offset:22528
	ds_read_b128 v[214:217], v157 offset:23552
	global_load_lds_dwordx4 v[206:207], off
	s_add_i32 m0, s20, 0x2000
	s_add_u32 s20, s22, 0x80000
	v_lshl_add_u64 v[218:219], s[22:23], 0, v[134:135]
	s_addc_u32 s21, s23, 0
	s_add_i32 s51, s41, s29
	global_load_lds_dwordx4 v[218:219], off
	v_lshl_add_u64 v[220:221], s[20:21], 0, v[130:131]
	s_mov_b32 m0, s51
	v_lshl_add_u64 v[222:223], s[24:25], 0, v[132:133]
	global_load_lds_dwordx4 v[220:221], off
	v_lshl_add_u64 v[220:221], s[20:21], 0, v[134:135]
	s_add_i32 m0, s51, 0x2000
	s_nop 0
	global_load_lds_dwordx4 v[220:221], off
	v_lshl_add_u64 v[220:221], s[24:25], 0, v[128:129]
	s_mov_b32 m0, s30
	s_nop 0
	global_load_lds_dwordx4 v[220:221], off
	s_mov_b32 m0, s31
	s_nop 0
	global_load_lds_dwordx4 v[222:223], off
	s_waitcnt vmcnt(8)
	s_waitcnt lgkmcnt(0)
	s_barrier
; #define PG8_STAGE(bufoff, gbase, voff) do { _Pragma("unroll") for (int _i = 0; _i < 2; ++_i) \
;         __builtin_amdgcn_global_load_lds((const unsigned*)((const char*)(gbase) + (voff)[_i]), (LAS unsigned*)(lds + (bufoff) + ldsw + _i * 8192), 16, 0, 0); } while (0)
; #define PG8_LDA(dst, b, h) do { _Pragma("unroll") for (int m = 0; m < 4; ++m) _Pragma("unroll") for (int k = 0; k < 2; ++k) dst[m][k] = *(const LAS bf16x8*)(lds + PG8_SA(b, h) + aoff + m * 2048 + k * 1024); } while (0)
; #define PG8_LDB(dst, b, h) do { _Pragma("unroll") for (int n = 0; n < 2; ++n) _Pragma("unroll") for (int k = 0; k < 2; ++k) dst[n][k] = *(const LAS bf16x8*)(lds + PG8_SB(b, h) + boff + n * 2048 + k * 1024); } while (0)
; #define PG8_MMA(ai, bj, At, Bt) do { __builtin_amdgcn_s_setprio(1); _Pragma("unroll") for (int m = 0; m < 4; ++m) _Pragma("unroll") for (int n = 0; n < 2; ++n) _Pragma("unroll") for (int k = 0; k < 2; ++k) \
;         acc[ai][bj][m][n] = __builtin_amdgcn_mfma_f32_16x16x32_bf16(Bt[n][k], At[m][k], acc[ai][bj][m][n], 0, 0, 0); __builtin_amdgcn_s_setprio(0); } while (0)
; #define PG8_WAIT_V(n) asm volatile("s_waitcnt vmcnt(" #n ")" ::: "memory")
; #define PG8_WAIT_L(n) asm volatile("s_waitcnt lgkmcnt(" #n ")" ::: "memory")
; #define PG8_BAR __builtin_amdgcn_s_barrier()
; #define PG8_SCHED __builtin_amdgcn_sched_barrier(0)
; template <class Epi>
; __device__ __forceinline__ void gemm_phase(LAS unsigned char* lds, const Gemm g, const StaticOrder& S, const Epi& E) {
;     ...
;             PG8_WAIT_V(8); PG8_WAIT_L(0); PG8_BAR; PG8_MMA(1, 0, At, B0); PG8_MMA(1, 1, At, B1); PG8_BAR; PG8_SCHED;
;             PG8_LDB(B0, 1, 0); PG8_LDB(B1, 1, 1); PG8_SCHED; PG8_LDA(At, 1, 0); PG8_STAGE(PG8_SA(0, 1), a2 + hstepA, voffA);
;             PG8_WAIT_V(8); PG8_WAIT_L(0); PG8_BAR; PG8_MMA(0, 0, At, B0); PG8_MMA(0, 1, At, B1); PG8_BAR; PG8_SCHED;
;             PG8_LDA(At, 1, 1); PG8_STAGE(PG8_SB(1, 0), b3, voffB); PG8_STAGE(PG8_SB(1, 1), b3 + hstepB, voffB); PG8_STAGE(PG8_SA(1, 0), a3, voffA);
	s_setprio 1
	s_waitcnt lgkmcnt(0)
	v_mfma_f32_16x16x32_bf16 v[60:63], v[144:147], v[182:185], v[60:63]
	v_mfma_f32_16x16x32_bf16 v[56:59], v[158:161], v[182:185], v[56:59]
	v_mfma_f32_16x16x32_bf16 v[44:47], v[144:147], v[190:193], v[44:47]
	v_mfma_f32_16x16x32_bf16 v[40:43], v[158:161], v[190:193], v[40:43]
	v_mfma_f32_16x16x32_bf16 v[28:31], v[144:147], v[198:201], v[28:31]
	v_mfma_f32_16x16x32_bf16 v[24:27], v[158:161], v[198:201], v[24:27]
	v_mfma_f32_16x16x32_bf16 v[12:15], v[144:147], v[210:213], v[12:15]
	v_mfma_f32_16x16x32_bf16 v[8:11], v[158:161], v[210:213], v[8:11]
	v_mfma_f32_16x16x32_bf16 v[60:63], v[148:151], v[186:189], v[60:63]
	v_mfma_f32_16x16x32_bf16 v[56:59], v[162:165], v[186:189], v[56:59]
	v_mfma_f32_16x16x32_bf16 v[44:47], v[148:151], v[194:197], v[44:47]
	v_mfma_f32_16x16x32_bf16 v[40:43], v[162:165], v[194:197], v[40:43]
	v_mfma_f32_16x16x32_bf16 v[28:31], v[148:151], v[202:205], v[28:31]
	v_mfma_f32_16x16x32_bf16 v[24:27], v[162:165], v[202:205], v[24:27]
	v_mfma_f32_16x16x32_bf16 v[12:15], v[148:151], v[214:217], v[12:15]
	v_mfma_f32_16x16x32_bf16 v[8:11], v[162:165], v[214:217], v[8:11]
	s_setprio 0
	s_setprio 1
	v_mfma_f32_16x16x32_bf16 v[52:55], v[166:169], v[182:185], v[52:55]
	v_mfma_f32_16x16x32_bf16 v[48:51], v[174:177], v[182:185], v[48:51]
	v_mfma_f32_16x16x32_bf16 v[36:39], v[166:169], v[190:193], v[36:39]
	v_mfma_f32_16x16x32_bf16 v[32:35], v[174:177], v[190:193], v[32:35]
	v_mfma_f32_16x16x32_bf16 v[20:23], v[166:169], v[198:201], v[20:23]
	v_mfma_f32_16x16x32_bf16 v[16:19], v[174:177], v[198:201], v[16:19]
	v_mfma_f32_16x16x32_bf16 v[4:7], v[166:169], v[210:213], v[4:7]
	v_mfma_f32_16x16x32_bf16 v[0:3], v[174:177], v[210:213], v[0:3]
	v_mfma_f32_16x16x32_bf16 v[52:55], v[170:173], v[186:189], v[52:55]
	v_mfma_f32_16x16x32_bf16 v[48:51], v[178:181], v[186:189], v[48:51]
	v_mfma_f32_16x16x32_bf16 v[36:39], v[170:173], v[194:197], v[36:39]
	v_mfma_f32_16x16x32_bf16 v[32:35], v[178:181], v[194:197], v[32:35]
	v_mfma_f32_16x16x32_bf16 v[20:23], v[170:173], v[202:205], v[20:23]
	v_mfma_f32_16x16x32_bf16 v[16:19], v[178:181], v[202:205], v[16:19]
	v_mfma_f32_16x16x32_bf16 v[4:7], v[170:173], v[214:217], v[4:7]
	v_mfma_f32_16x16x32_bf16 v[0:3], v[178:181], v[214:217], v[0:3]
	s_setprio 0
	s_barrier
	s_add_i32 s51, 0, 0x18000
	s_add_i32 s52, 0, 0x1c000
	v_add_u32_e32 v162, s51, v153
	v_add_u32_e32 v178, s52, v153
	ds_read_b128 v[144:147], v162
	ds_read_b128 v[148:151], v162 offset:1024
	ds_read_b128 v[158:161], v162 offset:2048
	ds_read_b128 v[162:165], v162 offset:3072
	ds_read_b128 v[166:169], v178
	ds_read_b128 v[170:173], v178 offset:1024
	ds_read_b128 v[174:177], v178 offset:2048
	ds_read_b128 v[178:181], v178 offset:3072
	s_add_u32 s20, s24, 0x320000
	s_addc_u32 s21, s25, 0
	s_mov_b32 m0, s33
	v_lshl_add_u64 v[224:225], s[20:21], 0, v[128:129]
	ds_read_b128 v[182:185], v157 offset:32768
	ds_read_b128 v[186:189], v157 offset:33792
	ds_read_b128 v[190:193], v157 offset:34816
	ds_read_b128 v[194:197], v157 offset:35840
	ds_read_b128 v[198:201], v157 offset:36864
	ds_read_b128 v[202:205], v157 offset:37888
	ds_read_b128 v[210:213], v157 offset:38912
	ds_read_b128 v[214:217], v157 offset:39936
	global_load_lds_dwordx4 v[224:225], off
	v_lshl_add_u64 v[224:225], s[20:21], 0, v[132:133]
	s_mov_b32 m0, s34
	s_nop 0
	global_load_lds_dwordx4 v[224:225], off
	s_waitcnt vmcnt(8)
	s_waitcnt lgkmcnt(0)
	s_barrier
	s_setprio 1
	s_waitcnt lgkmcnt(0)
	v_mfma_f32_16x16x32_bf16 v[124:127], v[144:147], v[182:185], v[124:127]
	v_mfma_f32_16x16x32_bf16 v[120:123], v[158:161], v[182:185], v[120:123]
	v_mfma_f32_16x16x32_bf16 v[108:111], v[144:147], v[190:193], v[108:111]
	v_mfma_f32_16x16x32_bf16 v[104:107], v[158:161], v[190:193], v[104:107]
	v_mfma_f32_16x16x32_bf16 v[92:95], v[144:147], v[198:201], v[92:95]
	v_mfma_f32_16x16x32_bf16 v[88:91], v[158:161], v[198:201], v[88:91]
	v_mfma_f32_16x16x32_bf16 v[76:79], v[144:147], v[210:213], v[76:79]
	v_mfma_f32_16x16x32_bf16 v[72:75], v[158:161], v[210:213], v[72:75]
	v_mfma_f32_16x16x32_bf16 v[124:127], v[148:151], v[186:189], v[124:127]
	v_mfma_f32_16x16x32_bf16 v[120:123], v[162:165], v[186:189], v[120:123]
	v_mfma_f32_16x16x32_bf16 v[108:111], v[148:151], v[194:197], v[108:111]
	v_mfma_f32_16x16x32_bf16 v[104:107], v[162:165], v[194:197], v[104:107]
	v_mfma_f32_16x16x32_bf16 v[92:95], v[148:151], v[202:205], v[92:95]
	v_mfma_f32_16x16x32_bf16 v[88:91], v[162:165], v[202:205], v[88:91]
	v_mfma_f32_16x16x32_bf16 v[76:79], v[148:151], v[214:217], v[76:79]
	v_mfma_f32_16x16x32_bf16 v[72:75], v[162:165], v[214:217], v[72:75]
	s_setprio 0
	s_setprio 1
	v_mfma_f32_16x16x32_bf16 v[116:119], v[166:169], v[182:185], v[116:119]
	v_mfma_f32_16x16x32_bf16 v[112:115], v[174:177], v[182:185], v[112:115]
	v_mfma_f32_16x16x32_bf16 v[100:103], v[166:169], v[190:193], v[100:103]
	v_mfma_f32_16x16x32_bf16 v[96:99], v[174:177], v[190:193], v[96:99]
	v_mfma_f32_16x16x32_bf16 v[84:87], v[166:169], v[198:201], v[84:87]
	v_mfma_f32_16x16x32_bf16 v[80:83], v[174:177], v[198:201], v[80:83]
	v_mfma_f32_16x16x32_bf16 v[68:71], v[166:169], v[210:213], v[68:71]
	v_mfma_f32_16x16x32_bf16 v[64:67], v[174:177], v[210:213], v[64:67]
	v_mfma_f32_16x16x32_bf16 v[116:119], v[170:173], v[186:189], v[116:119]
	v_mfma_f32_16x16x32_bf16 v[112:115], v[178:181], v[186:189], v[112:115]
	v_mfma_f32_16x16x32_bf16 v[100:103], v[170:173], v[194:197], v[100:103]
	v_mfma_f32_16x16x32_bf16 v[96:99], v[178:181], v[194:197], v[96:99]
	v_mfma_f32_16x16x32_bf16 v[84:87], v[170:173], v[202:205], v[84:87]
	v_mfma_f32_16x16x32_bf16 v[80:83], v[178:181], v[202:205], v[80:83]
	v_mfma_f32_16x16x32_bf16 v[68:71], v[170:173], v[214:217], v[68:71]
	v_mfma_f32_16x16x32_bf16 v[64:67], v[178:181], v[214:217], v[64:67]
	s_setprio 0
	s_barrier
; #define PG8_STAGE(bufoff, gbase, voff) do { _Pragma("unroll") for (int _i = 0; _i < 2; ++_i) \
;         __builtin_amdgcn_global_load_lds((const unsigned*)((const char*)(gbase) + (voff)[_i]), (LAS unsigned*)(lds + (bufoff) + ldsw + _i * 8192), 16, 0, 0); } while (0)
; #define PG8_LDA(dst, b, h) do { _Pragma("unroll") for (int m = 0; m < 4; ++m) _Pragma("unroll") for (int k = 0; k < 2; ++k) dst[m][k] = *(const LAS bf16x8*)(lds + PG8_SA(b, h) + aoff + m * 2048 + k * 1024); } while (0)
; #define PG8_MMA(ai, bj, At, Bt) do { __builtin_amdgcn_s_setprio(1); _Pragma("unroll") for (int m = 0; m < 4; ++m) _Pragma("unroll") for (int n = 0; n < 2; ++n) _Pragma("unroll") for (int k = 0; k < 2; ++k) \
;         acc[ai][bj][m][n] = __builtin_amdgcn_mfma_f32_16x16x32_bf16(Bt[n][k], At[m][k], acc[ai][bj][m][n], 0, 0, 0); __builtin_amdgcn_s_setprio(0); } while (0)
; #define PG8_WAIT_V(n) asm volatile("s_waitcnt vmcnt(" #n ")" ::: "memory")
; #define PG8_WAIT_L(n) asm volatile("s_waitcnt lgkmcnt(" #n ")" ::: "memory")
; #define PG8_BAR __builtin_amdgcn_s_barrier()
; #define PG8_SCHED __builtin_amdgcn_sched_barrier(0)
; template <class Epi>
; __device__ __forceinline__ void gemm_phase(LAS unsigned char* lds, const Gemm g, const StaticOrder& S, const Epi& E) {
;     ...
;             PG8_LDA(At, 1, 1); PG8_STAGE(PG8_SB(1, 0), b3, voffB); PG8_STAGE(PG8_SB(1, 1), b3 + hstepB, voffB); PG8_STAGE(PG8_SA(1, 0), a3, voffA);
;             PG8_WAIT_V(8); PG8_WAIT_L(0); PG8_BAR; PG8_MMA(1, 0, At, B0); PG8_MMA(1, 1, At, B1); PG8_BAR; PG8_SCHED;
;         }
;         if (wr == 0) PG8_BAR;
	s_add_i32 s20, s51, s29
	v_lshl_add_u64 v[206:207], v[206:207], 0, s[2:3]
	s_mov_b32 m0, s20
	ds_read_b128 v[182:185], v157 offset:49152
	ds_read_b128 v[186:189], v157 offset:50176
	ds_read_b128 v[190:193], v157 offset:51200
	ds_read_b128 v[194:197], v157 offset:52224
	ds_read_b128 v[198:201], v157 offset:53248
	ds_read_b128 v[202:205], v157 offset:54272
	ds_read_b128 v[210:213], v157 offset:55296
	ds_read_b128 v[214:217], v157 offset:56320
	global_load_lds_dwordx4 v[206:207], off
	s_add_i32 m0, s20, 0x2000
	s_add_u32 s20, s22, 0x80080
	v_lshl_add_u64 v[206:207], v[218:219], 0, s[2:3]
	s_addc_u32 s21, s23, 0
	s_add_i32 s22, s52, s29
	global_load_lds_dwordx4 v[206:207], off
	v_lshl_add_u64 v[206:207], s[20:21], 0, v[130:131]
	s_mov_b32 m0, s22
	s_nop 0
	global_load_lds_dwordx4 v[206:207], off
	v_lshl_add_u64 v[206:207], s[20:21], 0, v[134:135]
	s_add_i32 m0, s22, 0x2000
	s_nop 0
	global_load_lds_dwordx4 v[206:207], off
	v_lshl_add_u64 v[206:207], v[220:221], 0, s[2:3]
	s_mov_b32 m0, s36
	s_nop 0
	global_load_lds_dwordx4 v[206:207], off
	v_lshl_add_u64 v[206:207], v[222:223], 0, s[2:3]
	s_mov_b32 m0, s37
	s_nop 0
	global_load_lds_dwordx4 v[206:207], off
	s_waitcnt vmcnt(8)
	s_waitcnt lgkmcnt(0)
	s_barrier
	s_setprio 1
	s_waitcnt lgkmcnt(0)
	v_mfma_f32_16x16x32_bf16 v[60:63], v[144:147], v[182:185], v[60:63]
	v_mfma_f32_16x16x32_bf16 v[56:59], v[158:161], v[182:185], v[56:59]
	v_mfma_f32_16x16x32_bf16 v[44:47], v[144:147], v[190:193], v[44:47]
	v_mfma_f32_16x16x32_bf16 v[40:43], v[158:161], v[190:193], v[40:43]
	v_mfma_f32_16x16x32_bf16 v[28:31], v[144:147], v[198:201], v[28:31]
	v_mfma_f32_16x16x32_bf16 v[24:27], v[158:161], v[198:201], v[24:27]
	v_mfma_f32_16x16x32_bf16 v[12:15], v[144:147], v[210:213], v[12:15]
	v_mfma_f32_16x16x32_bf16 v[8:11], v[158:161], v[210:213], v[8:11]
	v_mfma_f32_16x16x32_bf16 v[60:63], v[148:151], v[186:189], v[60:63]
	v_mfma_f32_16x16x32_bf16 v[56:59], v[162:165], v[186:189], v[56:59]
	v_mfma_f32_16x16x32_bf16 v[44:47], v[148:151], v[194:197], v[44:47]
	v_mfma_f32_16x16x32_bf16 v[40:43], v[162:165], v[194:197], v[40:43]
	v_mfma_f32_16x16x32_bf16 v[28:31], v[148:151], v[202:205], v[28:31]
	v_mfma_f32_16x16x32_bf16 v[24:27], v[162:165], v[202:205], v[24:27]
	v_mfma_f32_16x16x32_bf16 v[12:15], v[148:151], v[214:217], v[12:15]
	v_mfma_f32_16x16x32_bf16 v[8:11], v[162:165], v[214:217], v[8:11]
	s_setprio 0
	s_setprio 1
	v_mfma_f32_16x16x32_bf16 v[52:55], v[166:169], v[182:185], v[52:55]
	v_mfma_f32_16x16x32_bf16 v[48:51], v[174:177], v[182:185], v[48:51]
	v_mfma_f32_16x16x32_bf16 v[36:39], v[166:169], v[190:193], v[36:39]
	v_mfma_f32_16x16x32_bf16 v[32:35], v[174:177], v[190:193], v[32:35]
	v_mfma_f32_16x16x32_bf16 v[20:23], v[166:169], v[198:201], v[20:23]
	v_mfma_f32_16x16x32_bf16 v[16:19], v[174:177], v[198:201], v[16:19]
	v_mfma_f32_16x16x32_bf16 v[4:7], v[166:169], v[210:213], v[4:7]
	v_mfma_f32_16x16x32_bf16 v[0:3], v[174:177], v[210:213], v[0:3]
	v_mfma_f32_16x16x32_bf16 v[52:55], v[170:173], v[186:189], v[52:55]
	v_mfma_f32_16x16x32_bf16 v[48:51], v[178:181], v[186:189], v[48:51]
	v_mfma_f32_16x16x32_bf16 v[36:39], v[170:173], v[194:197], v[36:39]
	v_mfma_f32_16x16x32_bf16 v[32:35], v[178:181], v[194:197], v[32:35]
	v_mfma_f32_16x16x32_bf16 v[20:23], v[170:173], v[202:205], v[20:23]
	v_mfma_f32_16x16x32_bf16 v[16:19], v[178:181], v[202:205], v[16:19]
	v_mfma_f32_16x16x32_bf16 v[4:7], v[170:173], v[214:217], v[4:7]
	v_mfma_f32_16x16x32_bf16 v[0:3], v[178:181], v[214:217], v[0:3]
	s_setprio 0
	s_add_i32 s50, s50, 2
	s_add_u32 s48, s48, 0x100
	s_addc_u32 s49, s49, 0
	s_cmp_gt_u32 s50, 29
	s_mov_b64 s[20:21], s[8:9]
	s_barrier
	s_cbranch_scc0 .LBB0_1503
	s_and_b64 vcc, exec, s[10:11]
	s_cbranch_vccz .LBB0_1506
	s_barrier

; #define PG8_STAGE(bufoff, gbase, voff) do { _Pragma("unroll") for (int _i = 0; _i < 2; ++_i) \
;         __builtin_amdgcn_global_load_lds((const unsigned*)((const char*)(gbase) + (voff)[_i]), (LAS unsigned*)(lds + (bufoff) + ldsw + _i * 8192), 16, 0, 0); } while (0)
; #define PG8_LDA(dst, b, h) do { _Pragma("unroll") for (int m = 0; m < 4; ++m) _Pragma("unroll") for (int k = 0; k < 2; ++k) dst[m][k] = *(const LAS bf16x8*)(lds + PG8_SA(b, h) + aoff + m * 2048 + k * 1024); } while (0)
; #define PG8_LDB(dst, b, h) do { _Pragma("unroll") for (int n = 0; n < 2; ++n) _Pragma("unroll") for (int k = 0; k < 2; ++k) dst[n][k] = *(const LAS bf16x8*)(lds + PG8_SB(b, h) + boff + n * 2048 + k * 1024); } while (0)
; #define PG8_MMA(ai, bj, At, Bt) do { __builtin_amdgcn_s_setprio(1); _Pragma("unroll") for (int m = 0; m < 4; ++m) _Pragma("unroll") for (int n = 0; n < 2; ++n) _Pragma("unroll") for (int k = 0; k < 2; ++k) \
;         acc[ai][bj][m][n] = __builtin_amdgcn_mfma_f32_16x16x32_bf16(Bt[n][k], At[m][k], acc[ai][bj][m][n], 0, 0, 0); __builtin_amdgcn_s_setprio(0); } while (0)
; #define PG8_WAIT_V(n) asm volatile("s_waitcnt vmcnt(" #n ")" ::: "memory")
; #define PG8_WAIT_L(n) asm volatile("s_waitcnt lgkmcnt(" #n ")" ::: "memory")
; #define PG8_BAR __builtin_amdgcn_s_barrier()
; #define PG8_SCHED __builtin_amdgcn_sched_barrier(0)
; template <class Epi>
; __device__ __forceinline__ void gemm_phase(LAS unsigned char* lds, const Gemm g, const StaticOrder& S, const Epi& E) {
;     ...
;         for (int t = 0; t < nt; t += 2) {
;             const bool last = (t == nt - 2);
;             const char* a1 = cA + (size_t)(t + 1) * kstepA;
;             const char* a2 = last ? nA : cA + (size_t)(t + 2) * kstepA; const char* b2 = last ? nB : cB + (size_t)(t + 2) * kstep;
;             const char* a3 = a2 + kstepA; const char* b3 = b2 + kstep;
;             PG8_LDB(B0, 0, 0); PG8_LDB(B1, 0, 1); PG8_SCHED; PG8_LDA(At, 0, 0); PG8_STAGE(PG8_SA(1, 1), a1 + hstepA, voffA);
;             PG8_WAIT_V(8); PG8_WAIT_L(0); PG8_BAR; PG8_MMA(0, 0, At, B0); PG8_MMA(0, 1, At, B1); PG8_BAR; PG8_SCHED;
;             PG8_LDA(At, 0, 1); PG8_STAGE(PG8_SB(0, 0), b2, voffB); PG8_STAGE(PG8_SB(0, 1), b2 + hstepB, voffB); PG8_STAGE(PG8_SA(0, 0), a2, voffA);
.LBB0_1598:
	ds_read_b128 v[128:131], v230
	ds_read_b128 v[132:135], v230 offset:1024
	ds_read_b128 v[136:139], v230 offset:2048
	ds_read_b128 v[140:143], v230 offset:3072
	ds_read_b128 v[144:147], v231
	ds_read_b128 v[148:151], v231 offset:1024
	ds_read_b128 v[152:155], v231 offset:2048
	ds_read_b128 v[156:159], v231 offset:3072
	s_add_u32 s12, s10, 0xfffc0080
	s_addc_u32 s13, s11, -1
	s_cmp_eq_u32 s54, 12
	s_cselect_b32 s15, s1, s13
	s_cselect_b32 s14, s29, s12
	s_cselect_b32 s13, s27, s53
	s_cselect_b32 s12, s51, s52
	v_lshl_add_u64 v[204:205], s[10:11], 0, v[196:197]
	s_add_i32 m0, s3, 0xc000
	ds_read_b128 v[160:163], v232
	ds_read_b128 v[164:167], v232 offset:1024
	ds_read_b128 v[168:171], v232 offset:2048
	ds_read_b128 v[172:175], v232 offset:3072
	ds_read_b128 v[176:179], v232 offset:4096
	ds_read_b128 v[180:183], v232 offset:5120
	ds_read_b128 v[184:187], v232 offset:6144
	ds_read_b128 v[188:191], v232 offset:7168
	global_load_lds_dwordx4 v[204:205], off
	v_lshl_add_u64 v[204:205], s[10:11], 0, v[198:199]
	s_add_i32 m0, s3, 0xe000
	s_nop 0
	global_load_lds_dwordx4 v[204:205], off
	s_waitcnt vmcnt(8)
	s_waitcnt lgkmcnt(0)
	s_barrier
	s_setprio 1
	s_waitcnt lgkmcnt(0)
	v_mfma_f32_16x16x32_bf16 v[120:123], v[128:131], v[160:163], v[120:123]
	v_mfma_f32_16x16x32_bf16 v[124:127], v[136:139], v[160:163], v[124:127]
	v_mfma_f32_16x16x32_bf16 v[104:107], v[128:131], v[168:171], v[104:107]
	v_mfma_f32_16x16x32_bf16 v[108:111], v[136:139], v[168:171], v[108:111]
	v_mfma_f32_16x16x32_bf16 v[88:91], v[128:131], v[176:179], v[88:91]
	v_mfma_f32_16x16x32_bf16 v[92:95], v[136:139], v[176:179], v[92:95]
	v_mfma_f32_16x16x32_bf16 v[72:75], v[128:131], v[184:187], v[72:75]
	v_mfma_f32_16x16x32_bf16 v[76:79], v[136:139], v[184:187], v[76:79]
	v_mfma_f32_16x16x32_bf16 v[120:123], v[132:135], v[164:167], v[120:123]
	v_mfma_f32_16x16x32_bf16 v[124:127], v[140:143], v[164:167], v[124:127]
	v_mfma_f32_16x16x32_bf16 v[104:107], v[132:135], v[172:175], v[104:107]
	v_mfma_f32_16x16x32_bf16 v[108:111], v[140:143], v[172:175], v[108:111]
	v_mfma_f32_16x16x32_bf16 v[88:91], v[132:135], v[180:183], v[88:91]
	v_mfma_f32_16x16x32_bf16 v[92:95], v[140:143], v[180:183], v[92:95]
	v_mfma_f32_16x16x32_bf16 v[72:75], v[132:135], v[188:191], v[72:75]
	v_mfma_f32_16x16x32_bf16 v[76:79], v[140:143], v[188:191], v[76:79]
	s_setprio 0
	s_setprio 1
	v_mfma_f32_16x16x32_bf16 v[112:115], v[144:147], v[160:163], v[112:115]
	v_mfma_f32_16x16x32_bf16 v[116:119], v[152:155], v[160:163], v[116:119]
	v_mfma_f32_16x16x32_bf16 v[96:99], v[144:147], v[168:171], v[96:99]
	v_mfma_f32_16x16x32_bf16 v[100:103], v[152:155], v[168:171], v[100:103]
	v_mfma_f32_16x16x32_bf16 v[80:83], v[144:147], v[176:179], v[80:83]
	v_mfma_f32_16x16x32_bf16 v[84:87], v[152:155], v[176:179], v[84:87]
	v_mfma_f32_16x16x32_bf16 v[64:67], v[144:147], v[184:187], v[64:67]
	v_mfma_f32_16x16x32_bf16 v[68:71], v[152:155], v[184:187], v[68:71]
	v_mfma_f32_16x16x32_bf16 v[112:115], v[148:151], v[164:167], v[112:115]
	v_mfma_f32_16x16x32_bf16 v[116:119], v[156:159], v[164:167], v[116:119]
	v_mfma_f32_16x16x32_bf16 v[96:99], v[148:151], v[172:175], v[96:99]
	v_mfma_f32_16x16x32_bf16 v[100:103], v[156:159], v[172:175], v[100:103]
	v_mfma_f32_16x16x32_bf16 v[80:83], v[148:151], v[180:183], v[80:83]
	v_mfma_f32_16x16x32_bf16 v[84:87], v[156:159], v[180:183], v[84:87]
	v_mfma_f32_16x16x32_bf16 v[64:67], v[148:151], v[188:191], v[64:67]
	v_mfma_f32_16x16x32_bf16 v[68:71], v[156:159], v[188:191], v[68:71]
	s_setprio 0
	s_barrier
	s_add_i32 s55, s48, s33
	v_lshl_add_u64 v[204:205], s[12:13], 0, v[192:193]
	s_mov_b32 m0, s55
	ds_read_b128 v[160:163], v232 offset:16384
	ds_read_b128 v[164:167], v232 offset:17408
	ds_read_b128 v[168:171], v232 offset:18432
	ds_read_b128 v[172:175], v232 offset:19456
	ds_read_b128 v[176:179], v232 offset:20480
	ds_read_b128 v[180:183], v232 offset:21504
	ds_read_b128 v[184:187], v232 offset:22528
	ds_read_b128 v[188:191], v232 offset:23552
	global_load_lds_dwordx4 v[204:205], off
	s_add_i32 m0, s55, 0x2000
	s_add_u32 s56, s12, 0x40000
	v_lshl_add_u64 v[206:207], s[12:13], 0, v[194:195]
	s_addc_u32 s57, s13, 0
	s_add_i32 s55, s49, s33
	global_load_lds_dwordx4 v[206:207], off
	v_lshl_add_u64 v[210:211], s[56:57], 0, v[192:193]
	s_mov_b32 m0, s55
	v_lshl_add_u64 v[212:213], s[14:15], 0, v[194:195]
	global_load_lds_dwordx4 v[210:211], off
	v_lshl_add_u64 v[210:211], s[56:57], 0, v[194:195]
	s_add_i32 m0, s55, 0x2000
	s_nop 0
	global_load_lds_dwordx4 v[210:211], off
	v_lshl_add_u64 v[210:211], s[14:15], 0, v[192:193]
	s_mov_b32 m0, s3
	s_nop 0
	global_load_lds_dwordx4 v[210:211], off
	s_mov_b32 m0, s36
	s_nop 0
	global_load_lds_dwordx4 v[212:213], off
	s_waitcnt vmcnt(8)
	s_waitcnt lgkmcnt(0)
	s_barrier
; #define PG8_STAGE(bufoff, gbase, voff) do { _Pragma("unroll") for (int _i = 0; _i < 2; ++_i) \
;         __builtin_amdgcn_global_load_lds((const unsigned*)((const char*)(gbase) + (voff)[_i]), (LAS unsigned*)(lds + (bufoff) + ldsw + _i * 8192), 16, 0, 0); } while (0)
; #define PG8_LDA(dst, b, h) do { _Pragma("unroll") for (int m = 0; m < 4; ++m) _Pragma("unroll") for (int k = 0; k < 2; ++k) dst[m][k] = *(const LAS bf16x8*)(lds + PG8_SA(b, h) + aoff + m * 2048 + k * 1024); } while (0)
; #define PG8_LDB(dst, b, h) do { _Pragma("unroll") for (int n = 0; n < 2; ++n) _Pragma("unroll") for (int k = 0; k < 2; ++k) dst[n][k] = *(const LAS bf16x8*)(lds + PG8_SB(b, h) + boff + n * 2048 + k * 1024); } while (0)
; #define PG8_MMA(ai, bj, At, Bt) do { __builtin_amdgcn_s_setprio(1); _Pragma("unroll") for (int m = 0; m < 4; ++m) _Pragma("unroll") for (int n = 0; n < 2; ++n) _Pragma("unroll") for (int k = 0; k < 2; ++k) \
;         acc[ai][bj][m][n] = __builtin_amdgcn_mfma_f32_16x16x32_bf16(Bt[n][k], At[m][k], acc[ai][bj][m][n], 0, 0, 0); __builtin_amdgcn_s_setprio(0); } while (0)
; #define PG8_WAIT_V(n) asm volatile("s_waitcnt vmcnt(" #n ")" ::: "memory")
; #define PG8_WAIT_L(n) asm volatile("s_waitcnt lgkmcnt(" #n ")" ::: "memory")
; #define PG8_BAR __builtin_amdgcn_s_barrier()
; #define PG8_SCHED __builtin_amdgcn_sched_barrier(0)
; template <class Epi>
; __device__ __forceinline__ void gemm_phase(LAS unsigned char* lds, const Gemm g, const StaticOrder& S, const Epi& E) {
;     ...
;             PG8_WAIT_V(8); PG8_WAIT_L(0); PG8_BAR; PG8_MMA(1, 0, At, B0); PG8_MMA(1, 1, At, B1); PG8_BAR; PG8_SCHED;
;             PG8_LDB(B0, 1, 0); PG8_LDB(B1, 1, 1); PG8_SCHED; PG8_LDA(At, 1, 0); PG8_STAGE(PG8_SA(0, 1), a2 + hstepA, voffA);
;             PG8_WAIT_V(8); PG8_WAIT_L(0); PG8_BAR; PG8_MMA(0, 0, At, B0); PG8_MMA(0, 1, At, B1); PG8_BAR; PG8_SCHED;
;             PG8_LDA(At, 1, 1); PG8_STAGE(PG8_SB(1, 0), b3, voffB); PG8_STAGE(PG8_SB(1, 1), b3 + hstepB, voffB); PG8_STAGE(PG8_SA(1, 0), a3, voffA);
	s_setprio 1
	s_waitcnt lgkmcnt(0)
	v_mfma_f32_16x16x32_bf16 v[56:59], v[128:131], v[160:163], v[56:59]
	v_mfma_f32_16x16x32_bf16 v[60:63], v[136:139], v[160:163], v[60:63]
	v_mfma_f32_16x16x32_bf16 v[40:43], v[128:131], v[168:171], v[40:43]
	v_mfma_f32_16x16x32_bf16 v[44:47], v[136:139], v[168:171], v[44:47]
	v_mfma_f32_16x16x32_bf16 v[24:27], v[128:131], v[176:179], v[24:27]
	v_mfma_f32_16x16x32_bf16 v[28:31], v[136:139], v[176:179], v[28:31]
	v_mfma_f32_16x16x32_bf16 v[8:11], v[128:131], v[184:187], v[8:11]
	v_mfma_f32_16x16x32_bf16 v[12:15], v[136:139], v[184:187], v[12:15]
	v_mfma_f32_16x16x32_bf16 v[56:59], v[132:135], v[164:167], v[56:59]
	v_mfma_f32_16x16x32_bf16 v[60:63], v[140:143], v[164:167], v[60:63]
	v_mfma_f32_16x16x32_bf16 v[40:43], v[132:135], v[172:175], v[40:43]
	v_mfma_f32_16x16x32_bf16 v[44:47], v[140:143], v[172:175], v[44:47]
	v_mfma_f32_16x16x32_bf16 v[24:27], v[132:135], v[180:183], v[24:27]
	v_mfma_f32_16x16x32_bf16 v[28:31], v[140:143], v[180:183], v[28:31]
	v_mfma_f32_16x16x32_bf16 v[8:11], v[132:135], v[188:191], v[8:11]
	v_mfma_f32_16x16x32_bf16 v[12:15], v[140:143], v[188:191], v[12:15]
	s_setprio 0
	s_setprio 1
	v_mfma_f32_16x16x32_bf16 v[48:51], v[144:147], v[160:163], v[48:51]
	v_mfma_f32_16x16x32_bf16 v[52:55], v[152:155], v[160:163], v[52:55]
	v_mfma_f32_16x16x32_bf16 v[32:35], v[144:147], v[168:171], v[32:35]
	v_mfma_f32_16x16x32_bf16 v[36:39], v[152:155], v[168:171], v[36:39]
	v_mfma_f32_16x16x32_bf16 v[16:19], v[144:147], v[176:179], v[16:19]
	v_mfma_f32_16x16x32_bf16 v[20:23], v[152:155], v[176:179], v[20:23]
	v_mfma_f32_16x16x32_bf16 v[4:7], v[144:147], v[184:187], v[4:7]
	v_mfma_f32_16x16x32_bf16 v[0:3], v[152:155], v[184:187], v[0:3]
	v_mfma_f32_16x16x32_bf16 v[48:51], v[148:151], v[164:167], v[48:51]
	v_mfma_f32_16x16x32_bf16 v[52:55], v[156:159], v[164:167], v[52:55]
	v_mfma_f32_16x16x32_bf16 v[32:35], v[148:151], v[172:175], v[32:35]
	v_mfma_f32_16x16x32_bf16 v[36:39], v[156:159], v[172:175], v[36:39]
	v_mfma_f32_16x16x32_bf16 v[16:19], v[148:151], v[180:183], v[16:19]
	v_mfma_f32_16x16x32_bf16 v[20:23], v[156:159], v[180:183], v[20:23]
	v_mfma_f32_16x16x32_bf16 v[4:7], v[148:151], v[188:191], v[4:7]
	v_mfma_f32_16x16x32_bf16 v[0:3], v[156:159], v[188:191], v[0:3]
	s_setprio 0
	s_barrier
	s_add_i32 s55, 0, 0x18000
	s_add_i32 s56, 0, 0x1c000
	v_add_u32_e32 v140, s55, v228
	v_add_u32_e32 v156, s56, v228
	ds_read_b128 v[128:131], v140
	ds_read_b128 v[132:135], v140 offset:1024
	ds_read_b128 v[136:139], v140 offset:2048
	ds_read_b128 v[140:143], v140 offset:3072
	ds_read_b128 v[144:147], v156
	ds_read_b128 v[148:151], v156 offset:1024
	ds_read_b128 v[152:155], v156 offset:2048
	ds_read_b128 v[156:159], v156 offset:3072
	s_add_u32 s14, s14, 0x40000
	s_addc_u32 s15, s15, 0
	s_mov_b32 m0, s37
	v_lshl_add_u64 v[214:215], s[14:15], 0, v[192:193]
	ds_read_b128 v[160:163], v232 offset:32768
	ds_read_b128 v[164:167], v232 offset:33792
	ds_read_b128 v[168:171], v232 offset:34816
	ds_read_b128 v[172:175], v232 offset:35840
	ds_read_b128 v[176:179], v232 offset:36864
	ds_read_b128 v[180:183], v232 offset:37888
	ds_read_b128 v[184:187], v232 offset:38912
	ds_read_b128 v[188:191], v232 offset:39936
	global_load_lds_dwordx4 v[214:215], off
	v_lshl_add_u64 v[214:215], s[14:15], 0, v[194:195]
	s_mov_b32 m0, s38
	s_nop 0
	global_load_lds_dwordx4 v[214:215], off
	s_waitcnt vmcnt(8)
	s_waitcnt lgkmcnt(0)
	s_barrier
	s_setprio 1
	s_waitcnt lgkmcnt(0)
	v_mfma_f32_16x16x32_bf16 v[120:123], v[128:131], v[160:163], v[120:123]
	v_mfma_f32_16x16x32_bf16 v[124:127], v[136:139], v[160:163], v[124:127]
	v_mfma_f32_16x16x32_bf16 v[104:107], v[128:131], v[168:171], v[104:107]
	v_mfma_f32_16x16x32_bf16 v[108:111], v[136:139], v[168:171], v[108:111]
	v_mfma_f32_16x16x32_bf16 v[88:91], v[128:131], v[176:179], v[88:91]
	v_mfma_f32_16x16x32_bf16 v[92:95], v[136:139], v[176:179], v[92:95]
	v_mfma_f32_16x16x32_bf16 v[72:75], v[128:131], v[184:187], v[72:75]
	v_mfma_f32_16x16x32_bf16 v[76:79], v[136:139], v[184:187], v[76:79]
	v_mfma_f32_16x16x32_bf16 v[120:123], v[132:135], v[164:167], v[120:123]
	v_mfma_f32_16x16x32_bf16 v[124:127], v[140:143], v[164:167], v[124:127]
	v_mfma_f32_16x16x32_bf16 v[104:107], v[132:135], v[172:175], v[104:107]
	v_mfma_f32_16x16x32_bf16 v[108:111], v[140:143], v[172:175], v[108:111]
	v_mfma_f32_16x16x32_bf16 v[88:91], v[132:135], v[180:183], v[88:91]
	v_mfma_f32_16x16x32_bf16 v[92:95], v[140:143], v[180:183], v[92:95]
	v_mfma_f32_16x16x32_bf16 v[72:75], v[132:135], v[188:191], v[72:75]
	v_mfma_f32_16x16x32_bf16 v[76:79], v[140:143], v[188:191], v[76:79]
	s_setprio 0
	s_setprio 1
	v_mfma_f32_16x16x32_bf16 v[112:115], v[144:147], v[160:163], v[112:115]
	v_mfma_f32_16x16x32_bf16 v[116:119], v[152:155], v[160:163], v[116:119]
	v_mfma_f32_16x16x32_bf16 v[96:99], v[144:147], v[168:171], v[96:99]
	v_mfma_f32_16x16x32_bf16 v[100:103], v[152:155], v[168:171], v[100:103]
	v_mfma_f32_16x16x32_bf16 v[80:83], v[144:147], v[176:179], v[80:83]
	v_mfma_f32_16x16x32_bf16 v[84:87], v[152:155], v[176:179], v[84:87]
	v_mfma_f32_16x16x32_bf16 v[64:67], v[144:147], v[184:187], v[64:67]
	v_mfma_f32_16x16x32_bf16 v[68:71], v[152:155], v[184:187], v[68:71]
	v_mfma_f32_16x16x32_bf16 v[112:115], v[148:151], v[164:167], v[112:115]
	v_mfma_f32_16x16x32_bf16 v[116:119], v[156:159], v[164:167], v[116:119]
	v_mfma_f32_16x16x32_bf16 v[96:99], v[148:151], v[172:175], v[96:99]
	v_mfma_f32_16x16x32_bf16 v[100:103], v[156:159], v[172:175], v[100:103]
	v_mfma_f32_16x16x32_bf16 v[80:83], v[148:151], v[180:183], v[80:83]
	v_mfma_f32_16x16x32_bf16 v[84:87], v[156:159], v[180:183], v[84:87]
	v_mfma_f32_16x16x32_bf16 v[64:67], v[148:151], v[188:191], v[64:67]
	v_mfma_f32_16x16x32_bf16 v[68:71], v[156:159], v[188:191], v[68:71]
	s_setprio 0
	s_barrier
; #define PG8_STAGE(bufoff, gbase, voff) do { _Pragma("unroll") for (int _i = 0; _i < 2; ++_i) \
;         __builtin_amdgcn_global_load_lds((const unsigned*)((const char*)(gbase) + (voff)[_i]), (LAS unsigned*)(lds + (bufoff) + ldsw + _i * 8192), 16, 0, 0); } while (0)
; #define PG8_LDA(dst, b, h) do { _Pragma("unroll") for (int m = 0; m < 4; ++m) _Pragma("unroll") for (int k = 0; k < 2; ++k) dst[m][k] = *(const LAS bf16x8*)(lds + PG8_SA(b, h) + aoff + m * 2048 + k * 1024); } while (0)
; #define PG8_MMA(ai, bj, At, Bt) do { __builtin_amdgcn_s_setprio(1); _Pragma("unroll") for (int m = 0; m < 4; ++m) _Pragma("unroll") for (int n = 0; n < 2; ++n) _Pragma("unroll") for (int k = 0; k < 2; ++k) \
;         acc[ai][bj][m][n] = __builtin_amdgcn_mfma_f32_16x16x32_bf16(Bt[n][k], At[m][k], acc[ai][bj][m][n], 0, 0, 0); __builtin_amdgcn_s_setprio(0); } while (0)
; #define PG8_WAIT_V(n) asm volatile("s_waitcnt vmcnt(" #n ")" ::: "memory")
; #define PG8_WAIT_L(n) asm volatile("s_waitcnt lgkmcnt(" #n ")" ::: "memory")
; #define PG8_BAR __builtin_amdgcn_s_barrier()
; #define PG8_SCHED __builtin_amdgcn_sched_barrier(0)
; template <class Epi>
; __device__ __forceinline__ void gemm_phase(LAS unsigned char* lds, const Gemm g, const StaticOrder& S, const Epi& E) {
;     ...
;             PG8_LDA(At, 1, 1); PG8_STAGE(PG8_SB(1, 0), b3, voffB); PG8_STAGE(PG8_SB(1, 1), b3 + hstepB, voffB); PG8_STAGE(PG8_SA(1, 0), a3, voffA);
;             PG8_WAIT_V(8); PG8_WAIT_L(0); PG8_BAR; PG8_MMA(1, 0, At, B0); PG8_MMA(1, 1, At, B1); PG8_BAR; PG8_SCHED;
;         }
;         if (wr == 0) PG8_BAR;
	s_add_i32 s14, s55, s33
	v_lshl_add_u64 v[204:205], v[204:205], 0, s[22:23]
	s_mov_b32 m0, s14
	ds_read_b128 v[160:163], v232 offset:49152
	ds_read_b128 v[164:167], v232 offset:50176
	ds_read_b128 v[168:171], v232 offset:51200
	ds_read_b128 v[172:175], v232 offset:52224
	ds_read_b128 v[176:179], v232 offset:53248
	ds_read_b128 v[180:183], v232 offset:54272
	ds_read_b128 v[184:187], v232 offset:55296
	ds_read_b128 v[188:191], v232 offset:56320
	global_load_lds_dwordx4 v[204:205], off
	s_add_i32 m0, s14, 0x2000
	s_add_u32 s12, s12, 0x40080
	v_lshl_add_u64 v[204:205], v[206:207], 0, s[22:23]
	s_addc_u32 s13, s13, 0
	s_add_i32 s14, s56, s33
	global_load_lds_dwordx4 v[204:205], off
	v_lshl_add_u64 v[204:205], s[12:13], 0, v[192:193]
	s_mov_b32 m0, s14
	s_nop 0
	global_load_lds_dwordx4 v[204:205], off
	v_lshl_add_u64 v[204:205], s[12:13], 0, v[194:195]
	s_add_i32 m0, s14, 0x2000
	s_nop 0
	global_load_lds_dwordx4 v[204:205], off
	v_lshl_add_u64 v[204:205], v[210:211], 0, s[22:23]
	s_mov_b32 m0, s40
	s_nop 0
	global_load_lds_dwordx4 v[204:205], off
	v_lshl_add_u64 v[204:205], v[212:213], 0, s[22:23]
	s_mov_b32 m0, s41
	s_nop 0
	global_load_lds_dwordx4 v[204:205], off
	s_waitcnt vmcnt(8)
	s_waitcnt lgkmcnt(0)
	s_barrier
	s_setprio 1
	s_waitcnt lgkmcnt(0)
	v_mfma_f32_16x16x32_bf16 v[56:59], v[128:131], v[160:163], v[56:59]
	v_mfma_f32_16x16x32_bf16 v[60:63], v[136:139], v[160:163], v[60:63]
	v_mfma_f32_16x16x32_bf16 v[40:43], v[128:131], v[168:171], v[40:43]
	v_mfma_f32_16x16x32_bf16 v[44:47], v[136:139], v[168:171], v[44:47]
	v_mfma_f32_16x16x32_bf16 v[24:27], v[128:131], v[176:179], v[24:27]
	v_mfma_f32_16x16x32_bf16 v[28:31], v[136:139], v[176:179], v[28:31]
	v_mfma_f32_16x16x32_bf16 v[8:11], v[128:131], v[184:187], v[8:11]
	v_mfma_f32_16x16x32_bf16 v[12:15], v[136:139], v[184:187], v[12:15]
	v_mfma_f32_16x16x32_bf16 v[56:59], v[132:135], v[164:167], v[56:59]
	v_mfma_f32_16x16x32_bf16 v[60:63], v[140:143], v[164:167], v[60:63]
	v_mfma_f32_16x16x32_bf16 v[40:43], v[132:135], v[172:175], v[40:43]
	v_mfma_f32_16x16x32_bf16 v[44:47], v[140:143], v[172:175], v[44:47]
	v_mfma_f32_16x16x32_bf16 v[24:27], v[132:135], v[180:183], v[24:27]
	v_mfma_f32_16x16x32_bf16 v[28:31], v[140:143], v[180:183], v[28:31]
	v_mfma_f32_16x16x32_bf16 v[8:11], v[132:135], v[188:191], v[8:11]
	v_mfma_f32_16x16x32_bf16 v[12:15], v[140:143], v[188:191], v[12:15]
	s_setprio 0
	s_setprio 1
	v_mfma_f32_16x16x32_bf16 v[48:51], v[144:147], v[160:163], v[48:51]
	v_mfma_f32_16x16x32_bf16 v[52:55], v[152:155], v[160:163], v[52:55]
	v_mfma_f32_16x16x32_bf16 v[32:35], v[144:147], v[168:171], v[32:35]
	v_mfma_f32_16x16x32_bf16 v[36:39], v[152:155], v[168:171], v[36:39]
	v_mfma_f32_16x16x32_bf16 v[16:19], v[144:147], v[176:179], v[16:19]
	v_mfma_f32_16x16x32_bf16 v[20:23], v[152:155], v[176:179], v[20:23]
	v_mfma_f32_16x16x32_bf16 v[4:7], v[144:147], v[184:187], v[4:7]
	v_mfma_f32_16x16x32_bf16 v[0:3], v[152:155], v[184:187], v[0:3]
	v_mfma_f32_16x16x32_bf16 v[48:51], v[148:151], v[164:167], v[48:51]
	v_mfma_f32_16x16x32_bf16 v[52:55], v[156:159], v[164:167], v[52:55]
	v_mfma_f32_16x16x32_bf16 v[32:35], v[148:151], v[172:175], v[32:35]
	v_mfma_f32_16x16x32_bf16 v[36:39], v[156:159], v[172:175], v[36:39]
	v_mfma_f32_16x16x32_bf16 v[16:19], v[148:151], v[180:183], v[16:19]
	v_mfma_f32_16x16x32_bf16 v[20:23], v[156:159], v[180:183], v[20:23]
	v_mfma_f32_16x16x32_bf16 v[4:7], v[148:151], v[188:191], v[4:7]
	v_mfma_f32_16x16x32_bf16 v[0:3], v[156:159], v[188:191], v[0:3]
	s_setprio 0
	s_add_i32 s54, s54, 2
	s_add_u32 s10, s10, 0x100
	s_addc_u32 s11, s11, 0
	s_add_u32 s52, s52, 0x100
	s_addc_u32 s53, s53, 0
	s_cmp_gt_u32 s54, 13
	s_barrier
	s_cbranch_scc0 .LBB0_1598
	s_and_b64 vcc, exec, s[24:25]
	s_cbranch_vccz .LBB0_1601
	s_barrier

; #define PG8_STAGE(bufoff, gbase, voff) do { _Pragma("unroll") for (int _i = 0; _i < 2; ++_i) \
;         __builtin_amdgcn_global_load_lds((const unsigned*)((const char*)(gbase) + (voff)[_i]), (LAS unsigned*)(lds + (bufoff) + ldsw + _i * 8192), 16, 0, 0); } while (0)
; #define PG8_LDA(dst, b, h) do { _Pragma("unroll") for (int m = 0; m < 4; ++m) _Pragma("unroll") for (int k = 0; k < 2; ++k) dst[m][k] = *(const LAS bf16x8*)(lds + PG8_SA(b, h) + aoff + m * 2048 + k * 1024); } while (0)
; #define PG8_LDB(dst, b, h) do { _Pragma("unroll") for (int n = 0; n < 2; ++n) _Pragma("unroll") for (int k = 0; k < 2; ++k) dst[n][k] = *(const LAS bf16x8*)(lds + PG8_SB(b, h) + boff + n * 2048 + k * 1024); } while (0)
; #define PG8_MMA(ai, bj, At, Bt) do { __builtin_amdgcn_s_setprio(1); _Pragma("unroll") for (int m = 0; m < 4; ++m) _Pragma("unroll") for (int n = 0; n < 2; ++n) _Pragma("unroll") for (int k = 0; k < 2; ++k) \
;         acc[ai][bj][m][n] = __builtin_amdgcn_mfma_f32_16x16x32_bf16(Bt[n][k], At[m][k], acc[ai][bj][m][n], 0, 0, 0); __builtin_amdgcn_s_setprio(0); } while (0)
; #define PG8_WAIT_V(n) asm volatile("s_waitcnt vmcnt(" #n ")" ::: "memory")
; #define PG8_WAIT_L(n) asm volatile("s_waitcnt lgkmcnt(" #n ")" ::: "memory")
; #define PG8_BAR __builtin_amdgcn_s_barrier()
; #define PG8_SCHED __builtin_amdgcn_sched_barrier(0)
; template <class Epi>
; __device__ __forceinline__ void gemm_phase(LAS unsigned char* lds, const Gemm g, const StaticOrder& S, const Epi& E) {
;     ...
;         for (int t = 0; t < nt; t += 2) {
;             const bool last = (t == nt - 2);
;             const char* a1 = cA + (size_t)(t + 1) * kstepA;
;             const char* a2 = last ? nA : cA + (size_t)(t + 2) * kstepA; const char* b2 = last ? nB : cB + (size_t)(t + 2) * kstep;
;             const char* a3 = a2 + kstepA; const char* b3 = b2 + kstep;
;             PG8_LDB(B0, 0, 0); PG8_LDB(B1, 0, 1); PG8_SCHED; PG8_LDA(At, 0, 0); PG8_STAGE(PG8_SA(1, 1), a1 + hstepA, voffA);
;             PG8_WAIT_V(8); PG8_WAIT_L(0); PG8_BAR; PG8_MMA(0, 0, At, B0); PG8_MMA(0, 1, At, B1); PG8_BAR; PG8_SCHED;
;             PG8_LDA(At, 0, 1); PG8_STAGE(PG8_SB(0, 0), b2, voffB); PG8_STAGE(PG8_SB(0, 1), b2 + hstepB, voffB); PG8_STAGE(PG8_SA(0, 0), a2, voffA);
.LBB0_1732:
	ds_read_b128 v[150:153], v146
	ds_read_b128 v[154:157], v146 offset:1024
	ds_read_b128 v[158:161], v146 offset:2048
	ds_read_b128 v[162:165], v146 offset:3072
	ds_read_b128 v[166:169], v147
	ds_read_b128 v[170:173], v147 offset:1024
	ds_read_b128 v[174:177], v147 offset:2048
	ds_read_b128 v[178:181], v147 offset:3072
	s_add_u32 s28, s26, 0xfffc0080
	s_addc_u32 s29, s27, -1
	s_cmp_eq_u32 s55, 12
	s_cselect_b32 s31, s21, s29
	s_cselect_b32 s30, s51, s28
	s_cselect_b32 s29, s15, s54
	s_cselect_b32 s28, s52, s53
	v_lshl_add_u64 v[206:207], s[26:27], 0, v[136:137]
	s_add_i32 m0, s36, 0xc000
	ds_read_b128 v[182:185], v148
	ds_read_b128 v[186:189], v148 offset:1024
	ds_read_b128 v[190:193], v148 offset:2048
	ds_read_b128 v[194:197], v148 offset:3072
	ds_read_b128 v[198:201], v148 offset:4096
	ds_read_b128 v[202:205], v148 offset:5120
	ds_read_b128 v[210:213], v148 offset:6144
	ds_read_b128 v[214:217], v148 offset:7168
	global_load_lds_dwordx4 v[206:207], off
	v_lshl_add_u64 v[206:207], s[26:27], 0, v[138:139]
	s_add_i32 m0, s36, 0xe000
	s_nop 0
	global_load_lds_dwordx4 v[206:207], off
	s_waitcnt vmcnt(8)
	s_waitcnt lgkmcnt(0)
	s_barrier
	s_setprio 1
	s_waitcnt lgkmcnt(0)
	v_mfma_f32_16x16x32_bf16 v[124:127], v[150:153], v[182:185], v[124:127]
	v_mfma_f32_16x16x32_bf16 v[116:119], v[158:161], v[182:185], v[116:119]
	v_mfma_f32_16x16x32_bf16 v[108:111], v[150:153], v[190:193], v[108:111]
	v_mfma_f32_16x16x32_bf16 v[100:103], v[158:161], v[190:193], v[100:103]
	v_mfma_f32_16x16x32_bf16 v[92:95], v[150:153], v[198:201], v[92:95]
	v_mfma_f32_16x16x32_bf16 v[84:87], v[158:161], v[198:201], v[84:87]
	v_mfma_f32_16x16x32_bf16 v[76:79], v[150:153], v[210:213], v[76:79]
	v_mfma_f32_16x16x32_bf16 v[68:71], v[158:161], v[210:213], v[68:71]
	v_mfma_f32_16x16x32_bf16 v[124:127], v[154:157], v[186:189], v[124:127]
	v_mfma_f32_16x16x32_bf16 v[116:119], v[162:165], v[186:189], v[116:119]
	v_mfma_f32_16x16x32_bf16 v[108:111], v[154:157], v[194:197], v[108:111]
	v_mfma_f32_16x16x32_bf16 v[100:103], v[162:165], v[194:197], v[100:103]
	v_mfma_f32_16x16x32_bf16 v[92:95], v[154:157], v[202:205], v[92:95]
	v_mfma_f32_16x16x32_bf16 v[84:87], v[162:165], v[202:205], v[84:87]
	v_mfma_f32_16x16x32_bf16 v[76:79], v[154:157], v[214:217], v[76:79]
	v_mfma_f32_16x16x32_bf16 v[68:71], v[162:165], v[214:217], v[68:71]
	s_setprio 0
	s_setprio 1
	v_mfma_f32_16x16x32_bf16 v[120:123], v[166:169], v[182:185], v[120:123]
	v_mfma_f32_16x16x32_bf16 v[112:115], v[174:177], v[182:185], v[112:115]
	v_mfma_f32_16x16x32_bf16 v[104:107], v[166:169], v[190:193], v[104:107]
	v_mfma_f32_16x16x32_bf16 v[96:99], v[174:177], v[190:193], v[96:99]
	v_mfma_f32_16x16x32_bf16 v[88:91], v[166:169], v[198:201], v[88:91]
	v_mfma_f32_16x16x32_bf16 v[80:83], v[174:177], v[198:201], v[80:83]
	v_mfma_f32_16x16x32_bf16 v[72:75], v[166:169], v[210:213], v[72:75]
	v_mfma_f32_16x16x32_bf16 v[64:67], v[174:177], v[210:213], v[64:67]
	v_mfma_f32_16x16x32_bf16 v[120:123], v[170:173], v[186:189], v[120:123]
	v_mfma_f32_16x16x32_bf16 v[112:115], v[178:181], v[186:189], v[112:115]
	v_mfma_f32_16x16x32_bf16 v[104:107], v[170:173], v[194:197], v[104:107]
	v_mfma_f32_16x16x32_bf16 v[96:99], v[178:181], v[194:197], v[96:99]
	v_mfma_f32_16x16x32_bf16 v[88:91], v[170:173], v[202:205], v[88:91]
	v_mfma_f32_16x16x32_bf16 v[80:83], v[178:181], v[202:205], v[80:83]
	v_mfma_f32_16x16x32_bf16 v[72:75], v[170:173], v[214:217], v[72:75]
	v_mfma_f32_16x16x32_bf16 v[64:67], v[178:181], v[214:217], v[64:67]
	s_setprio 0
	s_barrier
	s_add_i32 s56, s46, s33
	v_lshl_add_u64 v[206:207], s[28:29], 0, v[130:131]
	s_mov_b32 m0, s56
	ds_read_b128 v[182:185], v148 offset:16384
	ds_read_b128 v[186:189], v148 offset:17408
	ds_read_b128 v[190:193], v148 offset:18432
	ds_read_b128 v[194:197], v148 offset:19456
	ds_read_b128 v[198:201], v148 offset:20480
	ds_read_b128 v[202:205], v148 offset:21504
	ds_read_b128 v[210:213], v148 offset:22528
	ds_read_b128 v[214:217], v148 offset:23552
	global_load_lds_dwordx4 v[206:207], off
	s_add_i32 m0, s56, 0x2000
	s_add_u32 s56, s28, 0x40000
	v_lshl_add_u64 v[218:219], s[28:29], 0, v[128:129]
	s_addc_u32 s57, s29, 0
	s_add_i32 s58, s47, s33
	global_load_lds_dwordx4 v[218:219], off
	v_lshl_add_u64 v[220:221], s[56:57], 0, v[130:131]
	s_mov_b32 m0, s58
	v_lshl_add_u64 v[222:223], s[30:31], 0, v[128:129]
	global_load_lds_dwordx4 v[220:221], off
	v_lshl_add_u64 v[220:221], s[56:57], 0, v[128:129]
	s_add_i32 m0, s58, 0x2000
	s_nop 0
	global_load_lds_dwordx4 v[220:221], off
	v_lshl_add_u64 v[220:221], s[30:31], 0, v[130:131]
	s_mov_b32 m0, s36
	s_nop 0
	global_load_lds_dwordx4 v[220:221], off
	s_mov_b32 m0, s37
	s_nop 0
	global_load_lds_dwordx4 v[222:223], off
	s_waitcnt vmcnt(8)
	s_waitcnt lgkmcnt(0)
	s_barrier
; #define PG8_STAGE(bufoff, gbase, voff) do { _Pragma("unroll") for (int _i = 0; _i < 2; ++_i) \
;         __builtin_amdgcn_global_load_lds((const unsigned*)((const char*)(gbase) + (voff)[_i]), (LAS unsigned*)(lds + (bufoff) + ldsw + _i * 8192), 16, 0, 0); } while (0)
; #define PG8_LDA(dst, b, h) do { _Pragma("unroll") for (int m = 0; m < 4; ++m) _Pragma("unroll") for (int k = 0; k < 2; ++k) dst[m][k] = *(const LAS bf16x8*)(lds + PG8_SA(b, h) + aoff + m * 2048 + k * 1024); } while (0)
; #define PG8_LDB(dst, b, h) do { _Pragma("unroll") for (int n = 0; n < 2; ++n) _Pragma("unroll") for (int k = 0; k < 2; ++k) dst[n][k] = *(const LAS bf16x8*)(lds + PG8_SB(b, h) + boff + n * 2048 + k * 1024); } while (0)
; #define PG8_MMA(ai, bj, At, Bt) do { __builtin_amdgcn_s_setprio(1); _Pragma("unroll") for (int m = 0; m < 4; ++m) _Pragma("unroll") for (int n = 0; n < 2; ++n) _Pragma("unroll") for (int k = 0; k < 2; ++k) \
;         acc[ai][bj][m][n] = __builtin_amdgcn_mfma_f32_16x16x32_bf16(Bt[n][k], At[m][k], acc[ai][bj][m][n], 0, 0, 0); __builtin_amdgcn_s_setprio(0); } while (0)
; #define PG8_WAIT_V(n) asm volatile("s_waitcnt vmcnt(" #n ")" ::: "memory")
; #define PG8_WAIT_L(n) asm volatile("s_waitcnt lgkmcnt(" #n ")" ::: "memory")
; #define PG8_BAR __builtin_amdgcn_s_barrier()
; #define PG8_SCHED __builtin_amdgcn_sched_barrier(0)
; template <class Epi>
; __device__ __forceinline__ void gemm_phase(LAS unsigned char* lds, const Gemm g, const StaticOrder& S, const Epi& E) {
;     ...
;             PG8_WAIT_V(8); PG8_WAIT_L(0); PG8_BAR; PG8_MMA(1, 0, At, B0); PG8_MMA(1, 1, At, B1); PG8_BAR; PG8_SCHED;
;             PG8_LDB(B0, 1, 0); PG8_LDB(B1, 1, 1); PG8_SCHED; PG8_LDA(At, 1, 0); PG8_STAGE(PG8_SA(0, 1), a2 + hstepA, voffA);
;             PG8_WAIT_V(8); PG8_WAIT_L(0); PG8_BAR; PG8_MMA(0, 0, At, B0); PG8_MMA(0, 1, At, B1); PG8_BAR; PG8_SCHED;
;             PG8_LDA(At, 1, 1); PG8_STAGE(PG8_SB(1, 0), b3, voffB); PG8_STAGE(PG8_SB(1, 1), b3 + hstepB, voffB); PG8_STAGE(PG8_SA(1, 0), a3, voffA);
	s_setprio 1
	s_waitcnt lgkmcnt(0)
	v_mfma_f32_16x16x32_bf16 v[60:63], v[150:153], v[182:185], v[60:63]
	v_mfma_f32_16x16x32_bf16 v[52:55], v[158:161], v[182:185], v[52:55]
	v_mfma_f32_16x16x32_bf16 v[44:47], v[150:153], v[190:193], v[44:47]
	v_mfma_f32_16x16x32_bf16 v[36:39], v[158:161], v[190:193], v[36:39]
	v_mfma_f32_16x16x32_bf16 v[28:31], v[150:153], v[198:201], v[28:31]
	v_mfma_f32_16x16x32_bf16 v[20:23], v[158:161], v[198:201], v[20:23]
	v_mfma_f32_16x16x32_bf16 v[12:15], v[150:153], v[210:213], v[12:15]
	v_mfma_f32_16x16x32_bf16 v[4:7], v[158:161], v[210:213], v[4:7]
	v_mfma_f32_16x16x32_bf16 v[60:63], v[154:157], v[186:189], v[60:63]
	v_mfma_f32_16x16x32_bf16 v[52:55], v[162:165], v[186:189], v[52:55]
	v_mfma_f32_16x16x32_bf16 v[44:47], v[154:157], v[194:197], v[44:47]
	v_mfma_f32_16x16x32_bf16 v[36:39], v[162:165], v[194:197], v[36:39]
	v_mfma_f32_16x16x32_bf16 v[28:31], v[154:157], v[202:205], v[28:31]
	v_mfma_f32_16x16x32_bf16 v[20:23], v[162:165], v[202:205], v[20:23]
	v_mfma_f32_16x16x32_bf16 v[12:15], v[154:157], v[214:217], v[12:15]
	v_mfma_f32_16x16x32_bf16 v[4:7], v[162:165], v[214:217], v[4:7]
	s_setprio 0
	s_setprio 1
	v_mfma_f32_16x16x32_bf16 v[56:59], v[166:169], v[182:185], v[56:59]
	v_mfma_f32_16x16x32_bf16 v[48:51], v[174:177], v[182:185], v[48:51]
	v_mfma_f32_16x16x32_bf16 v[40:43], v[166:169], v[190:193], v[40:43]
	v_mfma_f32_16x16x32_bf16 v[32:35], v[174:177], v[190:193], v[32:35]
	v_mfma_f32_16x16x32_bf16 v[24:27], v[166:169], v[198:201], v[24:27]
	v_mfma_f32_16x16x32_bf16 v[16:19], v[174:177], v[198:201], v[16:19]
	v_mfma_f32_16x16x32_bf16 v[8:11], v[166:169], v[210:213], v[8:11]
	v_mfma_f32_16x16x32_bf16 v[0:3], v[174:177], v[210:213], v[0:3]
	v_mfma_f32_16x16x32_bf16 v[56:59], v[170:173], v[186:189], v[56:59]
	v_mfma_f32_16x16x32_bf16 v[48:51], v[178:181], v[186:189], v[48:51]
	v_mfma_f32_16x16x32_bf16 v[40:43], v[170:173], v[194:197], v[40:43]
	v_mfma_f32_16x16x32_bf16 v[32:35], v[178:181], v[194:197], v[32:35]
	v_mfma_f32_16x16x32_bf16 v[24:27], v[170:173], v[202:205], v[24:27]
	v_mfma_f32_16x16x32_bf16 v[16:19], v[178:181], v[202:205], v[16:19]
	v_mfma_f32_16x16x32_bf16 v[8:11], v[170:173], v[214:217], v[8:11]
	v_mfma_f32_16x16x32_bf16 v[0:3], v[178:181], v[214:217], v[0:3]
	s_setprio 0
	s_barrier
	s_add_i32 s56, 0, 0x18000
	s_add_i32 s57, 0, 0x1c000
	v_add_u32_e32 v162, s56, v145
	v_add_u32_e32 v178, s57, v145
	ds_read_b128 v[150:153], v162
	ds_read_b128 v[154:157], v162 offset:1024
	ds_read_b128 v[158:161], v162 offset:2048
	ds_read_b128 v[162:165], v162 offset:3072
	ds_read_b128 v[166:169], v178
	ds_read_b128 v[170:173], v178 offset:1024
	ds_read_b128 v[174:177], v178 offset:2048
	ds_read_b128 v[178:181], v178 offset:3072
	s_add_u32 s30, s30, 0x40000
	s_addc_u32 s31, s31, 0
	s_mov_b32 m0, s38
	v_lshl_add_u64 v[224:225], s[30:31], 0, v[130:131]
	ds_read_b128 v[182:185], v148 offset:32768
	ds_read_b128 v[186:189], v148 offset:33792
	ds_read_b128 v[190:193], v148 offset:34816
	ds_read_b128 v[194:197], v148 offset:35840
	ds_read_b128 v[198:201], v148 offset:36864
	ds_read_b128 v[202:205], v148 offset:37888
	ds_read_b128 v[210:213], v148 offset:38912
	ds_read_b128 v[214:217], v148 offset:39936
	global_load_lds_dwordx4 v[224:225], off
	v_lshl_add_u64 v[224:225], s[30:31], 0, v[128:129]
	s_mov_b32 m0, s39
	s_nop 0
	global_load_lds_dwordx4 v[224:225], off
	s_waitcnt vmcnt(8)
	s_waitcnt lgkmcnt(0)
	s_barrier
	s_setprio 1
	s_waitcnt lgkmcnt(0)
	v_mfma_f32_16x16x32_bf16 v[124:127], v[150:153], v[182:185], v[124:127]
	v_mfma_f32_16x16x32_bf16 v[116:119], v[158:161], v[182:185], v[116:119]
	v_mfma_f32_16x16x32_bf16 v[108:111], v[150:153], v[190:193], v[108:111]
	v_mfma_f32_16x16x32_bf16 v[100:103], v[158:161], v[190:193], v[100:103]
	v_mfma_f32_16x16x32_bf16 v[92:95], v[150:153], v[198:201], v[92:95]
	v_mfma_f32_16x16x32_bf16 v[84:87], v[158:161], v[198:201], v[84:87]
	v_mfma_f32_16x16x32_bf16 v[76:79], v[150:153], v[210:213], v[76:79]
	v_mfma_f32_16x16x32_bf16 v[68:71], v[158:161], v[210:213], v[68:71]
	v_mfma_f32_16x16x32_bf16 v[124:127], v[154:157], v[186:189], v[124:127]
	v_mfma_f32_16x16x32_bf16 v[116:119], v[162:165], v[186:189], v[116:119]
	v_mfma_f32_16x16x32_bf16 v[108:111], v[154:157], v[194:197], v[108:111]
	v_mfma_f32_16x16x32_bf16 v[100:103], v[162:165], v[194:197], v[100:103]
	v_mfma_f32_16x16x32_bf16 v[92:95], v[154:157], v[202:205], v[92:95]
	v_mfma_f32_16x16x32_bf16 v[84:87], v[162:165], v[202:205], v[84:87]
	v_mfma_f32_16x16x32_bf16 v[76:79], v[154:157], v[214:217], v[76:79]
	v_mfma_f32_16x16x32_bf16 v[68:71], v[162:165], v[214:217], v[68:71]
	s_setprio 0
	s_setprio 1
	v_mfma_f32_16x16x32_bf16 v[120:123], v[166:169], v[182:185], v[120:123]
	v_mfma_f32_16x16x32_bf16 v[112:115], v[174:177], v[182:185], v[112:115]
	v_mfma_f32_16x16x32_bf16 v[104:107], v[166:169], v[190:193], v[104:107]
	v_mfma_f32_16x16x32_bf16 v[96:99], v[174:177], v[190:193], v[96:99]
	v_mfma_f32_16x16x32_bf16 v[88:91], v[166:169], v[198:201], v[88:91]
	v_mfma_f32_16x16x32_bf16 v[80:83], v[174:177], v[198:201], v[80:83]
	v_mfma_f32_16x16x32_bf16 v[72:75], v[166:169], v[210:213], v[72:75]
	v_mfma_f32_16x16x32_bf16 v[64:67], v[174:177], v[210:213], v[64:67]
	v_mfma_f32_16x16x32_bf16 v[120:123], v[170:173], v[186:189], v[120:123]
	v_mfma_f32_16x16x32_bf16 v[112:115], v[178:181], v[186:189], v[112:115]
	v_mfma_f32_16x16x32_bf16 v[104:107], v[170:173], v[194:197], v[104:107]
	v_mfma_f32_16x16x32_bf16 v[96:99], v[178:181], v[194:197], v[96:99]
	v_mfma_f32_16x16x32_bf16 v[88:91], v[170:173], v[202:205], v[88:91]
	v_mfma_f32_16x16x32_bf16 v[80:83], v[178:181], v[202:205], v[80:83]
	v_mfma_f32_16x16x32_bf16 v[72:75], v[170:173], v[214:217], v[72:75]
	v_mfma_f32_16x16x32_bf16 v[64:67], v[178:181], v[214:217], v[64:67]
	s_setprio 0
	s_barrier
; #define PG8_STAGE(bufoff, gbase, voff) do { _Pragma("unroll") for (int _i = 0; _i < 2; ++_i) \
;         __builtin_amdgcn_global_load_lds((const unsigned*)((const char*)(gbase) + (voff)[_i]), (LAS unsigned*)(lds + (bufoff) + ldsw + _i * 8192), 16, 0, 0); } while (0)
; #define PG8_LDA(dst, b, h) do { _Pragma("unroll") for (int m = 0; m < 4; ++m) _Pragma("unroll") for (int k = 0; k < 2; ++k) dst[m][k] = *(const LAS bf16x8*)(lds + PG8_SA(b, h) + aoff + m * 2048 + k * 1024); } while (0)
; #define PG8_MMA(ai, bj, At, Bt) do { __builtin_amdgcn_s_setprio(1); _Pragma("unroll") for (int m = 0; m < 4; ++m) _Pragma("unroll") for (int n = 0; n < 2; ++n) _Pragma("unroll") for (int k = 0; k < 2; ++k) \
;         acc[ai][bj][m][n] = __builtin_amdgcn_mfma_f32_16x16x32_bf16(Bt[n][k], At[m][k], acc[ai][bj][m][n], 0, 0, 0); __builtin_amdgcn_s_setprio(0); } while (0)
; #define PG8_WAIT_V(n) asm volatile("s_waitcnt vmcnt(" #n ")" ::: "memory")
; #define PG8_WAIT_L(n) asm volatile("s_waitcnt lgkmcnt(" #n ")" ::: "memory")
; #define PG8_BAR __builtin_amdgcn_s_barrier()
; #define PG8_SCHED __builtin_amdgcn_sched_barrier(0)
; template <class Epi>
; __device__ __forceinline__ void gemm_phase(LAS unsigned char* lds, const Gemm g, const StaticOrder& S, const Epi& E) {
;     ...
;             PG8_LDA(At, 1, 1); PG8_STAGE(PG8_SB(1, 0), b3, voffB); PG8_STAGE(PG8_SB(1, 1), b3 + hstepB, voffB); PG8_STAGE(PG8_SA(1, 0), a3, voffA);
;             PG8_WAIT_V(8); PG8_WAIT_L(0); PG8_BAR; PG8_MMA(1, 0, At, B0); PG8_MMA(1, 1, At, B1); PG8_BAR; PG8_SCHED;
;         }
;         if (wr == 0) PG8_BAR;
	s_add_i32 s30, s56, s33
	v_lshl_add_u64 v[206:207], v[206:207], 0, s[10:11]
	s_mov_b32 m0, s30
	ds_read_b128 v[182:185], v148 offset:49152
	ds_read_b128 v[186:189], v148 offset:50176
	ds_read_b128 v[190:193], v148 offset:51200
	ds_read_b128 v[194:197], v148 offset:52224
	ds_read_b128 v[198:201], v148 offset:53248
	ds_read_b128 v[202:205], v148 offset:54272
	ds_read_b128 v[210:213], v148 offset:55296
	ds_read_b128 v[214:217], v148 offset:56320
	global_load_lds_dwordx4 v[206:207], off
	s_add_i32 m0, s30, 0x2000
	s_add_u32 s28, s28, 0x40080
	v_lshl_add_u64 v[206:207], v[218:219], 0, s[10:11]
	s_addc_u32 s29, s29, 0
	s_add_i32 s30, s57, s33
	global_load_lds_dwordx4 v[206:207], off
	v_lshl_add_u64 v[206:207], s[28:29], 0, v[130:131]
	s_mov_b32 m0, s30
	s_nop 0
	global_load_lds_dwordx4 v[206:207], off
	v_lshl_add_u64 v[206:207], s[28:29], 0, v[128:129]
	s_add_i32 m0, s30, 0x2000
	s_nop 0
	global_load_lds_dwordx4 v[206:207], off
	v_lshl_add_u64 v[206:207], v[220:221], 0, s[10:11]
	s_mov_b32 m0, s41
	s_nop 0
	global_load_lds_dwordx4 v[206:207], off
	v_lshl_add_u64 v[206:207], v[222:223], 0, s[10:11]
	s_mov_b32 m0, s42
	s_nop 0
	global_load_lds_dwordx4 v[206:207], off
	s_waitcnt vmcnt(8)
	s_waitcnt lgkmcnt(0)
	s_barrier
	s_setprio 1
	s_waitcnt lgkmcnt(0)
	v_mfma_f32_16x16x32_bf16 v[60:63], v[150:153], v[182:185], v[60:63]
	v_mfma_f32_16x16x32_bf16 v[52:55], v[158:161], v[182:185], v[52:55]
	v_mfma_f32_16x16x32_bf16 v[44:47], v[150:153], v[190:193], v[44:47]
	v_mfma_f32_16x16x32_bf16 v[36:39], v[158:161], v[190:193], v[36:39]
	v_mfma_f32_16x16x32_bf16 v[28:31], v[150:153], v[198:201], v[28:31]
	v_mfma_f32_16x16x32_bf16 v[20:23], v[158:161], v[198:201], v[20:23]
	v_mfma_f32_16x16x32_bf16 v[12:15], v[150:153], v[210:213], v[12:15]
	v_mfma_f32_16x16x32_bf16 v[4:7], v[158:161], v[210:213], v[4:7]
	v_mfma_f32_16x16x32_bf16 v[60:63], v[154:157], v[186:189], v[60:63]
	v_mfma_f32_16x16x32_bf16 v[52:55], v[162:165], v[186:189], v[52:55]
	v_mfma_f32_16x16x32_bf16 v[44:47], v[154:157], v[194:197], v[44:47]
	v_mfma_f32_16x16x32_bf16 v[36:39], v[162:165], v[194:197], v[36:39]
	v_mfma_f32_16x16x32_bf16 v[28:31], v[154:157], v[202:205], v[28:31]
	v_mfma_f32_16x16x32_bf16 v[20:23], v[162:165], v[202:205], v[20:23]
	v_mfma_f32_16x16x32_bf16 v[12:15], v[154:157], v[214:217], v[12:15]
	v_mfma_f32_16x16x32_bf16 v[4:7], v[162:165], v[214:217], v[4:7]
	s_setprio 0
	s_setprio 1
	v_mfma_f32_16x16x32_bf16 v[56:59], v[166:169], v[182:185], v[56:59]
	v_mfma_f32_16x16x32_bf16 v[48:51], v[174:177], v[182:185], v[48:51]
	v_mfma_f32_16x16x32_bf16 v[40:43], v[166:169], v[190:193], v[40:43]
	v_mfma_f32_16x16x32_bf16 v[32:35], v[174:177], v[190:193], v[32:35]
	v_mfma_f32_16x16x32_bf16 v[24:27], v[166:169], v[198:201], v[24:27]
	v_mfma_f32_16x16x32_bf16 v[16:19], v[174:177], v[198:201], v[16:19]
	v_mfma_f32_16x16x32_bf16 v[8:11], v[166:169], v[210:213], v[8:11]
	v_mfma_f32_16x16x32_bf16 v[0:3], v[174:177], v[210:213], v[0:3]
	v_mfma_f32_16x16x32_bf16 v[56:59], v[170:173], v[186:189], v[56:59]
	v_mfma_f32_16x16x32_bf16 v[48:51], v[178:181], v[186:189], v[48:51]
	v_mfma_f32_16x16x32_bf16 v[40:43], v[170:173], v[194:197], v[40:43]
	v_mfma_f32_16x16x32_bf16 v[32:35], v[178:181], v[194:197], v[32:35]
	v_mfma_f32_16x16x32_bf16 v[24:27], v[170:173], v[202:205], v[24:27]
	v_mfma_f32_16x16x32_bf16 v[16:19], v[178:181], v[202:205], v[16:19]
	v_mfma_f32_16x16x32_bf16 v[8:11], v[170:173], v[214:217], v[8:11]
	v_mfma_f32_16x16x32_bf16 v[0:3], v[178:181], v[214:217], v[0:3]
	s_setprio 0
	s_add_i32 s55, s55, 2
	s_add_u32 s26, s26, 0x100
	s_addc_u32 s27, s27, 0
	s_add_u32 s53, s53, 0x100
	s_addc_u32 s54, s54, 0
	s_cmp_gt_u32 s55, 13
	s_barrier
	s_cbranch_scc0 .LBB0_1732
	s_and_b64 vcc, exec, s[12:13]
	s_cbranch_vccz .LBB0_1735
	s_barrier

; #define PG8_STAGE(bufoff, gbase, voff) do { _Pragma("unroll") for (int _i = 0; _i < 2; ++_i) \
;         __builtin_amdgcn_global_load_lds((const unsigned*)((const char*)(gbase) + (voff)[_i]), (LAS unsigned*)(lds + (bufoff) + ldsw + _i * 8192), 16, 0, 0); } while (0)
; #define PG8_LDA(dst, b, h) do { _Pragma("unroll") for (int m = 0; m < 4; ++m) _Pragma("unroll") for (int k = 0; k < 2; ++k) dst[m][k] = *(const LAS bf16x8*)(lds + PG8_SA(b, h) + aoff + m * 2048 + k * 1024); } while (0)
; #define PG8_LDB(dst, b, h) do { _Pragma("unroll") for (int n = 0; n < 2; ++n) _Pragma("unroll") for (int k = 0; k < 2; ++k) dst[n][k] = *(const LAS bf16x8*)(lds + PG8_SB(b, h) + boff + n * 2048 + k * 1024); } while (0)
; #define PG8_MMA(ai, bj, At, Bt) do { __builtin_amdgcn_s_setprio(1); _Pragma("unroll") for (int m = 0; m < 4; ++m) _Pragma("unroll") for (int n = 0; n < 2; ++n) _Pragma("unroll") for (int k = 0; k < 2; ++k) \
;         acc[ai][bj][m][n] = __builtin_amdgcn_mfma_f32_16x16x32_bf16(Bt[n][k], At[m][k], acc[ai][bj][m][n], 0, 0, 0); __builtin_amdgcn_s_setprio(0); } while (0)
; #define PG8_WAIT_V(n) asm volatile("s_waitcnt vmcnt(" #n ")" ::: "memory")
; #define PG8_WAIT_L(n) asm volatile("s_waitcnt lgkmcnt(" #n ")" ::: "memory")
; #define PG8_BAR __builtin_amdgcn_s_barrier()
; #define PG8_SCHED __builtin_amdgcn_sched_barrier(0)
; template <class Epi>
; __device__ __forceinline__ void gemm_phase(LAS unsigned char* lds, const Gemm g, const StaticOrder& S, const Epi& E) {
;     ...
;         for (int t = 0; t < nt; t += 2) {
;             const bool last = (t == nt - 2);
;             const char* a1 = cA + (size_t)(t + 1) * kstepA;
;             const char* a2 = last ? nA : cA + (size_t)(t + 2) * kstepA; const char* b2 = last ? nB : cB + (size_t)(t + 2) * kstep;
;             const char* a3 = a2 + kstepA; const char* b3 = b2 + kstep;
;             PG8_LDB(B0, 0, 0); PG8_LDB(B1, 0, 1); PG8_SCHED; PG8_LDA(At, 0, 0); PG8_STAGE(PG8_SA(1, 1), a1 + hstepA, voffA);
;             PG8_WAIT_V(8); PG8_WAIT_L(0); PG8_BAR; PG8_MMA(0, 0, At, B0); PG8_MMA(0, 1, At, B1); PG8_BAR; PG8_SCHED;
;             PG8_LDA(At, 0, 1); PG8_STAGE(PG8_SB(0, 0), b2, voffB); PG8_STAGE(PG8_SB(0, 1), b2 + hstepB, voffB); PG8_STAGE(PG8_SA(0, 0), a2, voffA);
.LBB0_1828:
	ds_read_b128 v[128:131], v226
	ds_read_b128 v[132:135], v226 offset:1024
	ds_read_b128 v[136:139], v226 offset:2048
	ds_read_b128 v[140:143], v226 offset:3072
	ds_read_b128 v[144:147], v227
	ds_read_b128 v[148:151], v227 offset:1024
	ds_read_b128 v[152:155], v227 offset:2048
	ds_read_b128 v[156:159], v227 offset:3072
	s_add_u32 s6, s2, 0x4000
	s_addc_u32 s7, s3, 0
	s_cmp_eq_u32 s16, 40
	s_cselect_b32 s10, s24, s6
	s_cselect_b32 s11, s25, s7
	s_cselect_b32 s8, s26, s14
	s_cselect_b32 s9, s27, s15
	s_add_u32 s6, s10, 0x8000
	s_addc_u32 s7, s11, 0
	v_lshl_add_u64 v[212:213], s[2:3], 0, v[202:203]
	s_add_i32 m0, s31, 0xc000
	ds_read_b128 v[160:163], v228
	ds_read_b128 v[164:167], v228 offset:1024
	ds_read_b128 v[168:171], v228 offset:2048
	ds_read_b128 v[172:175], v228 offset:3072
	ds_read_b128 v[176:179], v228 offset:4096
	ds_read_b128 v[180:183], v228 offset:5120
	ds_read_b128 v[184:187], v228 offset:6144
	ds_read_b128 v[188:191], v228 offset:7168
	global_load_lds_dwordx4 v[212:213], off
	v_lshl_add_u64 v[212:213], s[2:3], 0, v[204:205]
	s_add_i32 m0, s31, 0xe000
	s_nop 0
	global_load_lds_dwordx4 v[212:213], off
	s_waitcnt vmcnt(8)
	s_waitcnt lgkmcnt(0)
	s_barrier
	s_setprio 1
	s_waitcnt lgkmcnt(0)
	v_mfma_f32_16x16x32_bf16 v[120:123], v[128:131], v[160:163], v[120:123]
	v_mfma_f32_16x16x32_bf16 v[124:127], v[136:139], v[160:163], v[124:127]
	v_mfma_f32_16x16x32_bf16 v[104:107], v[128:131], v[168:171], v[104:107]
	v_mfma_f32_16x16x32_bf16 v[108:111], v[136:139], v[168:171], v[108:111]
	v_mfma_f32_16x16x32_bf16 v[88:91], v[128:131], v[176:179], v[88:91]
	v_mfma_f32_16x16x32_bf16 v[92:95], v[136:139], v[176:179], v[92:95]
	v_mfma_f32_16x16x32_bf16 v[72:75], v[128:131], v[184:187], v[72:75]
	v_mfma_f32_16x16x32_bf16 v[76:79], v[136:139], v[184:187], v[76:79]
	v_mfma_f32_16x16x32_bf16 v[120:123], v[132:135], v[164:167], v[120:123]
	v_mfma_f32_16x16x32_bf16 v[124:127], v[140:143], v[164:167], v[124:127]
	v_mfma_f32_16x16x32_bf16 v[104:107], v[132:135], v[172:175], v[104:107]
	v_mfma_f32_16x16x32_bf16 v[108:111], v[140:143], v[172:175], v[108:111]
	v_mfma_f32_16x16x32_bf16 v[88:91], v[132:135], v[180:183], v[88:91]
	v_mfma_f32_16x16x32_bf16 v[92:95], v[140:143], v[180:183], v[92:95]
	v_mfma_f32_16x16x32_bf16 v[72:75], v[132:135], v[188:191], v[72:75]
	v_mfma_f32_16x16x32_bf16 v[76:79], v[140:143], v[188:191], v[76:79]
	s_setprio 0
	s_setprio 1
	v_mfma_f32_16x16x32_bf16 v[112:115], v[144:147], v[160:163], v[112:115]
	v_mfma_f32_16x16x32_bf16 v[116:119], v[152:155], v[160:163], v[116:119]
	v_mfma_f32_16x16x32_bf16 v[96:99], v[144:147], v[168:171], v[96:99]
	v_mfma_f32_16x16x32_bf16 v[100:103], v[152:155], v[168:171], v[100:103]
	v_mfma_f32_16x16x32_bf16 v[80:83], v[144:147], v[176:179], v[80:83]
	v_mfma_f32_16x16x32_bf16 v[84:87], v[152:155], v[176:179], v[84:87]
	v_mfma_f32_16x16x32_bf16 v[64:67], v[144:147], v[184:187], v[64:67]
	v_mfma_f32_16x16x32_bf16 v[68:71], v[152:155], v[184:187], v[68:71]
	v_mfma_f32_16x16x32_bf16 v[112:115], v[148:151], v[164:167], v[112:115]
	v_mfma_f32_16x16x32_bf16 v[116:119], v[156:159], v[164:167], v[116:119]
	v_mfma_f32_16x16x32_bf16 v[96:99], v[148:151], v[172:175], v[96:99]
	v_mfma_f32_16x16x32_bf16 v[100:103], v[156:159], v[172:175], v[100:103]
	v_mfma_f32_16x16x32_bf16 v[80:83], v[148:151], v[180:183], v[80:83]
	v_mfma_f32_16x16x32_bf16 v[84:87], v[156:159], v[180:183], v[84:87]
	v_mfma_f32_16x16x32_bf16 v[64:67], v[148:151], v[188:191], v[64:67]
	v_mfma_f32_16x16x32_bf16 v[68:71], v[156:159], v[188:191], v[68:71]
	s_setprio 0
	s_barrier
	s_add_i32 s17, s44, s30
	v_lshl_add_u64 v[212:213], s[8:9], 0, v[194:195]
	s_mov_b32 m0, s17
	ds_read_b128 v[160:163], v228 offset:16384
	ds_read_b128 v[164:167], v228 offset:17408
	ds_read_b128 v[168:171], v228 offset:18432
	ds_read_b128 v[172:175], v228 offset:19456
	ds_read_b128 v[176:179], v228 offset:20480
	ds_read_b128 v[180:183], v228 offset:21504
	ds_read_b128 v[184:187], v228 offset:22528
	ds_read_b128 v[188:191], v228 offset:23552
	global_load_lds_dwordx4 v[212:213], off
	s_add_i32 m0, s17, 0x2000
	s_add_u32 s28, s8, 0xb0000
	v_lshl_add_u64 v[214:215], s[8:9], 0, v[198:199]
	s_addc_u32 s29, s9, 0
	s_add_i32 s17, s45, s30
	global_load_lds_dwordx4 v[214:215], off
	v_lshl_add_u64 v[216:217], s[28:29], 0, v[194:195]
	s_mov_b32 m0, s17
	s_nop 0
	global_load_lds_dwordx4 v[216:217], off
	v_lshl_add_u64 v[216:217], s[28:29], 0, v[198:199]
	s_add_i32 m0, s17, 0x2000
	s_nop 0
	global_load_lds_dwordx4 v[216:217], off
	v_lshl_add_u64 v[216:217], s[10:11], 0, v[192:193]
	s_mov_b32 m0, s31
	s_nop 0
	global_load_lds_dwordx4 v[216:217], off
	v_lshl_add_u64 v[216:217], s[10:11], 0, v[196:197]
	s_mov_b32 m0, s33
	s_nop 0
	global_load_lds_dwordx4 v[216:217], off
	s_waitcnt vmcnt(8)
	s_waitcnt lgkmcnt(0)
	s_barrier
; #define PG8_STAGE(bufoff, gbase, voff) do { _Pragma("unroll") for (int _i = 0; _i < 2; ++_i) \
;         __builtin_amdgcn_global_load_lds((const unsigned*)((const char*)(gbase) + (voff)[_i]), (LAS unsigned*)(lds + (bufoff) + ldsw + _i * 8192), 16, 0, 0); } while (0)
; #define PG8_LDA(dst, b, h) do { _Pragma("unroll") for (int m = 0; m < 4; ++m) _Pragma("unroll") for (int k = 0; k < 2; ++k) dst[m][k] = *(const LAS bf16x8*)(lds + PG8_SA(b, h) + aoff + m * 2048 + k * 1024); } while (0)
; #define PG8_LDB(dst, b, h) do { _Pragma("unroll") for (int n = 0; n < 2; ++n) _Pragma("unroll") for (int k = 0; k < 2; ++k) dst[n][k] = *(const LAS bf16x8*)(lds + PG8_SB(b, h) + boff + n * 2048 + k * 1024); } while (0)
; #define PG8_MMA(ai, bj, At, Bt) do { __builtin_amdgcn_s_setprio(1); _Pragma("unroll") for (int m = 0; m < 4; ++m) _Pragma("unroll") for (int n = 0; n < 2; ++n) _Pragma("unroll") for (int k = 0; k < 2; ++k) \
;         acc[ai][bj][m][n] = __builtin_amdgcn_mfma_f32_16x16x32_bf16(Bt[n][k], At[m][k], acc[ai][bj][m][n], 0, 0, 0); __builtin_amdgcn_s_setprio(0); } while (0)
; #define PG8_WAIT_V(n) asm volatile("s_waitcnt vmcnt(" #n ")" ::: "memory")
; #define PG8_WAIT_L(n) asm volatile("s_waitcnt lgkmcnt(" #n ")" ::: "memory")
; #define PG8_BAR __builtin_amdgcn_s_barrier()
; #define PG8_SCHED __builtin_amdgcn_sched_barrier(0)
; template <class Epi>
; __device__ __forceinline__ void gemm_phase(LAS unsigned char* lds, const Gemm g, const StaticOrder& S, const Epi& E) {
;     ...
;             PG8_WAIT_V(8); PG8_WAIT_L(0); PG8_BAR; PG8_MMA(1, 0, At, B0); PG8_MMA(1, 1, At, B1); PG8_BAR; PG8_SCHED;
;             PG8_LDB(B0, 1, 0); PG8_LDB(B1, 1, 1); PG8_SCHED; PG8_LDA(At, 1, 0); PG8_STAGE(PG8_SA(0, 1), a2 + hstepA, voffA);
;             PG8_WAIT_V(8); PG8_WAIT_L(0); PG8_BAR; PG8_MMA(0, 0, At, B0); PG8_MMA(0, 1, At, B1); PG8_BAR; PG8_SCHED;
;             PG8_LDA(At, 1, 1); PG8_STAGE(PG8_SB(1, 0), b3, voffB); PG8_STAGE(PG8_SB(1, 1), b3 + hstepB, voffB); PG8_STAGE(PG8_SA(1, 0), a3, voffA);
	s_setprio 1
	s_waitcnt lgkmcnt(0)
	v_mfma_f32_16x16x32_bf16 v[56:59], v[128:131], v[160:163], v[56:59]
	v_mfma_f32_16x16x32_bf16 v[60:63], v[136:139], v[160:163], v[60:63]
	v_mfma_f32_16x16x32_bf16 v[40:43], v[128:131], v[168:171], v[40:43]
	v_mfma_f32_16x16x32_bf16 v[44:47], v[136:139], v[168:171], v[44:47]
	v_mfma_f32_16x16x32_bf16 v[24:27], v[128:131], v[176:179], v[24:27]
	v_mfma_f32_16x16x32_bf16 v[28:31], v[136:139], v[176:179], v[28:31]
	v_mfma_f32_16x16x32_bf16 v[8:11], v[128:131], v[184:187], v[8:11]
	v_mfma_f32_16x16x32_bf16 v[12:15], v[136:139], v[184:187], v[12:15]
	v_mfma_f32_16x16x32_bf16 v[56:59], v[132:135], v[164:167], v[56:59]
	v_mfma_f32_16x16x32_bf16 v[60:63], v[140:143], v[164:167], v[60:63]
	v_mfma_f32_16x16x32_bf16 v[40:43], v[132:135], v[172:175], v[40:43]
	v_mfma_f32_16x16x32_bf16 v[44:47], v[140:143], v[172:175], v[44:47]
	v_mfma_f32_16x16x32_bf16 v[24:27], v[132:135], v[180:183], v[24:27]
	v_mfma_f32_16x16x32_bf16 v[28:31], v[140:143], v[180:183], v[28:31]
	v_mfma_f32_16x16x32_bf16 v[8:11], v[132:135], v[188:191], v[8:11]
	v_mfma_f32_16x16x32_bf16 v[12:15], v[140:143], v[188:191], v[12:15]
	s_setprio 0
	s_setprio 1
	v_mfma_f32_16x16x32_bf16 v[48:51], v[144:147], v[160:163], v[48:51]
	v_mfma_f32_16x16x32_bf16 v[52:55], v[152:155], v[160:163], v[52:55]
	v_mfma_f32_16x16x32_bf16 v[32:35], v[144:147], v[168:171], v[32:35]
	v_mfma_f32_16x16x32_bf16 v[36:39], v[152:155], v[168:171], v[36:39]
	v_mfma_f32_16x16x32_bf16 v[16:19], v[144:147], v[176:179], v[16:19]
	v_mfma_f32_16x16x32_bf16 v[20:23], v[152:155], v[176:179], v[20:23]
	v_mfma_f32_16x16x32_bf16 v[4:7], v[144:147], v[184:187], v[4:7]
	v_mfma_f32_16x16x32_bf16 v[0:3], v[152:155], v[184:187], v[0:3]
	v_mfma_f32_16x16x32_bf16 v[48:51], v[148:151], v[164:167], v[48:51]
	v_mfma_f32_16x16x32_bf16 v[52:55], v[156:159], v[164:167], v[52:55]
	v_mfma_f32_16x16x32_bf16 v[32:35], v[148:151], v[172:175], v[32:35]
	v_mfma_f32_16x16x32_bf16 v[36:39], v[156:159], v[172:175], v[36:39]
	v_mfma_f32_16x16x32_bf16 v[16:19], v[148:151], v[180:183], v[16:19]
	v_mfma_f32_16x16x32_bf16 v[20:23], v[156:159], v[180:183], v[20:23]
	v_mfma_f32_16x16x32_bf16 v[4:7], v[148:151], v[188:191], v[4:7]
	v_mfma_f32_16x16x32_bf16 v[0:3], v[156:159], v[188:191], v[0:3]
	s_setprio 0
	s_barrier
	s_add_i32 s17, 0, 0x18000
	s_add_i32 s28, 0, 0x1c000
	v_add_u32_e32 v140, s17, v224
	v_add_u32_e32 v156, s28, v224
	ds_read_b128 v[128:131], v140
	ds_read_b128 v[132:135], v140 offset:1024
	ds_read_b128 v[136:139], v140 offset:2048
	ds_read_b128 v[140:143], v140 offset:3072
	ds_read_b128 v[144:147], v156
	ds_read_b128 v[148:151], v156 offset:1024
	ds_read_b128 v[152:155], v156 offset:2048
	ds_read_b128 v[156:159], v156 offset:3072
	s_add_u32 s10, s10, 0x4000
	s_addc_u32 s11, s11, 0
	s_mov_b32 m0, s34
	v_lshl_add_u64 v[216:217], s[10:11], 0, v[192:193]
	ds_read_b128 v[160:163], v228 offset:32768
	ds_read_b128 v[164:167], v228 offset:33792
	ds_read_b128 v[168:171], v228 offset:34816
	ds_read_b128 v[172:175], v228 offset:35840
	ds_read_b128 v[176:179], v228 offset:36864
	ds_read_b128 v[180:183], v228 offset:37888
	ds_read_b128 v[184:187], v228 offset:38912
	ds_read_b128 v[188:191], v228 offset:39936
	global_load_lds_dwordx4 v[216:217], off
	v_lshl_add_u64 v[216:217], s[10:11], 0, v[196:197]
	s_mov_b32 m0, s35
	s_nop 0
	global_load_lds_dwordx4 v[216:217], off
	s_waitcnt vmcnt(8)
	s_waitcnt lgkmcnt(0)
	s_barrier
	s_setprio 1
	s_waitcnt lgkmcnt(0)
	v_mfma_f32_16x16x32_bf16 v[120:123], v[128:131], v[160:163], v[120:123]
	v_mfma_f32_16x16x32_bf16 v[124:127], v[136:139], v[160:163], v[124:127]
	v_mfma_f32_16x16x32_bf16 v[104:107], v[128:131], v[168:171], v[104:107]
	v_mfma_f32_16x16x32_bf16 v[108:111], v[136:139], v[168:171], v[108:111]
	v_mfma_f32_16x16x32_bf16 v[88:91], v[128:131], v[176:179], v[88:91]
	v_mfma_f32_16x16x32_bf16 v[92:95], v[136:139], v[176:179], v[92:95]
	v_mfma_f32_16x16x32_bf16 v[72:75], v[128:131], v[184:187], v[72:75]
	v_mfma_f32_16x16x32_bf16 v[76:79], v[136:139], v[184:187], v[76:79]
	v_mfma_f32_16x16x32_bf16 v[120:123], v[132:135], v[164:167], v[120:123]
	v_mfma_f32_16x16x32_bf16 v[124:127], v[140:143], v[164:167], v[124:127]
	v_mfma_f32_16x16x32_bf16 v[104:107], v[132:135], v[172:175], v[104:107]
	v_mfma_f32_16x16x32_bf16 v[108:111], v[140:143], v[172:175], v[108:111]
	v_mfma_f32_16x16x32_bf16 v[88:91], v[132:135], v[180:183], v[88:91]
	v_mfma_f32_16x16x32_bf16 v[92:95], v[140:143], v[180:183], v[92:95]
	v_mfma_f32_16x16x32_bf16 v[72:75], v[132:135], v[188:191], v[72:75]
	v_mfma_f32_16x16x32_bf16 v[76:79], v[140:143], v[188:191], v[76:79]
	s_setprio 0
	s_setprio 1
	v_mfma_f32_16x16x32_bf16 v[112:115], v[144:147], v[160:163], v[112:115]
	v_mfma_f32_16x16x32_bf16 v[116:119], v[152:155], v[160:163], v[116:119]
	v_mfma_f32_16x16x32_bf16 v[96:99], v[144:147], v[168:171], v[96:99]
	v_mfma_f32_16x16x32_bf16 v[100:103], v[152:155], v[168:171], v[100:103]
	v_mfma_f32_16x16x32_bf16 v[80:83], v[144:147], v[176:179], v[80:83]
	v_mfma_f32_16x16x32_bf16 v[84:87], v[152:155], v[176:179], v[84:87]
	v_mfma_f32_16x16x32_bf16 v[64:67], v[144:147], v[184:187], v[64:67]
	v_mfma_f32_16x16x32_bf16 v[68:71], v[152:155], v[184:187], v[68:71]
	v_mfma_f32_16x16x32_bf16 v[112:115], v[148:151], v[164:167], v[112:115]
	v_mfma_f32_16x16x32_bf16 v[116:119], v[156:159], v[164:167], v[116:119]
	v_mfma_f32_16x16x32_bf16 v[96:99], v[148:151], v[172:175], v[96:99]
	v_mfma_f32_16x16x32_bf16 v[100:103], v[156:159], v[172:175], v[100:103]
	v_mfma_f32_16x16x32_bf16 v[80:83], v[148:151], v[180:183], v[80:83]
	v_mfma_f32_16x16x32_bf16 v[84:87], v[156:159], v[180:183], v[84:87]
	v_mfma_f32_16x16x32_bf16 v[64:67], v[148:151], v[188:191], v[64:67]
	v_mfma_f32_16x16x32_bf16 v[68:71], v[156:159], v[188:191], v[68:71]
	s_setprio 0
	s_barrier
; #define PG8_STAGE(bufoff, gbase, voff) do { _Pragma("unroll") for (int _i = 0; _i < 2; ++_i) \
;         __builtin_amdgcn_global_load_lds((const unsigned*)((const char*)(gbase) + (voff)[_i]), (LAS unsigned*)(lds + (bufoff) + ldsw + _i * 8192), 16, 0, 0); } while (0)
; #define PG8_LDA(dst, b, h) do { _Pragma("unroll") for (int m = 0; m < 4; ++m) _Pragma("unroll") for (int k = 0; k < 2; ++k) dst[m][k] = *(const LAS bf16x8*)(lds + PG8_SA(b, h) + aoff + m * 2048 + k * 1024); } while (0)
; #define PG8_MMA(ai, bj, At, Bt) do { __builtin_amdgcn_s_setprio(1); _Pragma("unroll") for (int m = 0; m < 4; ++m) _Pragma("unroll") for (int n = 0; n < 2; ++n) _Pragma("unroll") for (int k = 0; k < 2; ++k) \
;         acc[ai][bj][m][n] = __builtin_amdgcn_mfma_f32_16x16x32_bf16(Bt[n][k], At[m][k], acc[ai][bj][m][n], 0, 0, 0); __builtin_amdgcn_s_setprio(0); } while (0)
; #define PG8_WAIT_V(n) asm volatile("s_waitcnt vmcnt(" #n ")" ::: "memory")
; #define PG8_WAIT_L(n) asm volatile("s_waitcnt lgkmcnt(" #n ")" ::: "memory")
; #define PG8_BAR __builtin_amdgcn_s_barrier()
; #define PG8_SCHED __builtin_amdgcn_sched_barrier(0)
; template <class Epi>
; __device__ __forceinline__ void gemm_phase(LAS unsigned char* lds, const Gemm g, const StaticOrder& S, const Epi& E) {
;     ...
;             PG8_LDA(At, 1, 1); PG8_STAGE(PG8_SB(1, 0), b3, voffB); PG8_STAGE(PG8_SB(1, 1), b3 + hstepB, voffB); PG8_STAGE(PG8_SA(1, 0), a3, voffA);
;             PG8_WAIT_V(8); PG8_WAIT_L(0); PG8_BAR; PG8_MMA(1, 0, At, B0); PG8_MMA(1, 1, At, B1); PG8_BAR; PG8_SCHED;
;         }
;         if (wr == 0) PG8_BAR;
	s_add_i32 s10, s17, s30
	v_lshl_add_u64 v[212:213], v[212:213], 0, s[20:21]
	s_mov_b32 m0, s10
	ds_read_b128 v[160:163], v228 offset:49152
	ds_read_b128 v[164:167], v228 offset:50176
	ds_read_b128 v[168:171], v228 offset:51200
	ds_read_b128 v[172:175], v228 offset:52224
	ds_read_b128 v[176:179], v228 offset:53248
	ds_read_b128 v[180:183], v228 offset:54272
	ds_read_b128 v[184:187], v228 offset:55296
	ds_read_b128 v[188:191], v228 offset:56320
	global_load_lds_dwordx4 v[212:213], off
	s_add_i32 m0, s10, 0x2000
	s_add_u32 s8, s8, 0xb0080
	v_lshl_add_u64 v[212:213], v[214:215], 0, s[20:21]
	s_addc_u32 s9, s9, 0
	s_add_i32 s10, s28, s30
	global_load_lds_dwordx4 v[212:213], off
	v_lshl_add_u64 v[212:213], s[8:9], 0, v[194:195]
	s_mov_b32 m0, s10
	s_nop 0
	global_load_lds_dwordx4 v[212:213], off
	v_lshl_add_u64 v[212:213], s[8:9], 0, v[198:199]
	s_add_i32 m0, s10, 0x2000
	s_nop 0
	global_load_lds_dwordx4 v[212:213], off
	v_lshl_add_u64 v[212:213], s[6:7], 0, v[192:193]
	s_mov_b32 m0, s37
	s_nop 0
	global_load_lds_dwordx4 v[212:213], off
	v_lshl_add_u64 v[212:213], s[6:7], 0, v[196:197]
	s_mov_b32 m0, s38
	s_nop 0
	global_load_lds_dwordx4 v[212:213], off
	s_waitcnt vmcnt(8)
	s_waitcnt lgkmcnt(0)
	s_barrier
	s_setprio 1
	s_waitcnt lgkmcnt(0)
	v_mfma_f32_16x16x32_bf16 v[56:59], v[128:131], v[160:163], v[56:59]
	v_mfma_f32_16x16x32_bf16 v[60:63], v[136:139], v[160:163], v[60:63]
	v_mfma_f32_16x16x32_bf16 v[40:43], v[128:131], v[168:171], v[40:43]
	v_mfma_f32_16x16x32_bf16 v[44:47], v[136:139], v[168:171], v[44:47]
	v_mfma_f32_16x16x32_bf16 v[24:27], v[128:131], v[176:179], v[24:27]
	v_mfma_f32_16x16x32_bf16 v[28:31], v[136:139], v[176:179], v[28:31]
	v_mfma_f32_16x16x32_bf16 v[8:11], v[128:131], v[184:187], v[8:11]
	v_mfma_f32_16x16x32_bf16 v[12:15], v[136:139], v[184:187], v[12:15]
	v_mfma_f32_16x16x32_bf16 v[56:59], v[132:135], v[164:167], v[56:59]
	v_mfma_f32_16x16x32_bf16 v[60:63], v[140:143], v[164:167], v[60:63]
	v_mfma_f32_16x16x32_bf16 v[40:43], v[132:135], v[172:175], v[40:43]
	v_mfma_f32_16x16x32_bf16 v[44:47], v[140:143], v[172:175], v[44:47]
	v_mfma_f32_16x16x32_bf16 v[24:27], v[132:135], v[180:183], v[24:27]
	v_mfma_f32_16x16x32_bf16 v[28:31], v[140:143], v[180:183], v[28:31]
	v_mfma_f32_16x16x32_bf16 v[8:11], v[132:135], v[188:191], v[8:11]
	v_mfma_f32_16x16x32_bf16 v[12:15], v[140:143], v[188:191], v[12:15]
	s_setprio 0
	s_setprio 1
	v_mfma_f32_16x16x32_bf16 v[48:51], v[144:147], v[160:163], v[48:51]
	v_mfma_f32_16x16x32_bf16 v[52:55], v[152:155], v[160:163], v[52:55]
	v_mfma_f32_16x16x32_bf16 v[32:35], v[144:147], v[168:171], v[32:35]
	v_mfma_f32_16x16x32_bf16 v[36:39], v[152:155], v[168:171], v[36:39]
	v_mfma_f32_16x16x32_bf16 v[16:19], v[144:147], v[176:179], v[16:19]
	v_mfma_f32_16x16x32_bf16 v[20:23], v[152:155], v[176:179], v[20:23]
	v_mfma_f32_16x16x32_bf16 v[4:7], v[144:147], v[184:187], v[4:7]
	v_mfma_f32_16x16x32_bf16 v[0:3], v[152:155], v[184:187], v[0:3]
	v_mfma_f32_16x16x32_bf16 v[48:51], v[148:151], v[164:167], v[48:51]
	v_mfma_f32_16x16x32_bf16 v[52:55], v[156:159], v[164:167], v[52:55]
	v_mfma_f32_16x16x32_bf16 v[32:35], v[148:151], v[172:175], v[32:35]
	v_mfma_f32_16x16x32_bf16 v[36:39], v[156:159], v[172:175], v[36:39]
	v_mfma_f32_16x16x32_bf16 v[16:19], v[148:151], v[180:183], v[16:19]
	v_mfma_f32_16x16x32_bf16 v[20:23], v[156:159], v[180:183], v[20:23]
	v_mfma_f32_16x16x32_bf16 v[4:7], v[148:151], v[188:191], v[4:7]
	v_mfma_f32_16x16x32_bf16 v[0:3], v[156:159], v[188:191], v[0:3]
	s_setprio 0
	s_add_i32 s16, s16, 2
	s_add_u32 s14, s14, 0x100
	s_addc_u32 s15, s15, 0
	s_add_u32 s2, s2, 0x10000
	s_addc_u32 s3, s3, 0
	s_cmp_gt_u32 s16, 41
	s_barrier
	s_cbranch_scc0 .LBB0_1828
	s_and_b64 vcc, exec, s[22:23]
	s_cbranch_vccz .LBB0_1831
	s_barrier
